# GEMM main loops: staged K-slices retired by counted vmcnt(10) one phase before first read (every LDS-DMA stage gets 5-6 phases to land instead of 3)
# speedup vs baseline: 1.0681x; 1.0061x over previous
; #define LDA(dst, b, h) for (int m = 0; m < 4; ++m) for (int k = 0; k < 2; ++k) \
;     dst[m][k] = *reinterpret_cast<const bf16x8*>((char*)SA(b, h) + a_thr + (m * 2 + k) * 1024)
; #define LDB(dst, b, h) for (int n = 0; n < 2; ++n) for (int k = 0; k < 2; ++k) \
;     dst[n][k] = *reinterpret_cast<const bf16x8*>((char*)SB(b, h) + b_thr + (n * 2 + k) * 1024)
; #define MMA(ai, bj, At, Btf) do { __builtin_amdgcn_s_setprio(1); \
;     for (int m = 0; m < 4; ++m) for (int n = 0; n < 2; ++n) for (int k = 0; k < 2; ++k) \
;       acc[ai][bj][m][n] = __builtin_amdgcn_mfma_f32_16x16x32_bf16(Btf[n][k], At[m][k], acc[ai][bj][m][n], 0, 0, 0); \
;     __builtin_amdgcn_s_setprio(0); } while (0)
; #define WAIT_V(n) asm volatile("s_waitcnt vmcnt(" #n ")" ::: "memory")
; #define WAIT_L(n) asm volatile("s_waitcnt lgkmcnt(" #n ")" ::: "memory")
; #define BAR __builtin_amdgcn_s_barrier()
; #define SCHED __builtin_amdgcn_sched_barrier(0)
; template <bool OVL, bool PANEL = false, class Epi>
; __device__ __forceinline__ void gemm_phase(const bf16_t* __restrict__ A, long lda, const bf16_t* __restrict__ Bt, long ldb, int nM, int nN, int K,
;                                            const Epi& epi, bf16_t* shm, int w0) {
;     ...
;     for (int t = 0; t < nt - 2; t += 2) {
;       LDB(B0, 0, 0); SCHED; LDA(At, 0, 0); STAGE(SA(1, 1), A, lda, aoff, brow + HALF, t + 1);
;       WAIT_L(8); BAR; WAIT_L(0); MMA(0, 0, At, B0); BAR; SCHED;
;       LDB(B1, 0, 1); STAGE(SB(0, 0), Bt, ldb, boff, bcol, t + 2);
;       BAR; WAIT_L(0); MMA(0, 1, At, B1); BAR;
;       LDA(At, 0, 1); STAGE(SA(0, 0), A, lda, aoff, brow, t + 2);
;       BAR; WAIT_L(0); MMA(1, 0, At, B0); BAR; SCHED;
;       STAGE(SB(0, 1), Bt, ldb, boff, bcol + HALF, t + 2);
;       WAIT_V(6); BAR; MMA(1, 1, At, B1); BAR;
.LBB0_125:
	ds_read_b128 v[138:141], v218
	ds_read_b128 v[142:145], v218 offset:1024
	ds_read_b128 v[146:149], v218 offset:2048
	ds_read_b128 v[150:153], v218 offset:3072
	s_add_u32 s8, s4, s6
	s_addc_u32 s9, s5, s7
	ds_read_b128 v[154:157], v213
	ds_read_b128 v[158:161], v213 offset:1024
	ds_read_b128 v[162:165], v213 offset:2048
	ds_read_b128 v[166:169], v213 offset:3072
	ds_read_b128 v[170:173], v213 offset:4096
	ds_read_b128 v[174:177], v213 offset:5120
	ds_read_b128 v[178:181], v213 offset:6144
	ds_read_b128 v[182:185], v213 offset:7168
	s_mov_b32 m0, s25
	s_add_u32 s98, s8, s14
	s_addc_u32 s99, s9, s15
	global_load_lds_dwordx4 v203, s[98:99]
	s_mov_b32 m0, s32
	s_add_u32 s98, s8, s16
	s_addc_u32 s99, s9, s17
	global_load_lds_dwordx4 v203, s[98:99]
	s_waitcnt lgkmcnt(8)
	s_waitcnt vmcnt(10)
	s_barrier
	s_waitcnt lgkmcnt(0)
	s_setprio 1
	s_waitcnt lgkmcnt(0)
	v_mfma_f32_16x16x32_bf16 v[126:129], v[138:141], v[154:157], v[126:129]
	v_mfma_f32_16x16x32_bf16 v[122:125], v[146:149], v[154:157], v[122:125]
	v_mfma_f32_16x16x32_bf16 v[118:121], v[138:141], v[162:165], v[118:121]
	v_mfma_f32_16x16x32_bf16 v[114:117], v[146:149], v[162:165], v[114:117]
	v_mfma_f32_16x16x32_bf16 v[110:113], v[138:141], v[170:173], v[110:113]
	v_mfma_f32_16x16x32_bf16 v[106:109], v[146:149], v[170:173], v[106:109]
	v_mfma_f32_16x16x32_bf16 v[102:105], v[138:141], v[178:181], v[102:105]
	v_mfma_f32_16x16x32_bf16 v[98:101], v[146:149], v[178:181], v[98:101]
	v_mfma_f32_16x16x32_bf16 v[126:129], v[142:145], v[158:161], v[126:129]
	v_mfma_f32_16x16x32_bf16 v[122:125], v[150:153], v[158:161], v[122:125]
	v_mfma_f32_16x16x32_bf16 v[118:121], v[142:145], v[166:169], v[118:121]
	v_mfma_f32_16x16x32_bf16 v[114:117], v[150:153], v[166:169], v[114:117]
	v_mfma_f32_16x16x32_bf16 v[110:113], v[142:145], v[174:177], v[110:113]
	v_mfma_f32_16x16x32_bf16 v[106:109], v[150:153], v[174:177], v[106:109]
	v_mfma_f32_16x16x32_bf16 v[102:105], v[142:145], v[182:185], v[102:105]
	v_mfma_f32_16x16x32_bf16 v[98:101], v[150:153], v[182:185], v[98:101]
	s_setprio 0
	s_barrier
	s_add_u32 vcc_lo, s0, s6
	ds_read_b128 v[186:189], v219
	ds_read_b128 v[190:193], v219 offset:1024
	ds_read_b128 v[194:197], v219 offset:2048
	ds_read_b128 v[198:201], v219 offset:3072
	s_addc_u32 vcc_hi, s1, s7
	s_mov_b32 m0, s44
	s_add_u32 s98, vcc_lo, s34
	s_addc_u32 s99, vcc_hi, s35
	global_load_lds_dwordx4 v203, s[98:99]
	s_mov_b32 m0, s45
	s_add_u32 s98, vcc_lo, s18
	s_addc_u32 s99, vcc_hi, s19
	global_load_lds_dwordx4 v203, s[98:99]
	s_waitcnt vmcnt(10)
	s_barrier
	s_waitcnt lgkmcnt(0)
	s_setprio 1
	s_waitcnt lgkmcnt(0)
	v_mfma_f32_16x16x32_bf16 v[94:97], v[186:189], v[154:157], v[94:97]
	v_mfma_f32_16x16x32_bf16 v[90:93], v[194:197], v[154:157], v[90:93]
	v_mfma_f32_16x16x32_bf16 v[86:89], v[186:189], v[162:165], v[86:89]
	v_mfma_f32_16x16x32_bf16 v[82:85], v[194:197], v[162:165], v[82:85]
	v_mfma_f32_16x16x32_bf16 v[78:81], v[186:189], v[170:173], v[78:81]
	v_mfma_f32_16x16x32_bf16 v[74:77], v[194:197], v[170:173], v[74:77]
	v_mfma_f32_16x16x32_bf16 v[70:73], v[186:189], v[178:181], v[70:73]
	v_mfma_f32_16x16x32_bf16 v[66:69], v[194:197], v[178:181], v[66:69]
	v_mfma_f32_16x16x32_bf16 v[94:97], v[190:193], v[158:161], v[94:97]
	v_mfma_f32_16x16x32_bf16 v[90:93], v[198:201], v[158:161], v[90:93]
	v_mfma_f32_16x16x32_bf16 v[86:89], v[190:193], v[166:169], v[86:89]
	v_mfma_f32_16x16x32_bf16 v[82:85], v[198:201], v[166:169], v[82:85]
	v_mfma_f32_16x16x32_bf16 v[78:81], v[190:193], v[174:177], v[78:81]
	v_mfma_f32_16x16x32_bf16 v[74:77], v[198:201], v[174:177], v[74:77]
	v_mfma_f32_16x16x32_bf16 v[70:73], v[190:193], v[182:185], v[70:73]
	v_mfma_f32_16x16x32_bf16 v[66:69], v[198:201], v[182:185], v[66:69]
	s_setprio 0
	s_barrier
	ds_read_b128 v[154:157], v213 offset:16384
	ds_read_b128 v[158:161], v213 offset:17408
	ds_read_b128 v[162:165], v213 offset:18432
	ds_read_b128 v[166:169], v213 offset:19456
	ds_read_b128 v[170:173], v213 offset:20480
	ds_read_b128 v[174:177], v213 offset:21504
	ds_read_b128 v[178:181], v213 offset:22528
	ds_read_b128 v[182:185], v213 offset:23552
	s_mov_b32 m0, s46
	s_add_u32 s98, s8, s34
	s_addc_u32 s99, s9, s35
	global_load_lds_dwordx4 v203, s[98:99]
	s_mov_b32 m0, s47
	s_add_u32 s98, s8, s18
	s_addc_u32 s99, s9, s19
	global_load_lds_dwordx4 v203, s[98:99]
	s_barrier
	s_waitcnt lgkmcnt(0)
	s_setprio 1
	s_waitcnt lgkmcnt(0)
	v_mfma_f32_16x16x32_bf16 v[62:65], v[138:141], v[154:157], v[62:65]
	v_mfma_f32_16x16x32_bf16 v[58:61], v[146:149], v[154:157], v[58:61]
	v_mfma_f32_16x16x32_bf16 v[54:57], v[138:141], v[162:165], v[54:57]
	v_mfma_f32_16x16x32_bf16 v[50:53], v[146:149], v[162:165], v[50:53]
	v_mfma_f32_16x16x32_bf16 v[46:49], v[138:141], v[170:173], v[46:49]
	v_mfma_f32_16x16x32_bf16 v[42:45], v[146:149], v[170:173], v[42:45]
	v_mfma_f32_16x16x32_bf16 v[38:41], v[138:141], v[178:181], v[38:41]
	v_mfma_f32_16x16x32_bf16 v[34:37], v[146:149], v[178:181], v[34:37]
	v_mfma_f32_16x16x32_bf16 v[62:65], v[142:145], v[158:161], v[62:65]
	v_mfma_f32_16x16x32_bf16 v[58:61], v[150:153], v[158:161], v[58:61]
	v_mfma_f32_16x16x32_bf16 v[54:57], v[142:145], v[166:169], v[54:57]
	v_mfma_f32_16x16x32_bf16 v[50:53], v[150:153], v[166:169], v[50:53]
	v_mfma_f32_16x16x32_bf16 v[46:49], v[142:145], v[174:177], v[46:49]
	v_mfma_f32_16x16x32_bf16 v[42:45], v[150:153], v[174:177], v[42:45]
	v_mfma_f32_16x16x32_bf16 v[38:41], v[142:145], v[182:185], v[38:41]
	v_mfma_f32_16x16x32_bf16 v[34:37], v[150:153], v[182:185], v[34:37]
	s_setprio 0
	s_barrier
	s_mov_b32 m0, s48
	s_add_u32 s98, vcc_lo, s30
	s_addc_u32 s99, vcc_hi, s31
	global_load_lds_dwordx4 v203, s[98:99]
	s_mov_b32 m0, s49
	s_add_u32 s98, vcc_lo, s40
	s_addc_u32 s99, vcc_hi, s41
	global_load_lds_dwordx4 v203, s[98:99]
	s_waitcnt vmcnt(10)
	s_barrier
; #define LDA(dst, b, h) for (int m = 0; m < 4; ++m) for (int k = 0; k < 2; ++k) \
;     dst[m][k] = *reinterpret_cast<const bf16x8*>((char*)SA(b, h) + a_thr + (m * 2 + k) * 1024)
; #define LDB(dst, b, h) for (int n = 0; n < 2; ++n) for (int k = 0; k < 2; ++k) \
;     dst[n][k] = *reinterpret_cast<const bf16x8*>((char*)SB(b, h) + b_thr + (n * 2 + k) * 1024)
; #define MMA(ai, bj, At, Btf) do { __builtin_amdgcn_s_setprio(1); \
;     for (int m = 0; m < 4; ++m) for (int n = 0; n < 2; ++n) for (int k = 0; k < 2; ++k) \
;       acc[ai][bj][m][n] = __builtin_amdgcn_mfma_f32_16x16x32_bf16(Btf[n][k], At[m][k], acc[ai][bj][m][n], 0, 0, 0); \
;     __builtin_amdgcn_s_setprio(0); } while (0)
; #define WAIT_V(n) asm volatile("s_waitcnt vmcnt(" #n ")" ::: "memory")
; #define WAIT_L(n) asm volatile("s_waitcnt lgkmcnt(" #n ")" ::: "memory")
; #define BAR __builtin_amdgcn_s_barrier()
; #define SCHED __builtin_amdgcn_sched_barrier(0)
; template <bool OVL, bool PANEL = false, class Epi>
; __device__ __forceinline__ void gemm_phase(const bf16_t* __restrict__ A, long lda, const bf16_t* __restrict__ Bt, long ldb, int nM, int nN, int K,
;                                            const Epi& epi, bf16_t* shm, int w0) {
;     ...
;       WAIT_V(6); BAR; MMA(1, 1, At, B1); BAR;
;       LDB(B0, 1, 0); SCHED; LDA(At, 1, 0); STAGE(SA(0, 1), A, lda, aoff, brow + HALF, t + 2);
;       WAIT_L(8); BAR; WAIT_L(0); MMA(0, 0, At, B0); BAR; SCHED;
;       LDB(B1, 1, 1); STAGE(SB(1, 0), Bt, ldb, boff, bcol, t + 3);
;       BAR; WAIT_L(0); MMA(0, 1, At, B1); BAR;
;       LDA(At, 1, 1); STAGE(SA(1, 0), A, lda, aoff, brow, t + 3);
	s_setprio 1
	v_mfma_f32_16x16x32_bf16 v[30:33], v[186:189], v[154:157], v[30:33]
	v_mfma_f32_16x16x32_bf16 v[26:29], v[194:197], v[154:157], v[26:29]
	v_mfma_f32_16x16x32_bf16 v[22:25], v[186:189], v[162:165], v[22:25]
	v_mfma_f32_16x16x32_bf16 v[18:21], v[194:197], v[162:165], v[18:21]
	v_mfma_f32_16x16x32_bf16 v[14:17], v[186:189], v[170:173], v[14:17]
	v_mfma_f32_16x16x32_bf16 v[10:13], v[194:197], v[170:173], v[10:13]
	v_mfma_f32_16x16x32_bf16 v[6:9], v[186:189], v[178:181], v[6:9]
	v_mfma_f32_16x16x32_bf16 v[2:5], v[194:197], v[178:181], v[2:5]
	v_mfma_f32_16x16x32_bf16 v[30:33], v[190:193], v[158:161], v[30:33]
	v_mfma_f32_16x16x32_bf16 v[26:29], v[198:201], v[158:161], v[26:29]
	v_mfma_f32_16x16x32_bf16 v[22:25], v[190:193], v[166:169], v[22:25]
	v_mfma_f32_16x16x32_bf16 v[18:21], v[198:201], v[166:169], v[18:21]
	v_mfma_f32_16x16x32_bf16 v[14:17], v[190:193], v[174:177], v[14:17]
	v_mfma_f32_16x16x32_bf16 v[10:13], v[198:201], v[174:177], v[10:13]
	v_mfma_f32_16x16x32_bf16 v[6:9], v[190:193], v[182:185], v[6:9]
	v_mfma_f32_16x16x32_bf16 v[2:5], v[198:201], v[182:185], v[2:5]
	s_setprio 0
	s_barrier
	ds_read_b128 v[138:141], v220
	ds_read_b128 v[142:145], v220 offset:1024
	ds_read_b128 v[146:149], v220 offset:2048
	ds_read_b128 v[150:153], v220 offset:3072
	ds_read_b128 v[154:157], v213 offset:32768
	ds_read_b128 v[158:161], v213 offset:33792
	ds_read_b128 v[162:165], v213 offset:34816
	ds_read_b128 v[166:169], v213 offset:35840
	ds_read_b128 v[170:173], v213 offset:36864
	ds_read_b128 v[174:177], v213 offset:37888
	ds_read_b128 v[178:181], v213 offset:38912
	ds_read_b128 v[182:185], v213 offset:39936
	s_mov_b32 m0, s50
	s_add_u32 s98, s8, s30
	s_addc_u32 s99, s9, s31
	global_load_lds_dwordx4 v203, s[98:99]
	s_mov_b32 m0, s51
	s_add_u32 s98, s8, s40
	s_addc_u32 s99, s9, s41
	global_load_lds_dwordx4 v203, s[98:99]
	s_waitcnt lgkmcnt(8)
	s_waitcnt vmcnt(10)
	s_barrier
	s_waitcnt lgkmcnt(0)
	s_setprio 1
	s_waitcnt lgkmcnt(0)
	v_mfma_f32_16x16x32_bf16 v[126:129], v[138:141], v[154:157], v[126:129]
	v_mfma_f32_16x16x32_bf16 v[122:125], v[146:149], v[154:157], v[122:125]
	v_mfma_f32_16x16x32_bf16 v[118:121], v[138:141], v[162:165], v[118:121]
	v_mfma_f32_16x16x32_bf16 v[114:117], v[146:149], v[162:165], v[114:117]
	v_mfma_f32_16x16x32_bf16 v[110:113], v[138:141], v[170:173], v[110:113]
	v_mfma_f32_16x16x32_bf16 v[106:109], v[146:149], v[170:173], v[106:109]
	v_mfma_f32_16x16x32_bf16 v[102:105], v[138:141], v[178:181], v[102:105]
	v_mfma_f32_16x16x32_bf16 v[98:101], v[146:149], v[178:181], v[98:101]
	v_mfma_f32_16x16x32_bf16 v[126:129], v[142:145], v[158:161], v[126:129]
	v_mfma_f32_16x16x32_bf16 v[122:125], v[150:153], v[158:161], v[122:125]
	v_mfma_f32_16x16x32_bf16 v[118:121], v[142:145], v[166:169], v[118:121]
	v_mfma_f32_16x16x32_bf16 v[114:117], v[150:153], v[166:169], v[114:117]
	v_mfma_f32_16x16x32_bf16 v[110:113], v[142:145], v[174:177], v[110:113]
	v_mfma_f32_16x16x32_bf16 v[106:109], v[150:153], v[174:177], v[106:109]
	v_mfma_f32_16x16x32_bf16 v[102:105], v[142:145], v[182:185], v[102:105]
	v_mfma_f32_16x16x32_bf16 v[98:101], v[150:153], v[182:185], v[98:101]
	s_setprio 0
	s_barrier
	ds_read_b128 v[186:189], v221
	ds_read_b128 v[190:193], v221 offset:1024
	ds_read_b128 v[194:197], v221 offset:2048
	ds_read_b128 v[198:201], v221 offset:3072
	s_mov_b32 m0, s52
	s_add_u32 s98, vcc_lo, s94
	s_addc_u32 s99, vcc_hi, s95
	global_load_lds_dwordx4 v203, s[98:99]
	s_mov_b32 m0, s53
	s_add_u32 s98, vcc_lo, s42
	s_addc_u32 s99, vcc_hi, s43
	global_load_lds_dwordx4 v203, s[98:99]
	s_waitcnt vmcnt(10)
	s_barrier
	s_waitcnt lgkmcnt(0)
	s_setprio 1
	s_waitcnt lgkmcnt(0)
	v_mfma_f32_16x16x32_bf16 v[94:97], v[186:189], v[154:157], v[94:97]
	v_mfma_f32_16x16x32_bf16 v[90:93], v[194:197], v[154:157], v[90:93]
	v_mfma_f32_16x16x32_bf16 v[86:89], v[186:189], v[162:165], v[86:89]
	v_mfma_f32_16x16x32_bf16 v[82:85], v[194:197], v[162:165], v[82:85]
	v_mfma_f32_16x16x32_bf16 v[78:81], v[186:189], v[170:173], v[78:81]
	v_mfma_f32_16x16x32_bf16 v[74:77], v[194:197], v[170:173], v[74:77]
	v_mfma_f32_16x16x32_bf16 v[70:73], v[186:189], v[178:181], v[70:73]
	v_mfma_f32_16x16x32_bf16 v[66:69], v[194:197], v[178:181], v[66:69]
	v_mfma_f32_16x16x32_bf16 v[94:97], v[190:193], v[158:161], v[94:97]
	v_mfma_f32_16x16x32_bf16 v[90:93], v[198:201], v[158:161], v[90:93]
	v_mfma_f32_16x16x32_bf16 v[86:89], v[190:193], v[166:169], v[86:89]
	v_mfma_f32_16x16x32_bf16 v[82:85], v[198:201], v[166:169], v[82:85]
	v_mfma_f32_16x16x32_bf16 v[78:81], v[190:193], v[174:177], v[78:81]
	v_mfma_f32_16x16x32_bf16 v[74:77], v[198:201], v[174:177], v[74:77]
	v_mfma_f32_16x16x32_bf16 v[70:73], v[190:193], v[182:185], v[70:73]
	v_mfma_f32_16x16x32_bf16 v[66:69], v[198:201], v[182:185], v[66:69]
	s_setprio 0
	s_barrier
	ds_read_b128 v[154:157], v213 offset:49152
	ds_read_b128 v[158:161], v213 offset:50176
	ds_read_b128 v[162:165], v213 offset:51200
	ds_read_b128 v[166:169], v213 offset:52224
	ds_read_b128 v[170:173], v213 offset:53248
	ds_read_b128 v[174:177], v213 offset:54272
	ds_read_b128 v[178:181], v213 offset:55296
	ds_read_b128 v[182:185], v213 offset:56320
	s_mov_b32 m0, s54
	s_add_u32 s98, s8, s94
	s_addc_u32 s99, s9, s95
	global_load_lds_dwordx4 v203, s[98:99]
	s_mov_b32 m0, s55
	s_add_u32 s98, s8, s42
	s_addc_u32 s99, s9, s43
	global_load_lds_dwordx4 v203, s[98:99]
	s_barrier
; #define LDA(dst, b, h) for (int m = 0; m < 4; ++m) for (int k = 0; k < 2; ++k) \
;     dst[m][k] = *reinterpret_cast<const bf16x8*>((char*)SA(b, h) + a_thr + (m * 2 + k) * 1024)
; #define LDB(dst, b, h) for (int n = 0; n < 2; ++n) for (int k = 0; k < 2; ++k) \
;     dst[n][k] = *reinterpret_cast<const bf16x8*>((char*)SB(b, h) + b_thr + (n * 2 + k) * 1024)
; #define MMA(ai, bj, At, Btf) do { __builtin_amdgcn_s_setprio(1); \
;     for (int m = 0; m < 4; ++m) for (int n = 0; n < 2; ++n) for (int k = 0; k < 2; ++k) \
;       acc[ai][bj][m][n] = __builtin_amdgcn_mfma_f32_16x16x32_bf16(Btf[n][k], At[m][k], acc[ai][bj][m][n], 0, 0, 0); \
;     __builtin_amdgcn_s_setprio(0); } while (0)
; #define WAIT_V(n) asm volatile("s_waitcnt vmcnt(" #n ")" ::: "memory")
; #define WAIT_L(n) asm volatile("s_waitcnt lgkmcnt(" #n ")" ::: "memory")
; #define BAR __builtin_amdgcn_s_barrier()
; #define SCHED __builtin_amdgcn_sched_barrier(0)
; template <bool OVL, bool PANEL = false, class Epi>
; __device__ __forceinline__ void gemm_phase(const bf16_t* __restrict__ A, long lda, const bf16_t* __restrict__ Bt, long ldb, int nM, int nN, int K,
;                                            const Epi& epi, bf16_t* shm, int w0) {
;     ...
;       LDA(At, 1, 1); STAGE(SA(1, 0), A, lda, aoff, brow, t + 3);
;       BAR; WAIT_L(0); MMA(1, 0, At, B0); BAR; SCHED;
;       STAGE(SB(1, 1), Bt, ldb, boff, bcol + HALF, t + 3);
;       WAIT_V(6); BAR; MMA(1, 1, At, B1); BAR;
;     }
;     { LDB(B0, 0, 0); LDA(At, 0, 0); STAGE(SA(1, 1), A, lda, aoff, brow + HALF, nt - 1);
;       BAR; WAIT_L(0); MMA(0, 0, At, B0); BAR;
;       LDB(B1, 0, 1); BAR; WAIT_L(0); MMA(0, 1, At, B1); BAR;
	s_waitcnt lgkmcnt(0)
	s_setprio 1
	s_waitcnt lgkmcnt(0)
	v_mfma_f32_16x16x32_bf16 v[62:65], v[138:141], v[154:157], v[62:65]
	v_mfma_f32_16x16x32_bf16 v[58:61], v[146:149], v[154:157], v[58:61]
	v_mfma_f32_16x16x32_bf16 v[54:57], v[138:141], v[162:165], v[54:57]
	v_mfma_f32_16x16x32_bf16 v[50:53], v[146:149], v[162:165], v[50:53]
	v_mfma_f32_16x16x32_bf16 v[46:49], v[138:141], v[170:173], v[46:49]
	v_mfma_f32_16x16x32_bf16 v[42:45], v[146:149], v[170:173], v[42:45]
	v_mfma_f32_16x16x32_bf16 v[38:41], v[138:141], v[178:181], v[38:41]
	v_mfma_f32_16x16x32_bf16 v[34:37], v[146:149], v[178:181], v[34:37]
	v_mfma_f32_16x16x32_bf16 v[62:65], v[142:145], v[158:161], v[62:65]
	v_mfma_f32_16x16x32_bf16 v[58:61], v[150:153], v[158:161], v[58:61]
	v_mfma_f32_16x16x32_bf16 v[54:57], v[142:145], v[166:169], v[54:57]
	v_mfma_f32_16x16x32_bf16 v[50:53], v[150:153], v[166:169], v[50:53]
	v_mfma_f32_16x16x32_bf16 v[46:49], v[142:145], v[174:177], v[46:49]
	v_mfma_f32_16x16x32_bf16 v[42:45], v[150:153], v[174:177], v[42:45]
	v_mfma_f32_16x16x32_bf16 v[38:41], v[142:145], v[182:185], v[38:41]
	v_mfma_f32_16x16x32_bf16 v[34:37], v[150:153], v[182:185], v[34:37]
	s_setprio 0
	s_barrier
	s_mov_b64 s[8:9], 0xb0180
	s_mov_b64 s[8:9], 0x108180
	s_mov_b32 m0, s60
	s_add_u32 s98, vcc_lo, 0xb0180
	s_addc_u32 s99, vcc_hi, 0
	global_load_lds_dwordx4 v203, s[98:99]
	s_mov_b32 m0, s61
	s_add_u32 s98, vcc_lo, 0x108180
	s_addc_u32 s99, vcc_hi, 0
	global_load_lds_dwordx4 v203, s[98:99]
	s_waitcnt vmcnt(10)
	s_barrier
	s_setprio 1
	v_mfma_f32_16x16x32_bf16 v[30:33], v[186:189], v[154:157], v[30:33]
	v_mfma_f32_16x16x32_bf16 v[26:29], v[194:197], v[154:157], v[26:29]
	v_mfma_f32_16x16x32_bf16 v[22:25], v[186:189], v[162:165], v[22:25]
	v_mfma_f32_16x16x32_bf16 v[18:21], v[194:197], v[162:165], v[18:21]
	v_mfma_f32_16x16x32_bf16 v[14:17], v[186:189], v[170:173], v[14:17]
	v_mfma_f32_16x16x32_bf16 v[10:13], v[194:197], v[170:173], v[10:13]
	v_mfma_f32_16x16x32_bf16 v[6:9], v[186:189], v[178:181], v[6:9]
	v_mfma_f32_16x16x32_bf16 v[2:5], v[194:197], v[178:181], v[2:5]
	v_mfma_f32_16x16x32_bf16 v[30:33], v[190:193], v[158:161], v[30:33]
	v_mfma_f32_16x16x32_bf16 v[26:29], v[198:201], v[158:161], v[26:29]
	v_mfma_f32_16x16x32_bf16 v[22:25], v[190:193], v[166:169], v[22:25]
	v_mfma_f32_16x16x32_bf16 v[18:21], v[198:201], v[166:169], v[18:21]
	v_mfma_f32_16x16x32_bf16 v[14:17], v[190:193], v[174:177], v[14:17]
	v_mfma_f32_16x16x32_bf16 v[10:13], v[198:201], v[174:177], v[10:13]
	v_mfma_f32_16x16x32_bf16 v[6:9], v[190:193], v[182:185], v[6:9]
	v_mfma_f32_16x16x32_bf16 v[2:5], v[198:201], v[182:185], v[2:5]
	s_setprio 0
	s_add_i32 s2, s2, 2
	s_add_u32 s6, s6, 0x100
	s_addc_u32 s7, s7, 0
	s_cmp_gt_u32 s2, 39
	s_barrier
	s_cbranch_scc0 .LBB0_125
	s_waitcnt vmcnt(6)
	s_or_b32 s0, s28, 0x80
	s_mul_hi_i32 s1, s0, 0x1600
	s_mulk_i32 s0, 0x1600
	v_readlane_b32 s2, v250, 49
	v_add_u32_e32 v227, 16, v212
	s_add_u32 s0, s2, s0
	v_readlane_b32 s2, v250, 50
	v_add_u32_e32 v0, 0x10000, v227
	s_addc_u32 s1, s2, s1
	v_readfirstlane_b32 s2, v136
	ds_read_b128 v[130:133], v0
	ds_read_b128 v[138:141], v0 offset:1024
	ds_read_b128 v[142:145], v0 offset:2048
	ds_read_b128 v[146:149], v0 offset:3072
	ds_read_b128 v[150:153], v213
	ds_read_b128 v[154:157], v213 offset:1024
	ds_read_b128 v[158:161], v213 offset:2048
	ds_read_b128 v[162:165], v213 offset:3072
	ds_read_b128 v[166:169], v213 offset:4096
	ds_read_b128 v[170:173], v213 offset:5120
	ds_read_b128 v[174:177], v213 offset:6144
	ds_read_b128 v[178:181], v213 offset:7168
	v_mov_b32_e32 v0, v203
	s_mov_b32 m0, s2
	s_nop 0
	v_lshl_add_u64 v[134:135], s[0:1], 0, v[0:1]
	global_load_lds_dwordx4 v0, s[0:1]
	v_readfirstlane_b32 s0, v137
	v_lshl_add_u64 v[134:135], v[134:135], 0, s[26:27]
	s_mov_b32 m0, s0
	s_nop 0
	global_load_lds_dwordx4 v[134:135], off
	s_barrier
	s_waitcnt lgkmcnt(0)
	s_setprio 1
	s_waitcnt lgkmcnt(0)
	v_mfma_f32_16x16x32_bf16 v[126:129], v[130:133], v[150:153], v[126:129]
	v_mfma_f32_16x16x32_bf16 v[122:125], v[142:145], v[150:153], v[122:125]
	v_mfma_f32_16x16x32_bf16 v[118:121], v[130:133], v[158:161], v[118:121]
	v_mfma_f32_16x16x32_bf16 v[114:117], v[142:145], v[158:161], v[114:117]
	v_mfma_f32_16x16x32_bf16 v[110:113], v[130:133], v[166:169], v[110:113]
	v_mfma_f32_16x16x32_bf16 v[106:109], v[142:145], v[166:169], v[106:109]
	v_mfma_f32_16x16x32_bf16 v[102:105], v[130:133], v[174:177], v[102:105]
	v_mfma_f32_16x16x32_bf16 v[98:101], v[142:145], v[174:177], v[98:101]
	v_mfma_f32_16x16x32_bf16 v[126:129], v[138:141], v[154:157], v[126:129]
	v_mfma_f32_16x16x32_bf16 v[122:125], v[146:149], v[154:157], v[122:125]
	v_mfma_f32_16x16x32_bf16 v[118:121], v[138:141], v[162:165], v[118:121]
	v_mfma_f32_16x16x32_bf16 v[114:117], v[146:149], v[162:165], v[114:117]
	v_mfma_f32_16x16x32_bf16 v[110:113], v[138:141], v[170:173], v[110:113]
	v_mfma_f32_16x16x32_bf16 v[106:109], v[146:149], v[170:173], v[106:109]
	v_mfma_f32_16x16x32_bf16 v[102:105], v[138:141], v[178:181], v[102:105]
	v_mfma_f32_16x16x32_bf16 v[98:101], v[146:149], v[178:181], v[98:101]
	s_setprio 0
	v_add_u32_e32 v0, 0x14000, v227
	s_barrier
	ds_read_b128 v[134:137], v0
	ds_read_b128 v[182:185], v0 offset:1024
	ds_read_b128 v[186:189], v0 offset:2048
	ds_read_b128 v[190:193], v0 offset:3072
	s_barrier
; #define LDA(dst, b, h) for (int m = 0; m < 4; ++m) for (int k = 0; k < 2; ++k) \
;     dst[m][k] = *reinterpret_cast<const bf16x8*>((char*)SA(b, h) + a_thr + (m * 2 + k) * 1024)
; #define LDB(dst, b, h) for (int n = 0; n < 2; ++n) for (int k = 0; k < 2; ++k) \
;     dst[n][k] = *reinterpret_cast<const bf16x8*>((char*)SB(b, h) + b_thr + (n * 2 + k) * 1024)
; #define MMA(ai, bj, At, Btf) do { __builtin_amdgcn_s_setprio(1); \
;     for (int m = 0; m < 4; ++m) for (int n = 0; n < 2; ++n) for (int k = 0; k < 2; ++k) \
;       acc[ai][bj][m][n] = __builtin_amdgcn_mfma_f32_16x16x32_bf16(Btf[n][k], At[m][k], acc[ai][bj][m][n], 0, 0, 0); \
;     __builtin_amdgcn_s_setprio(0); } while (0)
; #define WAIT_V(n) asm volatile("s_waitcnt vmcnt(" #n ")" ::: "memory")
; #define WAIT_L(n) asm volatile("s_waitcnt lgkmcnt(" #n ")" ::: "memory")
; #define BAR __builtin_amdgcn_s_barrier()
; template <bool OVL, bool PANEL = false, class Epi>
; __device__ __forceinline__ void gemm_phase(const bf16_t* __restrict__ A, long lda, const bf16_t* __restrict__ Bt, long ldb, int nM, int nN, int K,
;                                            const Epi& epi, bf16_t* shm, int w0) {
;     ...
;       LDB(B1, 0, 1); BAR; WAIT_L(0); MMA(0, 1, At, B1); BAR;
;       LDA(At, 0, 1); WAIT_V(4); BAR; WAIT_L(0); MMA(1, 0, At, B0); MMA(1, 1, At, B1); BAR; }
;     { LDB(B0, 1, 0); LDA(At, 1, 0); WAIT_V(2); BAR; WAIT_L(0); MMA(0, 0, At, B0); BAR;
	s_waitcnt lgkmcnt(0)
	s_setprio 1
	s_waitcnt lgkmcnt(0)
	v_mfma_f32_16x16x32_bf16 v[94:97], v[134:137], v[150:153], v[94:97]
	v_mfma_f32_16x16x32_bf16 v[90:93], v[186:189], v[150:153], v[90:93]
	v_mfma_f32_16x16x32_bf16 v[86:89], v[134:137], v[158:161], v[86:89]
	v_mfma_f32_16x16x32_bf16 v[82:85], v[186:189], v[158:161], v[82:85]
	v_mfma_f32_16x16x32_bf16 v[78:81], v[134:137], v[166:169], v[78:81]
	v_mfma_f32_16x16x32_bf16 v[66:69], v[186:189], v[174:177], v[66:69]
	v_mfma_f32_16x16x32_bf16 v[94:97], v[182:185], v[154:157], v[94:97]
	v_mfma_f32_16x16x32_bf16 v[90:93], v[190:193], v[154:157], v[90:93]
	v_mfma_f32_16x16x32_bf16 v[86:89], v[182:185], v[162:165], v[86:89]
	v_mfma_f32_16x16x32_bf16 v[82:85], v[190:193], v[162:165], v[82:85]
	v_mfma_f32_16x16x32_bf16 v[78:81], v[182:185], v[170:173], v[78:81]
	v_mfma_f32_16x16x32_bf16 v[74:77], v[186:189], v[166:169], v[74:77]
	v_mfma_f32_16x16x32_bf16 v[70:73], v[134:137], v[174:177], v[70:73]
	v_mfma_f32_16x16x32_bf16 v[66:69], v[190:193], v[178:181], v[66:69]
	v_mfma_f32_16x16x32_bf16 v[150:153], v[190:193], v[170:173], v[74:77]
	v_mfma_f32_16x16x32_bf16 v[154:157], v[182:185], v[178:181], v[70:73]
	s_setprio 0
	s_barrier
	s_nop 2
	ds_read_b128 v[70:73], v213 offset:16384
	ds_read_b128 v[74:77], v213 offset:17408
	ds_read_b128 v[158:161], v213 offset:18432
	ds_read_b128 v[162:165], v213 offset:19456
	ds_read_b128 v[166:169], v213 offset:20480
	ds_read_b128 v[170:173], v213 offset:21504
	ds_read_b128 v[174:177], v213 offset:22528
	ds_read_b128 v[178:181], v213 offset:23552
	s_waitcnt vmcnt(4)
	s_barrier
	s_waitcnt lgkmcnt(0)
	s_setprio 1
	s_waitcnt lgkmcnt(0)
	v_mfma_f32_16x16x32_bf16 v[58:61], v[142:145], v[70:73], v[58:61]
	v_mfma_f32_16x16x32_bf16 v[54:57], v[130:133], v[158:161], v[54:57]
	v_mfma_f32_16x16x32_bf16 v[62:65], v[130:133], v[70:73], v[62:65]
	v_mfma_f32_16x16x32_bf16 v[58:61], v[146:149], v[74:77], v[58:61]
	v_mfma_f32_16x16x32_bf16 v[54:57], v[138:141], v[162:165], v[54:57]
	v_mfma_f32_16x16x32_bf16 v[50:53], v[142:145], v[158:161], v[50:53]
	v_mfma_f32_16x16x32_bf16 v[46:49], v[130:133], v[166:169], v[46:49]
	v_mfma_f32_16x16x32_bf16 v[42:45], v[142:145], v[166:169], v[42:45]
	v_mfma_f32_16x16x32_bf16 v[38:41], v[130:133], v[174:177], v[38:41]
	v_mfma_f32_16x16x32_bf16 v[34:37], v[142:145], v[174:177], v[34:37]
	v_mfma_f32_16x16x32_bf16 v[194:197], v[138:141], v[74:77], v[62:65]
	v_mfma_f32_16x16x32_bf16 v[198:201], v[146:149], v[162:165], v[50:53]
	v_mfma_f32_16x16x32_bf16 v[214:217], v[138:141], v[170:173], v[46:49]
	v_mfma_f32_16x16x32_bf16 v[218:221], v[146:149], v[170:173], v[42:45]
	v_mfma_f32_16x16x32_bf16 v[130:133], v[138:141], v[178:181], v[38:41]
	v_mfma_f32_16x16x32_bf16 v[138:141], v[146:149], v[178:181], v[34:37]
	s_setprio 0
	s_setprio 1
	v_mfma_f32_16x16x32_bf16 v[30:33], v[134:137], v[70:73], v[30:33]
	v_mfma_f32_16x16x32_bf16 v[26:29], v[186:189], v[70:73], v[26:29]
	v_mfma_f32_16x16x32_bf16 v[22:25], v[134:137], v[158:161], v[22:25]
	v_mfma_f32_16x16x32_bf16 v[18:21], v[186:189], v[158:161], v[18:21]
	v_mfma_f32_16x16x32_bf16 v[14:17], v[134:137], v[166:169], v[14:17]
	v_mfma_f32_16x16x32_bf16 v[10:13], v[186:189], v[166:169], v[10:13]
	v_mfma_f32_16x16x32_bf16 v[6:9], v[134:137], v[174:177], v[6:9]
	v_mfma_f32_16x16x32_bf16 v[2:5], v[186:189], v[174:177], v[2:5]
	v_mfma_f32_16x16x32_bf16 v[142:145], v[182:185], v[74:77], v[30:33]
	v_mfma_f32_16x16x32_bf16 v[146:149], v[190:193], v[74:77], v[26:29]
	v_mfma_f32_16x16x32_bf16 v[222:225], v[182:185], v[162:165], v[22:25]
	v_mfma_f32_16x16x32_bf16 v[158:161], v[190:193], v[162:165], v[18:21]
	v_mfma_f32_16x16x32_bf16 v[162:165], v[182:185], v[170:173], v[14:17]
	v_mfma_f32_16x16x32_bf16 v[166:169], v[190:193], v[170:173], v[10:13]
	v_mfma_f32_16x16x32_bf16 v[134:137], v[182:185], v[178:181], v[6:9]
	v_mfma_f32_16x16x32_bf16 v[170:173], v[190:193], v[178:181], v[2:5]
	s_setprio 0
	v_add_u32_e32 v0, 0x18000, v227
	s_barrier
	ds_read_b128 v[34:37], v0
	ds_read_b128 v[174:177], v0 offset:1024
	ds_read_b128 v[178:181], v0 offset:2048
	ds_read_b128 v[182:185], v0 offset:3072
	ds_read_b128 v[18:21], v213 offset:32768
	ds_read_b128 v[22:25], v213 offset:33792
	ds_read_b128 v[26:29], v213 offset:34816
	ds_read_b128 v[50:53], v213 offset:35840
	ds_read_b128 v[186:189], v213 offset:36864
	ds_read_b128 v[190:193], v213 offset:37888
	ds_read_b128 v[228:231], v213 offset:38912
	ds_read_b128 v[232:235], v213 offset:39936
	s_waitcnt vmcnt(2)
	s_barrier
; #define LDA(dst, b, h) for (int m = 0; m < 4; ++m) for (int k = 0; k < 2; ++k) \
;     dst[m][k] = *reinterpret_cast<const bf16x8*>((char*)SA(b, h) + a_thr + (m * 2 + k) * 1024)
; #define LDB(dst, b, h) for (int n = 0; n < 2; ++n) for (int k = 0; k < 2; ++k) \
;     dst[n][k] = *reinterpret_cast<const bf16x8*>((char*)SB(b, h) + b_thr + (n * 2 + k) * 1024)
; #define MMA(ai, bj, At, Btf) do { __builtin_amdgcn_s_setprio(1); \
;     for (int m = 0; m < 4; ++m) for (int n = 0; n < 2; ++n) for (int k = 0; k < 2; ++k) \
;       acc[ai][bj][m][n] = __builtin_amdgcn_mfma_f32_16x16x32_bf16(Btf[n][k], At[m][k], acc[ai][bj][m][n], 0, 0, 0); \
;     __builtin_amdgcn_s_setprio(0); } while (0)
; #define WAIT_V(n) asm volatile("s_waitcnt vmcnt(" #n ")" ::: "memory")
; #define WAIT_L(n) asm volatile("s_waitcnt lgkmcnt(" #n ")" ::: "memory")
; #define BAR __builtin_amdgcn_s_barrier()
; template <bool OVL, bool PANEL = false, class Epi>
; __device__ __forceinline__ void gemm_phase(const bf16_t* __restrict__ A, long lda, const bf16_t* __restrict__ Bt, long ldb, int nM, int nN, int K,
;                                            const Epi& epi, bf16_t* shm, int w0) {
;     ...
;     { LDB(B0, 1, 0); LDA(At, 1, 0); WAIT_V(2); BAR; WAIT_L(0); MMA(0, 0, At, B0); BAR;
;       LDB(B1, 1, 1); WAIT_V(0); BAR; WAIT_L(0); MMA(0, 1, At, B1); BAR;
;       LDA(At, 1, 1); BAR; WAIT_L(0); MMA(1, 0, At, B0); MMA(1, 1, At, B1); BAR; }
;     if (wr == 0) BAR;
	s_waitcnt lgkmcnt(0)
	s_setprio 1
	s_waitcnt lgkmcnt(0)
	v_mfma_f32_16x16x32_bf16 v[6:9], v[178:181], v[18:21], v[122:125]
	v_mfma_f32_16x16x32_bf16 v[10:13], v[178:181], v[26:29], v[114:117]
	v_mfma_f32_16x16x32_bf16 v[14:17], v[178:181], v[186:189], v[106:109]
	v_mfma_f32_16x16x32_bf16 v[2:5], v[34:37], v[18:21], v[126:129]
	v_mfma_f32_16x16x32_bf16 v[30:33], v[182:185], v[22:25], v[6:9]
	v_mfma_f32_16x16x32_bf16 v[6:9], v[34:37], v[26:29], v[118:121]
	v_mfma_f32_16x16x32_bf16 v[38:41], v[182:185], v[50:53], v[10:13]
	v_mfma_f32_16x16x32_bf16 v[10:13], v[34:37], v[186:189], v[110:113]
	v_mfma_f32_16x16x32_bf16 v[42:45], v[182:185], v[190:193], v[14:17]
	v_mfma_f32_16x16x32_bf16 v[14:17], v[34:37], v[228:231], v[102:105]
	v_mfma_f32_16x16x32_bf16 v[46:49], v[178:181], v[228:231], v[98:101]
	v_mfma_f32_16x16x32_bf16 v[2:5], v[174:177], v[22:25], v[2:5]
	v_mfma_f32_16x16x32_bf16 v[6:9], v[174:177], v[50:53], v[6:9]
	v_mfma_f32_16x16x32_bf16 v[10:13], v[174:177], v[190:193], v[10:13]
	v_mfma_f32_16x16x32_bf16 v[14:17], v[174:177], v[232:235], v[14:17]
	v_mfma_f32_16x16x32_bf16 v[46:49], v[182:185], v[232:235], v[46:49]
	s_setprio 0
	v_add_u32_e32 v0, 0x1c000, v227
	s_barrier
	ds_read_b128 v[102:105], v0
	ds_read_b128 v[236:239], v0 offset:1024
	ds_read_b128 v[240:243], v0 offset:2048
	ds_read_b128 v[244:247], v0 offset:3072
	s_waitcnt vmcnt(0)
	s_barrier
	s_waitcnt lgkmcnt(0)
	s_setprio 1
	s_waitcnt lgkmcnt(0)
	v_mfma_f32_16x16x32_bf16 v[62:65], v[102:105], v[18:21], v[94:97]
	v_mfma_f32_16x16x32_bf16 v[18:21], v[240:243], v[18:21], v[90:93]
	v_mfma_f32_16x16x32_bf16 v[98:101], v[244:247], v[22:25], v[18:21]
	v_mfma_f32_16x16x32_bf16 v[18:21], v[102:105], v[26:29], v[86:89]
	v_mfma_f32_16x16x32_bf16 v[70:73], v[236:239], v[50:53], v[18:21]
	v_mfma_f32_16x16x32_bf16 v[18:21], v[240:243], v[26:29], v[82:85]
	v_mfma_f32_16x16x32_bf16 v[106:109], v[244:247], v[50:53], v[18:21]
	v_mfma_f32_16x16x32_bf16 v[18:21], v[102:105], v[186:189], v[78:81]
	v_mfma_f32_16x16x32_bf16 v[74:77], v[236:239], v[190:193], v[18:21]
	v_mfma_f32_16x16x32_bf16 v[18:21], v[240:243], v[186:189], v[150:153]
	v_mfma_f32_16x16x32_bf16 v[110:113], v[244:247], v[190:193], v[18:21]
	v_mfma_f32_16x16x32_bf16 v[18:21], v[102:105], v[228:231], v[154:157]
	v_mfma_f32_16x16x32_bf16 v[78:81], v[236:239], v[232:235], v[18:21]
	v_mfma_f32_16x16x32_bf16 v[18:21], v[240:243], v[228:231], v[66:69]
	v_mfma_f32_16x16x32_bf16 v[62:65], v[236:239], v[22:25], v[62:65]
	v_mfma_f32_16x16x32_bf16 v[114:117], v[244:247], v[232:235], v[18:21]
	s_setprio 0
	s_barrier
	ds_read_b128 v[86:89], v213 offset:49152
	ds_read_b128 v[90:93], v213 offset:50176
	ds_read_b128 v[94:97], v213 offset:51200
	ds_read_b128 v[118:121], v213 offset:52224
	ds_read_b128 v[150:153], v213 offset:53248
	ds_read_b128 v[154:157], v213 offset:54272
	ds_read_b128 v[186:189], v213 offset:55296
	ds_read_b128 v[190:193], v213 offset:56320
	s_barrier
	s_waitcnt lgkmcnt(0)
	s_setprio 1
	s_waitcnt lgkmcnt(0)
	v_mfma_f32_16x16x32_bf16 v[22:25], v[178:181], v[86:89], v[58:61]
	v_mfma_f32_16x16x32_bf16 v[26:29], v[178:181], v[94:97], v[198:201]
	v_mfma_f32_16x16x32_bf16 v[18:21], v[34:37], v[86:89], v[194:197]
	v_mfma_f32_16x16x32_bf16 v[50:53], v[182:185], v[90:93], v[22:25]
	v_mfma_f32_16x16x32_bf16 v[22:25], v[34:37], v[94:97], v[54:57]
	v_mfma_f32_16x16x32_bf16 v[54:57], v[182:185], v[118:121], v[26:29]
	v_mfma_f32_16x16x32_bf16 v[26:29], v[34:37], v[150:153], v[214:217]
	v_mfma_f32_16x16x32_bf16 v[58:61], v[178:181], v[150:153], v[218:221]
	v_mfma_f32_16x16x32_bf16 v[34:37], v[34:37], v[186:189], v[130:133]
	v_mfma_f32_16x16x32_bf16 v[66:69], v[178:181], v[186:189], v[138:141]
	v_mfma_f32_16x16x32_bf16 v[18:21], v[174:177], v[90:93], v[18:21]
	v_mfma_f32_16x16x32_bf16 v[22:25], v[174:177], v[118:121], v[22:25]
	v_mfma_f32_16x16x32_bf16 v[26:29], v[174:177], v[154:157], v[26:29]
	v_mfma_f32_16x16x32_bf16 v[58:61], v[182:185], v[154:157], v[58:61]
	v_mfma_f32_16x16x32_bf16 v[34:37], v[174:177], v[190:193], v[34:37]
	v_mfma_f32_16x16x32_bf16 v[66:69], v[182:185], v[190:193], v[66:69]
	s_setprio 0
	s_setprio 1
	v_mfma_f32_16x16x32_bf16 v[82:85], v[102:105], v[86:89], v[142:145]
	v_mfma_f32_16x16x32_bf16 v[86:89], v[240:243], v[86:89], v[146:149]
	v_mfma_f32_16x16x32_bf16 v[82:85], v[236:239], v[90:93], v[82:85]
	v_mfma_f32_16x16x32_bf16 v[122:125], v[244:247], v[90:93], v[86:89]
	v_mfma_f32_16x16x32_bf16 v[86:89], v[102:105], v[94:97], v[222:225]
	v_mfma_f32_16x16x32_bf16 v[90:93], v[240:243], v[94:97], v[158:161]
	v_mfma_f32_16x16x32_bf16 v[94:97], v[240:243], v[150:153], v[166:169]
	v_mfma_f32_16x16x32_bf16 v[86:89], v[236:239], v[118:121], v[86:89]
	v_mfma_f32_16x16x32_bf16 v[126:129], v[244:247], v[118:121], v[90:93]
	v_mfma_f32_16x16x32_bf16 v[118:121], v[244:247], v[154:157], v[94:97]
	v_mfma_f32_16x16x32_bf16 v[94:97], v[102:105], v[186:189], v[134:137]
	v_mfma_f32_16x16x32_bf16 v[90:93], v[102:105], v[150:153], v[162:165]
	v_mfma_f32_16x16x32_bf16 v[102:105], v[236:239], v[190:193], v[94:97]
	v_mfma_f32_16x16x32_bf16 v[94:97], v[240:243], v[186:189], v[170:173]
	v_mfma_f32_16x16x32_bf16 v[90:93], v[236:239], v[154:157], v[90:93]
	v_mfma_f32_16x16x32_bf16 v[94:97], v[244:247], v[190:193], v[94:97]
	s_setprio 0
	s_barrier
	s_and_saveexec_b64 s[0:1], s[58:59]
	s_cbranch_execz .LBB0_128
	s_barrier

; #define LDA(dst, b, h) for (int m = 0; m < 4; ++m) for (int k = 0; k < 2; ++k) \
;     dst[m][k] = *reinterpret_cast<const bf16x8*>((char*)SA(b, h) + a_thr + (m * 2 + k) * 1024)
; #define LDB(dst, b, h) for (int n = 0; n < 2; ++n) for (int k = 0; k < 2; ++k) \
;     dst[n][k] = *reinterpret_cast<const bf16x8*>((char*)SB(b, h) + b_thr + (n * 2 + k) * 1024)
; #define MMA(ai, bj, At, Btf) do { __builtin_amdgcn_s_setprio(1); \
;     for (int m = 0; m < 4; ++m) for (int n = 0; n < 2; ++n) for (int k = 0; k < 2; ++k) \
;       acc[ai][bj][m][n] = __builtin_amdgcn_mfma_f32_16x16x32_bf16(Btf[n][k], At[m][k], acc[ai][bj][m][n], 0, 0, 0); \
;     __builtin_amdgcn_s_setprio(0); } while (0)
; #define WAIT_V(n) asm volatile("s_waitcnt vmcnt(" #n ")" ::: "memory")
; #define WAIT_L(n) asm volatile("s_waitcnt lgkmcnt(" #n ")" ::: "memory")
; #define BAR __builtin_amdgcn_s_barrier()
; #define SCHED __builtin_amdgcn_sched_barrier(0)
; template <bool OVL, bool PANEL = false, class Epi>
; __device__ __forceinline__ void gemm_phase(const bf16_t* __restrict__ A, long lda, const bf16_t* __restrict__ Bt, long ldb, int nM, int nN, int K,
;                                            const Epi& epi, bf16_t* shm, int w0) {
;     ...
;     for (int t = 0; t < nt - 2; t += 2) {
;       LDB(B0, 0, 0); SCHED; LDA(At, 0, 0); STAGE(SA(1, 1), A, lda, aoff, brow + HALF, t + 1);
;       WAIT_L(8); BAR; WAIT_L(0); MMA(0, 0, At, B0); BAR; SCHED;
;       LDB(B1, 0, 1); STAGE(SB(0, 0), Bt, ldb, boff, bcol, t + 2);
;       BAR; WAIT_L(0); MMA(0, 1, At, B1); BAR;
;       LDA(At, 0, 1); STAGE(SA(0, 0), A, lda, aoff, brow, t + 2);
;       BAR; WAIT_L(0); MMA(1, 0, At, B0); BAR; SCHED;
;       STAGE(SB(0, 1), Bt, ldb, boff, bcol + HALF, t + 2);
;       WAIT_V(6); BAR; MMA(1, 1, At, B1); BAR;
.LBB0_386:
	ds_read_b128 v[150:153], v218
	ds_read_b128 v[154:157], v218 offset:1024
	ds_read_b128 v[158:161], v218 offset:2048
	ds_read_b128 v[162:165], v218 offset:3072
	s_add_u32 s42, s10, vcc_lo
	s_addc_u32 s43, s11, vcc_hi
	ds_read_b128 v[166:169], v141
	ds_read_b128 v[170:173], v141 offset:1024
	ds_read_b128 v[174:177], v141 offset:2048
	ds_read_b128 v[178:181], v141 offset:3072
	ds_read_b128 v[182:185], v141 offset:4096
	ds_read_b128 v[186:189], v141 offset:5120
	ds_read_b128 v[190:193], v141 offset:6144
	ds_read_b128 v[194:197], v141 offset:7168
	s_mov_b32 m0, s16
	s_add_u32 s98, s42, s28
	s_addc_u32 s99, s43, s29
	global_load_lds_dwordx4 v131, s[98:99]
	s_mov_b32 m0, s32
	s_add_u32 s98, s42, s36
	s_addc_u32 s99, s43, s37
	global_load_lds_dwordx4 v131, s[98:99]
	s_waitcnt lgkmcnt(8)
	s_waitcnt vmcnt(10)
	s_barrier
	s_waitcnt lgkmcnt(0)
	s_setprio 1
	s_waitcnt lgkmcnt(0)
	v_mfma_f32_16x16x32_bf16 v[126:129], v[150:153], v[166:169], v[126:129]
	v_mfma_f32_16x16x32_bf16 v[122:125], v[158:161], v[166:169], v[122:125]
	v_mfma_f32_16x16x32_bf16 v[118:121], v[150:153], v[174:177], v[118:121]
	v_mfma_f32_16x16x32_bf16 v[114:117], v[158:161], v[174:177], v[114:117]
	v_mfma_f32_16x16x32_bf16 v[110:113], v[150:153], v[182:185], v[110:113]
	v_mfma_f32_16x16x32_bf16 v[106:109], v[158:161], v[182:185], v[106:109]
	v_mfma_f32_16x16x32_bf16 v[102:105], v[150:153], v[190:193], v[102:105]
	v_mfma_f32_16x16x32_bf16 v[98:101], v[158:161], v[190:193], v[98:101]
	v_mfma_f32_16x16x32_bf16 v[126:129], v[154:157], v[170:173], v[126:129]
	v_mfma_f32_16x16x32_bf16 v[122:125], v[162:165], v[170:173], v[122:125]
	v_mfma_f32_16x16x32_bf16 v[118:121], v[154:157], v[178:181], v[118:121]
	v_mfma_f32_16x16x32_bf16 v[114:117], v[162:165], v[178:181], v[114:117]
	v_mfma_f32_16x16x32_bf16 v[110:113], v[154:157], v[186:189], v[110:113]
	v_mfma_f32_16x16x32_bf16 v[106:109], v[162:165], v[186:189], v[106:109]
	v_mfma_f32_16x16x32_bf16 v[102:105], v[154:157], v[194:197], v[102:105]
	v_mfma_f32_16x16x32_bf16 v[98:101], v[162:165], v[194:197], v[98:101]
	s_setprio 0
	s_barrier
	s_add_u32 s66, s8, vcc_lo
	ds_read_b128 v[198:201], v219
	ds_read_b128 v[202:205], v219 offset:1024
	ds_read_b128 v[206:209], v219 offset:2048
	ds_read_b128 v[210:213], v219 offset:3072
	s_addc_u32 s67, s9, vcc_hi
	s_mov_b32 m0, s46
	s_add_u32 s98, s66, s34
	s_addc_u32 s99, s67, s35
	global_load_lds_dwordx4 v131, s[98:99]
	s_mov_b32 m0, s47
	s_add_u32 s98, s66, s64
	s_addc_u32 s99, s67, s65
	global_load_lds_dwordx4 v131, s[98:99]
	s_waitcnt vmcnt(10)
	s_barrier
	s_waitcnt lgkmcnt(0)
	s_setprio 1
	s_waitcnt lgkmcnt(0)
	v_mfma_f32_16x16x32_bf16 v[94:97], v[198:201], v[166:169], v[94:97]
	v_mfma_f32_16x16x32_bf16 v[90:93], v[206:209], v[166:169], v[90:93]
	v_mfma_f32_16x16x32_bf16 v[86:89], v[198:201], v[174:177], v[86:89]
	v_mfma_f32_16x16x32_bf16 v[82:85], v[206:209], v[174:177], v[82:85]
	v_mfma_f32_16x16x32_bf16 v[78:81], v[198:201], v[182:185], v[78:81]
	v_mfma_f32_16x16x32_bf16 v[74:77], v[206:209], v[182:185], v[74:77]
	v_mfma_f32_16x16x32_bf16 v[70:73], v[198:201], v[190:193], v[70:73]
	v_mfma_f32_16x16x32_bf16 v[66:69], v[206:209], v[190:193], v[66:69]
	v_mfma_f32_16x16x32_bf16 v[94:97], v[202:205], v[170:173], v[94:97]
	v_mfma_f32_16x16x32_bf16 v[90:93], v[210:213], v[170:173], v[90:93]
	v_mfma_f32_16x16x32_bf16 v[86:89], v[202:205], v[178:181], v[86:89]
	v_mfma_f32_16x16x32_bf16 v[82:85], v[210:213], v[178:181], v[82:85]
	v_mfma_f32_16x16x32_bf16 v[78:81], v[202:205], v[186:189], v[78:81]
	v_mfma_f32_16x16x32_bf16 v[74:77], v[210:213], v[186:189], v[74:77]
	v_mfma_f32_16x16x32_bf16 v[70:73], v[202:205], v[194:197], v[70:73]
	v_mfma_f32_16x16x32_bf16 v[66:69], v[210:213], v[194:197], v[66:69]
	s_setprio 0
	s_barrier
	ds_read_b128 v[166:169], v141 offset:16384
	ds_read_b128 v[170:173], v141 offset:17408
	ds_read_b128 v[174:177], v141 offset:18432
	ds_read_b128 v[178:181], v141 offset:19456
	ds_read_b128 v[182:185], v141 offset:20480
	ds_read_b128 v[186:189], v141 offset:21504
	ds_read_b128 v[190:193], v141 offset:22528
	ds_read_b128 v[194:197], v141 offset:23552
	s_mov_b32 m0, s48
	s_add_u32 s98, s42, s34
	s_addc_u32 s99, s43, s35
	global_load_lds_dwordx4 v131, s[98:99]
	s_mov_b32 m0, s49
	s_add_u32 s98, s42, s64
	s_addc_u32 s99, s43, s65
	global_load_lds_dwordx4 v131, s[98:99]
	s_barrier
	s_waitcnt lgkmcnt(0)
	s_setprio 1
	s_waitcnt lgkmcnt(0)
	v_mfma_f32_16x16x32_bf16 v[62:65], v[150:153], v[166:169], v[62:65]
	v_mfma_f32_16x16x32_bf16 v[58:61], v[158:161], v[166:169], v[58:61]
	v_mfma_f32_16x16x32_bf16 v[54:57], v[150:153], v[174:177], v[54:57]
	v_mfma_f32_16x16x32_bf16 v[50:53], v[158:161], v[174:177], v[50:53]
	v_mfma_f32_16x16x32_bf16 v[46:49], v[150:153], v[182:185], v[46:49]
	v_mfma_f32_16x16x32_bf16 v[42:45], v[158:161], v[182:185], v[42:45]
	v_mfma_f32_16x16x32_bf16 v[38:41], v[150:153], v[190:193], v[38:41]
	v_mfma_f32_16x16x32_bf16 v[34:37], v[158:161], v[190:193], v[34:37]
	v_mfma_f32_16x16x32_bf16 v[62:65], v[154:157], v[170:173], v[62:65]
	v_mfma_f32_16x16x32_bf16 v[58:61], v[162:165], v[170:173], v[58:61]
	v_mfma_f32_16x16x32_bf16 v[54:57], v[154:157], v[178:181], v[54:57]
	v_mfma_f32_16x16x32_bf16 v[50:53], v[162:165], v[178:181], v[50:53]
	v_mfma_f32_16x16x32_bf16 v[46:49], v[154:157], v[186:189], v[46:49]
	v_mfma_f32_16x16x32_bf16 v[42:45], v[162:165], v[186:189], v[42:45]
	v_mfma_f32_16x16x32_bf16 v[38:41], v[154:157], v[194:197], v[38:41]
	v_mfma_f32_16x16x32_bf16 v[34:37], v[162:165], v[194:197], v[34:37]
	s_setprio 0
	s_barrier
	s_mov_b32 m0, s50
	s_add_u32 s98, s66, s68
	s_addc_u32 s99, s67, s69
	global_load_lds_dwordx4 v131, s[98:99]
	s_mov_b32 m0, s51
	s_add_u32 s98, s66, s70
	s_addc_u32 s99, s67, s71
	global_load_lds_dwordx4 v131, s[98:99]
	s_waitcnt vmcnt(10)
	s_barrier
; #define LDA(dst, b, h) for (int m = 0; m < 4; ++m) for (int k = 0; k < 2; ++k) \
;     dst[m][k] = *reinterpret_cast<const bf16x8*>((char*)SA(b, h) + a_thr + (m * 2 + k) * 1024)
; #define LDB(dst, b, h) for (int n = 0; n < 2; ++n) for (int k = 0; k < 2; ++k) \
;     dst[n][k] = *reinterpret_cast<const bf16x8*>((char*)SB(b, h) + b_thr + (n * 2 + k) * 1024)
; #define MMA(ai, bj, At, Btf) do { __builtin_amdgcn_s_setprio(1); \
;     for (int m = 0; m < 4; ++m) for (int n = 0; n < 2; ++n) for (int k = 0; k < 2; ++k) \
;       acc[ai][bj][m][n] = __builtin_amdgcn_mfma_f32_16x16x32_bf16(Btf[n][k], At[m][k], acc[ai][bj][m][n], 0, 0, 0); \
;     __builtin_amdgcn_s_setprio(0); } while (0)
; #define WAIT_V(n) asm volatile("s_waitcnt vmcnt(" #n ")" ::: "memory")
; #define WAIT_L(n) asm volatile("s_waitcnt lgkmcnt(" #n ")" ::: "memory")
; #define BAR __builtin_amdgcn_s_barrier()
; #define SCHED __builtin_amdgcn_sched_barrier(0)
; template <bool OVL, bool PANEL = false, class Epi>
; __device__ __forceinline__ void gemm_phase(const bf16_t* __restrict__ A, long lda, const bf16_t* __restrict__ Bt, long ldb, int nM, int nN, int K,
;                                            const Epi& epi, bf16_t* shm, int w0) {
;     ...
;       WAIT_V(6); BAR; MMA(1, 1, At, B1); BAR;
;       LDB(B0, 1, 0); SCHED; LDA(At, 1, 0); STAGE(SA(0, 1), A, lda, aoff, brow + HALF, t + 2);
;       WAIT_L(8); BAR; WAIT_L(0); MMA(0, 0, At, B0); BAR; SCHED;
;       LDB(B1, 1, 1); STAGE(SB(1, 0), Bt, ldb, boff, bcol, t + 3);
;       BAR; WAIT_L(0); MMA(0, 1, At, B1); BAR;
;       LDA(At, 1, 1); STAGE(SA(1, 0), A, lda, aoff, brow, t + 3);
	s_setprio 1
	v_mfma_f32_16x16x32_bf16 v[30:33], v[198:201], v[166:169], v[30:33]
	v_mfma_f32_16x16x32_bf16 v[26:29], v[206:209], v[166:169], v[26:29]
	v_mfma_f32_16x16x32_bf16 v[22:25], v[198:201], v[174:177], v[22:25]
	v_mfma_f32_16x16x32_bf16 v[18:21], v[206:209], v[174:177], v[18:21]
	v_mfma_f32_16x16x32_bf16 v[14:17], v[198:201], v[182:185], v[14:17]
	v_mfma_f32_16x16x32_bf16 v[10:13], v[206:209], v[182:185], v[10:13]
	v_mfma_f32_16x16x32_bf16 v[6:9], v[198:201], v[190:193], v[6:9]
	v_mfma_f32_16x16x32_bf16 v[2:5], v[206:209], v[190:193], v[2:5]
	v_mfma_f32_16x16x32_bf16 v[30:33], v[202:205], v[170:173], v[30:33]
	v_mfma_f32_16x16x32_bf16 v[26:29], v[210:213], v[170:173], v[26:29]
	v_mfma_f32_16x16x32_bf16 v[22:25], v[202:205], v[178:181], v[22:25]
	v_mfma_f32_16x16x32_bf16 v[18:21], v[210:213], v[178:181], v[18:21]
	v_mfma_f32_16x16x32_bf16 v[14:17], v[202:205], v[186:189], v[14:17]
	v_mfma_f32_16x16x32_bf16 v[10:13], v[210:213], v[186:189], v[10:13]
	v_mfma_f32_16x16x32_bf16 v[6:9], v[202:205], v[194:197], v[6:9]
	v_mfma_f32_16x16x32_bf16 v[2:5], v[210:213], v[194:197], v[2:5]
	s_setprio 0
	s_barrier
	ds_read_b128 v[150:153], v220
	ds_read_b128 v[154:157], v220 offset:1024
	ds_read_b128 v[158:161], v220 offset:2048
	ds_read_b128 v[162:165], v220 offset:3072
	ds_read_b128 v[166:169], v141 offset:32768
	ds_read_b128 v[170:173], v141 offset:33792
	ds_read_b128 v[174:177], v141 offset:34816
	ds_read_b128 v[178:181], v141 offset:35840
	ds_read_b128 v[182:185], v141 offset:36864
	ds_read_b128 v[186:189], v141 offset:37888
	ds_read_b128 v[190:193], v141 offset:38912
	ds_read_b128 v[194:197], v141 offset:39936
	s_mov_b32 m0, s52
	s_add_u32 s98, s42, s68
	s_addc_u32 s99, s43, s69
	global_load_lds_dwordx4 v131, s[98:99]
	s_mov_b32 m0, s53
	s_add_u32 s98, s42, s70
	s_addc_u32 s99, s43, s71
	global_load_lds_dwordx4 v131, s[98:99]
	s_waitcnt lgkmcnt(8)
	s_waitcnt vmcnt(10)
	s_barrier
	s_waitcnt lgkmcnt(0)
	s_setprio 1
	s_waitcnt lgkmcnt(0)
	v_mfma_f32_16x16x32_bf16 v[126:129], v[150:153], v[166:169], v[126:129]
	v_mfma_f32_16x16x32_bf16 v[122:125], v[158:161], v[166:169], v[122:125]
	v_mfma_f32_16x16x32_bf16 v[118:121], v[150:153], v[174:177], v[118:121]
	v_mfma_f32_16x16x32_bf16 v[114:117], v[158:161], v[174:177], v[114:117]
	v_mfma_f32_16x16x32_bf16 v[110:113], v[150:153], v[182:185], v[110:113]
	v_mfma_f32_16x16x32_bf16 v[106:109], v[158:161], v[182:185], v[106:109]
	v_mfma_f32_16x16x32_bf16 v[102:105], v[150:153], v[190:193], v[102:105]
	v_mfma_f32_16x16x32_bf16 v[98:101], v[158:161], v[190:193], v[98:101]
	v_mfma_f32_16x16x32_bf16 v[126:129], v[154:157], v[170:173], v[126:129]
	v_mfma_f32_16x16x32_bf16 v[122:125], v[162:165], v[170:173], v[122:125]
	v_mfma_f32_16x16x32_bf16 v[118:121], v[154:157], v[178:181], v[118:121]
	v_mfma_f32_16x16x32_bf16 v[114:117], v[162:165], v[178:181], v[114:117]
	v_mfma_f32_16x16x32_bf16 v[110:113], v[154:157], v[186:189], v[110:113]
	v_mfma_f32_16x16x32_bf16 v[106:109], v[162:165], v[186:189], v[106:109]
	v_mfma_f32_16x16x32_bf16 v[102:105], v[154:157], v[194:197], v[102:105]
	v_mfma_f32_16x16x32_bf16 v[98:101], v[162:165], v[194:197], v[98:101]
	s_setprio 0
	s_barrier
	ds_read_b128 v[198:201], v221
	ds_read_b128 v[202:205], v221 offset:1024
	ds_read_b128 v[206:209], v221 offset:2048
	ds_read_b128 v[210:213], v221 offset:3072
	s_mov_b32 m0, s54
	s_add_u32 s98, s66, s94
	s_addc_u32 s99, s67, s95
	global_load_lds_dwordx4 v131, s[98:99]
	s_mov_b32 m0, s55
	s_add_u32 s98, s66, s72
	s_addc_u32 s99, s67, s73
	global_load_lds_dwordx4 v131, s[98:99]
	s_waitcnt vmcnt(10)
	s_barrier
	s_waitcnt lgkmcnt(0)
	s_setprio 1
	s_waitcnt lgkmcnt(0)
	v_mfma_f32_16x16x32_bf16 v[94:97], v[198:201], v[166:169], v[94:97]
	v_mfma_f32_16x16x32_bf16 v[90:93], v[206:209], v[166:169], v[90:93]
	v_mfma_f32_16x16x32_bf16 v[86:89], v[198:201], v[174:177], v[86:89]
	v_mfma_f32_16x16x32_bf16 v[82:85], v[206:209], v[174:177], v[82:85]
	v_mfma_f32_16x16x32_bf16 v[78:81], v[198:201], v[182:185], v[78:81]
	v_mfma_f32_16x16x32_bf16 v[74:77], v[206:209], v[182:185], v[74:77]
	v_mfma_f32_16x16x32_bf16 v[70:73], v[198:201], v[190:193], v[70:73]
	v_mfma_f32_16x16x32_bf16 v[66:69], v[206:209], v[190:193], v[66:69]
	v_mfma_f32_16x16x32_bf16 v[94:97], v[202:205], v[170:173], v[94:97]
	v_mfma_f32_16x16x32_bf16 v[90:93], v[210:213], v[170:173], v[90:93]
	v_mfma_f32_16x16x32_bf16 v[86:89], v[202:205], v[178:181], v[86:89]
	v_mfma_f32_16x16x32_bf16 v[82:85], v[210:213], v[178:181], v[82:85]
	v_mfma_f32_16x16x32_bf16 v[78:81], v[202:205], v[186:189], v[78:81]
	v_mfma_f32_16x16x32_bf16 v[74:77], v[210:213], v[186:189], v[74:77]
	v_mfma_f32_16x16x32_bf16 v[70:73], v[202:205], v[194:197], v[70:73]
	v_mfma_f32_16x16x32_bf16 v[66:69], v[210:213], v[194:197], v[66:69]
	s_setprio 0
	s_barrier
	ds_read_b128 v[166:169], v141 offset:49152
	ds_read_b128 v[170:173], v141 offset:50176
	ds_read_b128 v[174:177], v141 offset:51200
	ds_read_b128 v[178:181], v141 offset:52224
	ds_read_b128 v[182:185], v141 offset:53248
	ds_read_b128 v[186:189], v141 offset:54272
	ds_read_b128 v[190:193], v141 offset:55296
	ds_read_b128 v[194:197], v141 offset:56320
	s_mov_b32 m0, s56
	s_add_u32 s98, s42, s94
	s_addc_u32 s99, s43, s95
	global_load_lds_dwordx4 v131, s[98:99]
	s_mov_b32 m0, s57
	s_add_u32 s98, s42, s72
	s_addc_u32 s99, s43, s73
	global_load_lds_dwordx4 v131, s[98:99]
	s_barrier
; #define LDA(dst, b, h) for (int m = 0; m < 4; ++m) for (int k = 0; k < 2; ++k) \
;     dst[m][k] = *reinterpret_cast<const bf16x8*>((char*)SA(b, h) + a_thr + (m * 2 + k) * 1024)
; #define LDB(dst, b, h) for (int n = 0; n < 2; ++n) for (int k = 0; k < 2; ++k) \
;     dst[n][k] = *reinterpret_cast<const bf16x8*>((char*)SB(b, h) + b_thr + (n * 2 + k) * 1024)
; #define MMA(ai, bj, At, Btf) do { __builtin_amdgcn_s_setprio(1); \
;     for (int m = 0; m < 4; ++m) for (int n = 0; n < 2; ++n) for (int k = 0; k < 2; ++k) \
;       acc[ai][bj][m][n] = __builtin_amdgcn_mfma_f32_16x16x32_bf16(Btf[n][k], At[m][k], acc[ai][bj][m][n], 0, 0, 0); \
;     __builtin_amdgcn_s_setprio(0); } while (0)
; #define WAIT_V(n) asm volatile("s_waitcnt vmcnt(" #n ")" ::: "memory")
; #define WAIT_L(n) asm volatile("s_waitcnt lgkmcnt(" #n ")" ::: "memory")
; #define BAR __builtin_amdgcn_s_barrier()
; #define SCHED __builtin_amdgcn_sched_barrier(0)
; template <bool OVL, bool PANEL = false, class Epi>
; __device__ __forceinline__ void gemm_phase(const bf16_t* __restrict__ A, long lda, const bf16_t* __restrict__ Bt, long ldb, int nM, int nN, int K,
;                                            const Epi& epi, bf16_t* shm, int w0) {
;     ...
;       LDA(At, 1, 1); STAGE(SA(1, 0), A, lda, aoff, brow, t + 3);
;       BAR; WAIT_L(0); MMA(1, 0, At, B0); BAR; SCHED;
;       STAGE(SB(1, 1), Bt, ldb, boff, bcol + HALF, t + 3);
;       WAIT_V(6); BAR; MMA(1, 1, At, B1); BAR;
;     }
;     { LDB(B0, 0, 0); LDA(At, 0, 0); STAGE(SA(1, 1), A, lda, aoff, brow + HALF, nt - 1);
;       BAR; WAIT_L(0); MMA(0, 0, At, B0); BAR;
;       LDB(B1, 0, 1); BAR; WAIT_L(0); MMA(0, 1, At, B1); BAR;
	s_waitcnt lgkmcnt(0)
	s_setprio 1
	s_waitcnt lgkmcnt(0)
	v_mfma_f32_16x16x32_bf16 v[62:65], v[150:153], v[166:169], v[62:65]
	v_mfma_f32_16x16x32_bf16 v[58:61], v[158:161], v[166:169], v[58:61]
	v_mfma_f32_16x16x32_bf16 v[54:57], v[150:153], v[174:177], v[54:57]
	v_mfma_f32_16x16x32_bf16 v[50:53], v[158:161], v[174:177], v[50:53]
	v_mfma_f32_16x16x32_bf16 v[46:49], v[150:153], v[182:185], v[46:49]
	v_mfma_f32_16x16x32_bf16 v[42:45], v[158:161], v[182:185], v[42:45]
	v_mfma_f32_16x16x32_bf16 v[38:41], v[150:153], v[190:193], v[38:41]
	v_mfma_f32_16x16x32_bf16 v[34:37], v[158:161], v[190:193], v[34:37]
	v_mfma_f32_16x16x32_bf16 v[62:65], v[154:157], v[170:173], v[62:65]
	v_mfma_f32_16x16x32_bf16 v[58:61], v[162:165], v[170:173], v[58:61]
	v_mfma_f32_16x16x32_bf16 v[54:57], v[154:157], v[178:181], v[54:57]
	v_mfma_f32_16x16x32_bf16 v[50:53], v[162:165], v[178:181], v[50:53]
	v_mfma_f32_16x16x32_bf16 v[46:49], v[154:157], v[186:189], v[46:49]
	v_mfma_f32_16x16x32_bf16 v[42:45], v[162:165], v[186:189], v[42:45]
	v_mfma_f32_16x16x32_bf16 v[38:41], v[154:157], v[194:197], v[38:41]
	v_mfma_f32_16x16x32_bf16 v[34:37], v[162:165], v[194:197], v[34:37]
	s_setprio 0
	s_barrier
	s_mov_b32 m0, s58
	s_add_u32 s98, s66, s30
	s_addc_u32 s99, s67, s31
	global_load_lds_dwordx4 v131, s[98:99]
	s_mov_b32 m0, s59
	s_add_u32 s98, s66, s44
	s_addc_u32 s99, s67, s45
	global_load_lds_dwordx4 v131, s[98:99]
	s_waitcnt vmcnt(10)
	s_barrier
	s_setprio 1
	v_mfma_f32_16x16x32_bf16 v[30:33], v[198:201], v[166:169], v[30:33]
	v_mfma_f32_16x16x32_bf16 v[26:29], v[206:209], v[166:169], v[26:29]
	v_mfma_f32_16x16x32_bf16 v[22:25], v[198:201], v[174:177], v[22:25]
	v_mfma_f32_16x16x32_bf16 v[18:21], v[206:209], v[174:177], v[18:21]
	v_mfma_f32_16x16x32_bf16 v[14:17], v[198:201], v[182:185], v[14:17]
	v_mfma_f32_16x16x32_bf16 v[10:13], v[206:209], v[182:185], v[10:13]
	v_mfma_f32_16x16x32_bf16 v[6:9], v[198:201], v[190:193], v[6:9]
	v_mfma_f32_16x16x32_bf16 v[2:5], v[206:209], v[190:193], v[2:5]
	v_mfma_f32_16x16x32_bf16 v[30:33], v[202:205], v[170:173], v[30:33]
	v_mfma_f32_16x16x32_bf16 v[26:29], v[210:213], v[170:173], v[26:29]
	v_mfma_f32_16x16x32_bf16 v[22:25], v[202:205], v[178:181], v[22:25]
	v_mfma_f32_16x16x32_bf16 v[18:21], v[210:213], v[178:181], v[18:21]
	v_mfma_f32_16x16x32_bf16 v[14:17], v[202:205], v[186:189], v[14:17]
	v_mfma_f32_16x16x32_bf16 v[10:13], v[210:213], v[186:189], v[10:13]
	v_mfma_f32_16x16x32_bf16 v[6:9], v[202:205], v[194:197], v[6:9]
	v_mfma_f32_16x16x32_bf16 v[2:5], v[210:213], v[194:197], v[2:5]
	s_setprio 0
	s_add_i32 s18, s18, 2
	s_add_u32 vcc_lo, vcc_lo, 0x100
	s_addc_u32 vcc_hi, vcc_hi, 0
	s_cmp_lt_u32 s18, 12
	s_barrier
	s_cbranch_scc1 .LBB0_386
	s_waitcnt vmcnt(6)
	s_or_b32 s8, s2, 0x80
	s_mov_b32 s9, s3
	v_readlane_b32 s44, v252, 20
	s_lshl_b64 s[8:9], s[8:9], 11
	v_readlane_b32 s50, v252, 26
	v_add_u32_e32 v214, 16, v140
	v_readlane_b32 s51, v252, 27
	s_add_u32 s8, s50, s8
	v_add_u32_e32 v0, 0x10000, v214
	s_addc_u32 s9, s51, s9
	ds_read_b128 v[142:145], v0
	ds_read_b128 v[150:153], v0 offset:1024
	ds_read_b128 v[154:157], v0 offset:2048
	ds_read_b128 v[158:161], v0 offset:3072
	ds_read_b128 v[162:165], v141
	ds_read_b128 v[166:169], v141 offset:1024
	ds_read_b128 v[170:173], v141 offset:2048
	ds_read_b128 v[174:177], v141 offset:3072
	ds_read_b128 v[178:181], v141 offset:4096
	ds_read_b128 v[182:185], v141 offset:5120
	ds_read_b128 v[186:189], v141 offset:6144
	ds_read_b128 v[190:193], v141 offset:7168
	v_mov_b32_e32 v0, v131
	v_readlane_b32 s45, v252, 21
	v_lshl_add_u64 v[146:147], s[8:9], 0, v[0:1]
	s_mov_b64 s[8:9], 0x780
	v_lshl_add_u64 v[194:195], v[146:147], 0, s[8:9]
	v_readfirstlane_b32 s8, v148
	s_mov_b32 m0, s8
	s_mov_b64 s[8:9], 0x20780
	v_lshl_add_u64 v[146:147], v[146:147], 0, s[8:9]
	v_readfirstlane_b32 s8, v149
	global_load_lds_dwordx4 v[194:195], off
	s_mov_b32 m0, s8
	v_readlane_b32 s46, v252, 22
	global_load_lds_dwordx4 v[146:147], off
	s_barrier
	s_waitcnt lgkmcnt(0)
	v_readlane_b32 s47, v252, 23
	v_readlane_b32 s48, v252, 24
	v_readlane_b32 s49, v252, 25
	v_readlane_b32 s52, v252, 28
	v_readlane_b32 s53, v252, 29
	v_readlane_b32 s54, v252, 30
	v_readlane_b32 s55, v252, 31
	v_readlane_b32 s56, v252, 32
	v_readlane_b32 s57, v252, 33
	v_readlane_b32 s58, v252, 34
	v_readlane_b32 s59, v252, 35
	s_setprio 1
	s_waitcnt lgkmcnt(0)
	v_mfma_f32_16x16x32_bf16 v[126:129], v[142:145], v[162:165], v[126:129]
	v_mfma_f32_16x16x32_bf16 v[122:125], v[154:157], v[162:165], v[122:125]
	v_mfma_f32_16x16x32_bf16 v[118:121], v[142:145], v[170:173], v[118:121]
	v_mfma_f32_16x16x32_bf16 v[114:117], v[154:157], v[170:173], v[114:117]
	v_mfma_f32_16x16x32_bf16 v[110:113], v[142:145], v[178:181], v[110:113]
	v_mfma_f32_16x16x32_bf16 v[106:109], v[154:157], v[178:181], v[106:109]
	v_mfma_f32_16x16x32_bf16 v[98:101], v[154:157], v[186:189], v[98:101]
	v_mfma_f32_16x16x32_bf16 v[126:129], v[150:153], v[166:169], v[126:129]
	v_mfma_f32_16x16x32_bf16 v[122:125], v[158:161], v[166:169], v[122:125]
	v_mfma_f32_16x16x32_bf16 v[118:121], v[150:153], v[174:177], v[118:121]
	v_mfma_f32_16x16x32_bf16 v[114:117], v[158:161], v[174:177], v[114:117]
	v_mfma_f32_16x16x32_bf16 v[110:113], v[150:153], v[182:185], v[110:113]
	v_mfma_f32_16x16x32_bf16 v[106:109], v[158:161], v[182:185], v[106:109]
	v_mfma_f32_16x16x32_bf16 v[102:105], v[142:145], v[186:189], v[102:105]
	v_mfma_f32_16x16x32_bf16 v[98:101], v[158:161], v[190:193], v[98:101]
	v_mfma_f32_16x16x32_bf16 v[146:149], v[150:153], v[190:193], v[102:105]
	s_setprio 0
	v_add_u32_e32 v0, 0x14000, v214
	s_barrier
	s_nop 2
	ds_read_b128 v[102:105], v0
	ds_read_b128 v[194:197], v0 offset:1024
	ds_read_b128 v[198:201], v0 offset:2048
	ds_read_b128 v[202:205], v0 offset:3072
	s_barrier
; #define LDA(dst, b, h) for (int m = 0; m < 4; ++m) for (int k = 0; k < 2; ++k) \
;     dst[m][k] = *reinterpret_cast<const bf16x8*>((char*)SA(b, h) + a_thr + (m * 2 + k) * 1024)
; #define LDB(dst, b, h) for (int n = 0; n < 2; ++n) for (int k = 0; k < 2; ++k) \
;     dst[n][k] = *reinterpret_cast<const bf16x8*>((char*)SB(b, h) + b_thr + (n * 2 + k) * 1024)
; #define MMA(ai, bj, At, Btf) do { __builtin_amdgcn_s_setprio(1); \
;     for (int m = 0; m < 4; ++m) for (int n = 0; n < 2; ++n) for (int k = 0; k < 2; ++k) \
;       acc[ai][bj][m][n] = __builtin_amdgcn_mfma_f32_16x16x32_bf16(Btf[n][k], At[m][k], acc[ai][bj][m][n], 0, 0, 0); \
;     __builtin_amdgcn_s_setprio(0); } while (0)
; #define WAIT_V(n) asm volatile("s_waitcnt vmcnt(" #n ")" ::: "memory")
; #define WAIT_L(n) asm volatile("s_waitcnt lgkmcnt(" #n ")" ::: "memory")
; #define BAR __builtin_amdgcn_s_barrier()
; template <bool OVL, bool PANEL = false, class Epi>
; __device__ __forceinline__ void gemm_phase(const bf16_t* __restrict__ A, long lda, const bf16_t* __restrict__ Bt, long ldb, int nM, int nN, int K,
;                                            const Epi& epi, bf16_t* shm, int w0) {
;     ...
;       LDB(B1, 0, 1); BAR; WAIT_L(0); MMA(0, 1, At, B1); BAR;
;       LDA(At, 0, 1); WAIT_V(4); BAR; WAIT_L(0); MMA(1, 0, At, B0); MMA(1, 1, At, B1); BAR; }
;     { LDB(B0, 1, 0); LDA(At, 1, 0); WAIT_V(2); BAR; WAIT_L(0); MMA(0, 0, At, B0); BAR;
	s_waitcnt lgkmcnt(0)
	s_setprio 1
	s_waitcnt lgkmcnt(0)
	v_mfma_f32_16x16x32_bf16 v[94:97], v[102:105], v[162:165], v[94:97]
	v_mfma_f32_16x16x32_bf16 v[86:89], v[102:105], v[170:173], v[86:89]
	v_mfma_f32_16x16x32_bf16 v[78:81], v[102:105], v[178:181], v[78:81]
	v_mfma_f32_16x16x32_bf16 v[74:77], v[198:201], v[178:181], v[74:77]
	v_mfma_f32_16x16x32_bf16 v[94:97], v[194:197], v[166:169], v[94:97]
	v_mfma_f32_16x16x32_bf16 v[90:93], v[198:201], v[162:165], v[90:93]
	v_mfma_f32_16x16x32_bf16 v[86:89], v[194:197], v[174:177], v[86:89]
	v_mfma_f32_16x16x32_bf16 v[82:85], v[198:201], v[170:173], v[82:85]
	v_mfma_f32_16x16x32_bf16 v[78:81], v[194:197], v[182:185], v[78:81]
	v_mfma_f32_16x16x32_bf16 v[74:77], v[202:205], v[182:185], v[74:77]
	v_mfma_f32_16x16x32_bf16 v[70:73], v[102:105], v[186:189], v[70:73]
	v_mfma_f32_16x16x32_bf16 v[66:69], v[198:201], v[186:189], v[66:69]
	v_mfma_f32_16x16x32_bf16 v[162:165], v[202:205], v[166:169], v[90:93]
	v_mfma_f32_16x16x32_bf16 v[166:169], v[202:205], v[174:177], v[82:85]
	v_mfma_f32_16x16x32_bf16 v[170:173], v[194:197], v[190:193], v[70:73]
	v_mfma_f32_16x16x32_bf16 v[174:177], v[202:205], v[190:193], v[66:69]
	s_setprio 0
	s_barrier
	s_nop 1
	ds_read_b128 v[66:69], v141 offset:16384
	ds_read_b128 v[70:73], v141 offset:17408
	ds_read_b128 v[82:85], v141 offset:18432
	ds_read_b128 v[90:93], v141 offset:19456
	ds_read_b128 v[178:181], v141 offset:20480
	ds_read_b128 v[182:185], v141 offset:21504
	ds_read_b128 v[186:189], v141 offset:22528
	ds_read_b128 v[190:193], v141 offset:23552
	s_waitcnt vmcnt(4)
	s_barrier
	s_waitcnt lgkmcnt(0)
	s_setprio 1
	s_waitcnt lgkmcnt(0)
	v_mfma_f32_16x16x32_bf16 v[62:65], v[142:145], v[66:69], v[62:65]
	v_mfma_f32_16x16x32_bf16 v[54:57], v[142:145], v[82:85], v[54:57]
	v_mfma_f32_16x16x32_bf16 v[46:49], v[142:145], v[178:181], v[46:49]
	v_mfma_f32_16x16x32_bf16 v[42:45], v[154:157], v[178:181], v[42:45]
	v_mfma_f32_16x16x32_bf16 v[38:41], v[142:145], v[186:189], v[38:41]
	v_mfma_f32_16x16x32_bf16 v[34:37], v[154:157], v[186:189], v[34:37]
	v_mfma_f32_16x16x32_bf16 v[62:65], v[150:153], v[70:73], v[62:65]
	v_mfma_f32_16x16x32_bf16 v[58:61], v[154:157], v[66:69], v[58:61]
	v_mfma_f32_16x16x32_bf16 v[54:57], v[150:153], v[90:93], v[54:57]
	v_mfma_f32_16x16x32_bf16 v[50:53], v[154:157], v[82:85], v[50:53]
	v_mfma_f32_16x16x32_bf16 v[46:49], v[150:153], v[182:185], v[46:49]
	v_mfma_f32_16x16x32_bf16 v[42:45], v[158:161], v[182:185], v[42:45]
	v_mfma_f32_16x16x32_bf16 v[38:41], v[150:153], v[190:193], v[38:41]
	v_mfma_f32_16x16x32_bf16 v[34:37], v[158:161], v[190:193], v[34:37]
	v_mfma_f32_16x16x32_bf16 v[206:209], v[158:161], v[70:73], v[58:61]
	v_mfma_f32_16x16x32_bf16 v[210:213], v[158:161], v[90:93], v[50:53]
	s_setprio 0
	s_setprio 1
	v_mfma_f32_16x16x32_bf16 v[30:33], v[102:105], v[66:69], v[30:33]
	v_mfma_f32_16x16x32_bf16 v[26:29], v[198:201], v[66:69], v[26:29]
	v_mfma_f32_16x16x32_bf16 v[22:25], v[102:105], v[82:85], v[22:25]
	v_mfma_f32_16x16x32_bf16 v[18:21], v[198:201], v[82:85], v[18:21]
	v_mfma_f32_16x16x32_bf16 v[14:17], v[102:105], v[178:181], v[14:17]
	v_mfma_f32_16x16x32_bf16 v[10:13], v[198:201], v[178:181], v[10:13]
	v_mfma_f32_16x16x32_bf16 v[6:9], v[102:105], v[186:189], v[6:9]
	v_mfma_f32_16x16x32_bf16 v[2:5], v[198:201], v[186:189], v[2:5]
	v_mfma_f32_16x16x32_bf16 v[30:33], v[194:197], v[70:73], v[30:33]
	v_mfma_f32_16x16x32_bf16 v[26:29], v[202:205], v[70:73], v[26:29]
	v_mfma_f32_16x16x32_bf16 v[22:25], v[194:197], v[90:93], v[22:25]
	v_mfma_f32_16x16x32_bf16 v[18:21], v[202:205], v[90:93], v[18:21]
	v_mfma_f32_16x16x32_bf16 v[14:17], v[194:197], v[182:185], v[14:17]
	v_mfma_f32_16x16x32_bf16 v[10:13], v[202:205], v[182:185], v[10:13]
	v_mfma_f32_16x16x32_bf16 v[6:9], v[194:197], v[190:193], v[6:9]
	v_mfma_f32_16x16x32_bf16 v[2:5], v[202:205], v[190:193], v[2:5]
	s_setprio 0
	v_add_u32_e32 v0, 0x18000, v214
	s_barrier
	ds_read_b128 v[142:145], v0
	ds_read_b128 v[150:153], v0 offset:1024
	ds_read_b128 v[154:157], v0 offset:2048
	ds_read_b128 v[158:161], v0 offset:3072
	ds_read_b128 v[50:53], v141 offset:32768
	ds_read_b128 v[58:61], v141 offset:33792
	ds_read_b128 v[66:69], v141 offset:34816
	ds_read_b128 v[70:73], v141 offset:35840
	ds_read_b128 v[178:181], v141 offset:36864
	ds_read_b128 v[182:185], v141 offset:37888
	ds_read_b128 v[186:189], v141 offset:38912
	ds_read_b128 v[190:193], v141 offset:39936
	s_waitcnt vmcnt(2)
	s_barrier
; #define LDA(dst, b, h) for (int m = 0; m < 4; ++m) for (int k = 0; k < 2; ++k) \
;     dst[m][k] = *reinterpret_cast<const bf16x8*>((char*)SA(b, h) + a_thr + (m * 2 + k) * 1024)
; #define LDB(dst, b, h) for (int n = 0; n < 2; ++n) for (int k = 0; k < 2; ++k) \
;     dst[n][k] = *reinterpret_cast<const bf16x8*>((char*)SB(b, h) + b_thr + (n * 2 + k) * 1024)
; #define MMA(ai, bj, At, Btf) do { __builtin_amdgcn_s_setprio(1); \
;     for (int m = 0; m < 4; ++m) for (int n = 0; n < 2; ++n) for (int k = 0; k < 2; ++k) \
;       acc[ai][bj][m][n] = __builtin_amdgcn_mfma_f32_16x16x32_bf16(Btf[n][k], At[m][k], acc[ai][bj][m][n], 0, 0, 0); \
;     __builtin_amdgcn_s_setprio(0); } while (0)
; #define WAIT_V(n) asm volatile("s_waitcnt vmcnt(" #n ")" ::: "memory")
; #define WAIT_L(n) asm volatile("s_waitcnt lgkmcnt(" #n ")" ::: "memory")
; #define BAR __builtin_amdgcn_s_barrier()
; template <bool OVL, bool PANEL = false, class Epi>
; __device__ __forceinline__ void gemm_phase(const bf16_t* __restrict__ A, long lda, const bf16_t* __restrict__ Bt, long ldb, int nM, int nN, int K,
;                                            const Epi& epi, bf16_t* shm, int w0) {
;     ...
;     { LDB(B0, 1, 0); LDA(At, 1, 0); WAIT_V(2); BAR; WAIT_L(0); MMA(0, 0, At, B0); BAR;
;       LDB(B1, 1, 1); WAIT_V(0); BAR; WAIT_L(0); MMA(0, 1, At, B1); BAR;
;       LDA(At, 1, 1); BAR; WAIT_L(0); MMA(1, 0, At, B0); MMA(1, 1, At, B1); BAR; }
;     if (wr == 0) BAR;
	s_waitcnt lgkmcnt(0)
	s_setprio 1
	s_waitcnt lgkmcnt(0)
	v_mfma_f32_16x16x32_bf16 v[82:85], v[142:145], v[50:53], v[126:129]
	v_mfma_f32_16x16x32_bf16 v[126:129], v[150:153], v[58:61], v[82:85]
	v_mfma_f32_16x16x32_bf16 v[82:85], v[154:157], v[50:53], v[122:125]
	v_mfma_f32_16x16x32_bf16 v[122:125], v[158:161], v[58:61], v[82:85]
	v_mfma_f32_16x16x32_bf16 v[82:85], v[142:145], v[66:69], v[118:121]
	v_mfma_f32_16x16x32_bf16 v[118:121], v[150:153], v[70:73], v[82:85]
	v_mfma_f32_16x16x32_bf16 v[82:85], v[154:157], v[66:69], v[114:117]
	v_mfma_f32_16x16x32_bf16 v[114:117], v[158:161], v[70:73], v[82:85]
	v_mfma_f32_16x16x32_bf16 v[82:85], v[142:145], v[178:181], v[110:113]
	v_mfma_f32_16x16x32_bf16 v[110:113], v[150:153], v[182:185], v[82:85]
	v_mfma_f32_16x16x32_bf16 v[82:85], v[154:157], v[178:181], v[106:109]
	v_mfma_f32_16x16x32_bf16 v[102:105], v[158:161], v[182:185], v[82:85]
	v_mfma_f32_16x16x32_bf16 v[82:85], v[142:145], v[186:189], v[146:149]
	v_mfma_f32_16x16x32_bf16 v[90:93], v[150:153], v[190:193], v[82:85]
	v_mfma_f32_16x16x32_bf16 v[82:85], v[154:157], v[186:189], v[98:101]
	v_mfma_f32_16x16x32_bf16 v[82:85], v[158:161], v[190:193], v[82:85]
	s_setprio 0
	v_add_u32_e32 v0, 0x1c000, v214
	s_barrier
	ds_read_b128 v[146:149], v0
	ds_read_b128 v[194:197], v0 offset:1024
	ds_read_b128 v[198:201], v0 offset:2048
	ds_read_b128 v[202:205], v0 offset:3072
	s_waitcnt vmcnt(0)
	s_barrier
	s_waitcnt lgkmcnt(0)
	s_setprio 1
	s_waitcnt lgkmcnt(0)
	v_mfma_f32_16x16x32_bf16 v[94:97], v[146:149], v[50:53], v[94:97]
	v_mfma_f32_16x16x32_bf16 v[50:53], v[198:201], v[50:53], v[162:165]
	v_mfma_f32_16x16x32_bf16 v[98:101], v[202:205], v[58:61], v[50:53]
	v_mfma_f32_16x16x32_bf16 v[50:53], v[146:149], v[66:69], v[86:89]
	v_mfma_f32_16x16x32_bf16 v[106:109], v[194:197], v[58:61], v[94:97]
	v_mfma_f32_16x16x32_bf16 v[94:97], v[194:197], v[70:73], v[50:53]
	v_mfma_f32_16x16x32_bf16 v[50:53], v[198:201], v[66:69], v[166:169]
	v_mfma_f32_16x16x32_bf16 v[86:89], v[202:205], v[70:73], v[50:53]
	v_mfma_f32_16x16x32_bf16 v[50:53], v[146:149], v[178:181], v[78:81]
	v_mfma_f32_16x16x32_bf16 v[70:73], v[194:197], v[182:185], v[50:53]
	v_mfma_f32_16x16x32_bf16 v[50:53], v[198:201], v[178:181], v[74:77]
	v_mfma_f32_16x16x32_bf16 v[66:69], v[202:205], v[182:185], v[50:53]
	v_mfma_f32_16x16x32_bf16 v[50:53], v[146:149], v[186:189], v[170:173]
	v_mfma_f32_16x16x32_bf16 v[58:61], v[194:197], v[190:193], v[50:53]
	v_mfma_f32_16x16x32_bf16 v[50:53], v[198:201], v[186:189], v[174:177]
	v_mfma_f32_16x16x32_bf16 v[50:53], v[202:205], v[190:193], v[50:53]
	s_setprio 0
	s_barrier
	ds_read_b128 v[162:165], v141 offset:49152
	ds_read_b128 v[166:169], v141 offset:50176
	ds_read_b128 v[170:173], v141 offset:51200
	ds_read_b128 v[174:177], v141 offset:52224
	ds_read_b128 v[178:181], v141 offset:53248
	ds_read_b128 v[182:185], v141 offset:54272
	ds_read_b128 v[186:189], v141 offset:55296
	ds_read_b128 v[190:193], v141 offset:56320
	s_barrier
	s_waitcnt lgkmcnt(0)
	s_setprio 1
	s_waitcnt lgkmcnt(0)
	v_mfma_f32_16x16x32_bf16 v[62:65], v[142:145], v[162:165], v[62:65]
	v_mfma_f32_16x16x32_bf16 v[78:81], v[150:153], v[166:169], v[62:65]
	v_mfma_f32_16x16x32_bf16 v[62:65], v[154:157], v[162:165], v[206:209]
	v_mfma_f32_16x16x32_bf16 v[54:57], v[142:145], v[170:173], v[54:57]
	v_mfma_f32_16x16x32_bf16 v[74:77], v[158:161], v[166:169], v[62:65]
	v_mfma_f32_16x16x32_bf16 v[62:65], v[150:153], v[174:177], v[54:57]
	v_mfma_f32_16x16x32_bf16 v[54:57], v[154:157], v[170:173], v[210:213]
	v_mfma_f32_16x16x32_bf16 v[46:49], v[142:145], v[178:181], v[46:49]
	v_mfma_f32_16x16x32_bf16 v[42:45], v[154:157], v[178:181], v[42:45]
	v_mfma_f32_16x16x32_bf16 v[38:41], v[142:145], v[186:189], v[38:41]
	v_mfma_f32_16x16x32_bf16 v[34:37], v[154:157], v[186:189], v[34:37]
	v_mfma_f32_16x16x32_bf16 v[54:57], v[158:161], v[174:177], v[54:57]
	v_mfma_f32_16x16x32_bf16 v[46:49], v[150:153], v[182:185], v[46:49]
	v_mfma_f32_16x16x32_bf16 v[42:45], v[158:161], v[182:185], v[42:45]
	v_mfma_f32_16x16x32_bf16 v[38:41], v[150:153], v[190:193], v[38:41]
	v_mfma_f32_16x16x32_bf16 v[34:37], v[158:161], v[190:193], v[34:37]
	s_setprio 0
	s_setprio 1
	v_mfma_f32_16x16x32_bf16 v[30:33], v[146:149], v[162:165], v[30:33]
	v_mfma_f32_16x16x32_bf16 v[26:29], v[198:201], v[162:165], v[26:29]
	v_mfma_f32_16x16x32_bf16 v[22:25], v[146:149], v[170:173], v[22:25]
	v_mfma_f32_16x16x32_bf16 v[18:21], v[198:201], v[170:173], v[18:21]
	v_mfma_f32_16x16x32_bf16 v[14:17], v[146:149], v[178:181], v[14:17]
	v_mfma_f32_16x16x32_bf16 v[10:13], v[198:201], v[178:181], v[10:13]
	v_mfma_f32_16x16x32_bf16 v[6:9], v[146:149], v[186:189], v[6:9]
	v_mfma_f32_16x16x32_bf16 v[2:5], v[198:201], v[186:189], v[2:5]
	v_mfma_f32_16x16x32_bf16 v[30:33], v[194:197], v[166:169], v[30:33]
	v_mfma_f32_16x16x32_bf16 v[26:29], v[202:205], v[166:169], v[26:29]
	v_mfma_f32_16x16x32_bf16 v[22:25], v[194:197], v[174:177], v[22:25]
	v_mfma_f32_16x16x32_bf16 v[18:21], v[202:205], v[174:177], v[18:21]
	v_mfma_f32_16x16x32_bf16 v[14:17], v[194:197], v[182:185], v[14:17]
	v_mfma_f32_16x16x32_bf16 v[10:13], v[202:205], v[182:185], v[10:13]
	v_mfma_f32_16x16x32_bf16 v[6:9], v[194:197], v[190:193], v[6:9]
	v_mfma_f32_16x16x32_bf16 v[2:5], v[202:205], v[190:193], v[2:5]
	s_setprio 0
	s_barrier
	s_and_saveexec_b64 s[8:9], s[78:79]
	s_cbranch_execz .LBB0_389
	s_barrier

; #define LDA(dst, b, h) for (int m = 0; m < 4; ++m) for (int k = 0; k < 2; ++k) \
;     dst[m][k] = *reinterpret_cast<const bf16x8*>((char*)SA(b, h) + a_thr + (m * 2 + k) * 1024)
; #define LDB(dst, b, h) for (int n = 0; n < 2; ++n) for (int k = 0; k < 2; ++k) \
;     dst[n][k] = *reinterpret_cast<const bf16x8*>((char*)SB(b, h) + b_thr + (n * 2 + k) * 1024)
; #define MMA(ai, bj, At, Btf) do { __builtin_amdgcn_s_setprio(1); \
;     for (int m = 0; m < 4; ++m) for (int n = 0; n < 2; ++n) for (int k = 0; k < 2; ++k) \
;       acc[ai][bj][m][n] = __builtin_amdgcn_mfma_f32_16x16x32_bf16(Btf[n][k], At[m][k], acc[ai][bj][m][n], 0, 0, 0); \
;     __builtin_amdgcn_s_setprio(0); } while (0)
; #define WAIT_V(n) asm volatile("s_waitcnt vmcnt(" #n ")" ::: "memory")
; #define WAIT_L(n) asm volatile("s_waitcnt lgkmcnt(" #n ")" ::: "memory")
; #define BAR __builtin_amdgcn_s_barrier()
; #define SCHED __builtin_amdgcn_sched_barrier(0)
; template <bool OVL, bool PANEL = false, class Epi>
; __device__ __forceinline__ void gemm_phase(const bf16_t* __restrict__ A, long lda, const bf16_t* __restrict__ Bt, long ldb, int nM, int nN, int K,
;                                            const Epi& epi, bf16_t* shm, int w0) {
;     ...
;     for (int t = 0; t < nt - 2; t += 2) {
;       LDB(B0, 0, 0); SCHED; LDA(At, 0, 0); STAGE(SA(1, 1), A, lda, aoff, brow + HALF, t + 1);
;       WAIT_L(8); BAR; WAIT_L(0); MMA(0, 0, At, B0); BAR; SCHED;
;       LDB(B1, 0, 1); STAGE(SB(0, 0), Bt, ldb, boff, bcol, t + 2);
;       BAR; WAIT_L(0); MMA(0, 1, At, B1); BAR;
;       LDA(At, 0, 1); STAGE(SA(0, 0), A, lda, aoff, brow, t + 2);
;       BAR; WAIT_L(0); MMA(1, 0, At, B0); BAR; SCHED;
;       STAGE(SB(0, 1), Bt, ldb, boff, bcol + HALF, t + 2);
;       WAIT_V(6); BAR; MMA(1, 1, At, B1); BAR;
.LBB0_410:
	ds_read_b128 v[152:155], v220
	ds_read_b128 v[156:159], v220 offset:1024
	ds_read_b128 v[160:163], v220 offset:2048
	ds_read_b128 v[164:167], v220 offset:3072
	s_add_u32 s12, s8, s10
	s_addc_u32 s13, s9, s11
	ds_read_b128 v[168:171], v143
	ds_read_b128 v[172:175], v143 offset:1024
	ds_read_b128 v[176:179], v143 offset:2048
	ds_read_b128 v[180:183], v143 offset:3072
	ds_read_b128 v[184:187], v143 offset:4096
	ds_read_b128 v[188:191], v143 offset:5120
	ds_read_b128 v[192:195], v143 offset:6144
	ds_read_b128 v[196:199], v143 offset:7168
	s_mov_b32 m0, s16
	s_add_u32 s98, s12, s24
	s_addc_u32 s99, s13, s25
	global_load_lds_dwordx4 v131, s[98:99]
	s_mov_b32 m0, s23
	s_add_u32 s98, s12, s36
	s_addc_u32 s99, s13, s37
	global_load_lds_dwordx4 v131, s[98:99]
	s_waitcnt lgkmcnt(8)
	s_waitcnt vmcnt(10)
	s_barrier
	s_waitcnt lgkmcnt(0)
	s_setprio 1
	s_waitcnt lgkmcnt(0)
	v_mfma_f32_16x16x32_bf16 v[126:129], v[152:155], v[168:171], v[126:129]
	v_mfma_f32_16x16x32_bf16 v[122:125], v[160:163], v[168:171], v[122:125]
	v_mfma_f32_16x16x32_bf16 v[118:121], v[152:155], v[176:179], v[118:121]
	v_mfma_f32_16x16x32_bf16 v[114:117], v[160:163], v[176:179], v[114:117]
	v_mfma_f32_16x16x32_bf16 v[110:113], v[152:155], v[184:187], v[110:113]
	v_mfma_f32_16x16x32_bf16 v[106:109], v[160:163], v[184:187], v[106:109]
	v_mfma_f32_16x16x32_bf16 v[102:105], v[152:155], v[192:195], v[102:105]
	v_mfma_f32_16x16x32_bf16 v[98:101], v[160:163], v[192:195], v[98:101]
	v_mfma_f32_16x16x32_bf16 v[126:129], v[156:159], v[172:175], v[126:129]
	v_mfma_f32_16x16x32_bf16 v[122:125], v[164:167], v[172:175], v[122:125]
	v_mfma_f32_16x16x32_bf16 v[118:121], v[156:159], v[180:183], v[118:121]
	v_mfma_f32_16x16x32_bf16 v[114:117], v[164:167], v[180:183], v[114:117]
	v_mfma_f32_16x16x32_bf16 v[110:113], v[156:159], v[188:191], v[110:113]
	v_mfma_f32_16x16x32_bf16 v[106:109], v[164:167], v[188:191], v[106:109]
	v_mfma_f32_16x16x32_bf16 v[102:105], v[156:159], v[196:199], v[102:105]
	v_mfma_f32_16x16x32_bf16 v[98:101], v[164:167], v[196:199], v[98:101]
	s_setprio 0
	s_barrier
	s_add_u32 s14, s0, s10
	ds_read_b128 v[200:203], v221
	ds_read_b128 v[204:207], v221 offset:1024
	ds_read_b128 v[208:211], v221 offset:2048
	ds_read_b128 v[212:215], v221 offset:3072
	s_addc_u32 s15, s1, s11
	s_mov_b32 m0, s30
	s_add_u32 s98, s14, s34
	s_addc_u32 s99, s15, s35
	global_load_lds_dwordx4 v131, s[98:99]
	s_mov_b32 m0, s31
	s_add_u32 s98, s14, s64
	s_addc_u32 s99, s15, s65
	global_load_lds_dwordx4 v131, s[98:99]
	s_waitcnt vmcnt(10)
	s_barrier
	s_waitcnt lgkmcnt(0)
	s_setprio 1
	s_waitcnt lgkmcnt(0)
	v_mfma_f32_16x16x32_bf16 v[94:97], v[200:203], v[168:171], v[94:97]
	v_mfma_f32_16x16x32_bf16 v[90:93], v[208:211], v[168:171], v[90:93]
	v_mfma_f32_16x16x32_bf16 v[86:89], v[200:203], v[176:179], v[86:89]
	v_mfma_f32_16x16x32_bf16 v[82:85], v[208:211], v[176:179], v[82:85]
	v_mfma_f32_16x16x32_bf16 v[78:81], v[200:203], v[184:187], v[78:81]
	v_mfma_f32_16x16x32_bf16 v[74:77], v[208:211], v[184:187], v[74:77]
	v_mfma_f32_16x16x32_bf16 v[70:73], v[200:203], v[192:195], v[70:73]
	v_mfma_f32_16x16x32_bf16 v[66:69], v[208:211], v[192:195], v[66:69]
	v_mfma_f32_16x16x32_bf16 v[94:97], v[204:207], v[172:175], v[94:97]
	v_mfma_f32_16x16x32_bf16 v[90:93], v[212:215], v[172:175], v[90:93]
	v_mfma_f32_16x16x32_bf16 v[86:89], v[204:207], v[180:183], v[86:89]
	v_mfma_f32_16x16x32_bf16 v[82:85], v[212:215], v[180:183], v[82:85]
	v_mfma_f32_16x16x32_bf16 v[78:81], v[204:207], v[188:191], v[78:81]
	v_mfma_f32_16x16x32_bf16 v[74:77], v[212:215], v[188:191], v[74:77]
	v_mfma_f32_16x16x32_bf16 v[70:73], v[204:207], v[196:199], v[70:73]
	v_mfma_f32_16x16x32_bf16 v[66:69], v[212:215], v[196:199], v[66:69]
	s_setprio 0
	s_barrier
	ds_read_b128 v[168:171], v143 offset:16384
	ds_read_b128 v[172:175], v143 offset:17408
	ds_read_b128 v[176:179], v143 offset:18432
	ds_read_b128 v[180:183], v143 offset:19456
	ds_read_b128 v[184:187], v143 offset:20480
	ds_read_b128 v[188:191], v143 offset:21504
	ds_read_b128 v[192:195], v143 offset:22528
	ds_read_b128 v[196:199], v143 offset:23552
	s_mov_b32 m0, s32
	s_add_u32 s98, s12, s34
	s_addc_u32 s99, s13, s35
	global_load_lds_dwordx4 v131, s[98:99]
	s_mov_b32 m0, s40
	s_add_u32 s98, s12, s64
	s_addc_u32 s99, s13, s65
	global_load_lds_dwordx4 v131, s[98:99]
	s_barrier
	s_waitcnt lgkmcnt(0)
	s_setprio 1
	s_waitcnt lgkmcnt(0)
	v_mfma_f32_16x16x32_bf16 v[62:65], v[152:155], v[168:171], v[62:65]
	v_mfma_f32_16x16x32_bf16 v[58:61], v[160:163], v[168:171], v[58:61]
	v_mfma_f32_16x16x32_bf16 v[54:57], v[152:155], v[176:179], v[54:57]
	v_mfma_f32_16x16x32_bf16 v[50:53], v[160:163], v[176:179], v[50:53]
	v_mfma_f32_16x16x32_bf16 v[46:49], v[152:155], v[184:187], v[46:49]
	v_mfma_f32_16x16x32_bf16 v[42:45], v[160:163], v[184:187], v[42:45]
	v_mfma_f32_16x16x32_bf16 v[38:41], v[152:155], v[192:195], v[38:41]
	v_mfma_f32_16x16x32_bf16 v[34:37], v[160:163], v[192:195], v[34:37]
	v_mfma_f32_16x16x32_bf16 v[62:65], v[156:159], v[172:175], v[62:65]
	v_mfma_f32_16x16x32_bf16 v[58:61], v[164:167], v[172:175], v[58:61]
	v_mfma_f32_16x16x32_bf16 v[54:57], v[156:159], v[180:183], v[54:57]
	v_mfma_f32_16x16x32_bf16 v[50:53], v[164:167], v[180:183], v[50:53]
	v_mfma_f32_16x16x32_bf16 v[46:49], v[156:159], v[188:191], v[46:49]
	v_mfma_f32_16x16x32_bf16 v[42:45], v[164:167], v[188:191], v[42:45]
	v_mfma_f32_16x16x32_bf16 v[38:41], v[156:159], v[196:199], v[38:41]
	v_mfma_f32_16x16x32_bf16 v[34:37], v[164:167], v[196:199], v[34:37]
	s_setprio 0
	s_barrier
	s_mov_b32 m0, s41
	s_add_u32 s98, s14, s68
	s_addc_u32 s99, s15, s69
	global_load_lds_dwordx4 v131, s[98:99]
	s_mov_b32 m0, s42
	s_add_u32 s98, s14, s70
	s_addc_u32 s99, s15, s71
	global_load_lds_dwordx4 v131, s[98:99]
	s_waitcnt vmcnt(10)
	s_barrier
; #define LDA(dst, b, h) for (int m = 0; m < 4; ++m) for (int k = 0; k < 2; ++k) \
;     dst[m][k] = *reinterpret_cast<const bf16x8*>((char*)SA(b, h) + a_thr + (m * 2 + k) * 1024)
; #define LDB(dst, b, h) for (int n = 0; n < 2; ++n) for (int k = 0; k < 2; ++k) \
;     dst[n][k] = *reinterpret_cast<const bf16x8*>((char*)SB(b, h) + b_thr + (n * 2 + k) * 1024)
; #define MMA(ai, bj, At, Btf) do { __builtin_amdgcn_s_setprio(1); \
;     for (int m = 0; m < 4; ++m) for (int n = 0; n < 2; ++n) for (int k = 0; k < 2; ++k) \
;       acc[ai][bj][m][n] = __builtin_amdgcn_mfma_f32_16x16x32_bf16(Btf[n][k], At[m][k], acc[ai][bj][m][n], 0, 0, 0); \
;     __builtin_amdgcn_s_setprio(0); } while (0)
; #define WAIT_V(n) asm volatile("s_waitcnt vmcnt(" #n ")" ::: "memory")
; #define WAIT_L(n) asm volatile("s_waitcnt lgkmcnt(" #n ")" ::: "memory")
; #define BAR __builtin_amdgcn_s_barrier()
; #define SCHED __builtin_amdgcn_sched_barrier(0)
; template <bool OVL, bool PANEL = false, class Epi>
; __device__ __forceinline__ void gemm_phase(const bf16_t* __restrict__ A, long lda, const bf16_t* __restrict__ Bt, long ldb, int nM, int nN, int K,
;                                            const Epi& epi, bf16_t* shm, int w0) {
;     ...
;       WAIT_V(6); BAR; MMA(1, 1, At, B1); BAR;
;       LDB(B0, 1, 0); SCHED; LDA(At, 1, 0); STAGE(SA(0, 1), A, lda, aoff, brow + HALF, t + 2);
;       WAIT_L(8); BAR; WAIT_L(0); MMA(0, 0, At, B0); BAR; SCHED;
;       LDB(B1, 1, 1); STAGE(SB(1, 0), Bt, ldb, boff, bcol, t + 3);
;       BAR; WAIT_L(0); MMA(0, 1, At, B1); BAR;
;       LDA(At, 1, 1); STAGE(SA(1, 0), A, lda, aoff, brow, t + 3);
	s_setprio 1
	v_mfma_f32_16x16x32_bf16 v[30:33], v[200:203], v[168:171], v[30:33]
	v_mfma_f32_16x16x32_bf16 v[26:29], v[208:211], v[168:171], v[26:29]
	v_mfma_f32_16x16x32_bf16 v[22:25], v[200:203], v[176:179], v[22:25]
	v_mfma_f32_16x16x32_bf16 v[18:21], v[208:211], v[176:179], v[18:21]
	v_mfma_f32_16x16x32_bf16 v[14:17], v[200:203], v[184:187], v[14:17]
	v_mfma_f32_16x16x32_bf16 v[10:13], v[208:211], v[184:187], v[10:13]
	v_mfma_f32_16x16x32_bf16 v[6:9], v[200:203], v[192:195], v[6:9]
	v_mfma_f32_16x16x32_bf16 v[2:5], v[208:211], v[192:195], v[2:5]
	v_mfma_f32_16x16x32_bf16 v[30:33], v[204:207], v[172:175], v[30:33]
	v_mfma_f32_16x16x32_bf16 v[26:29], v[212:215], v[172:175], v[26:29]
	v_mfma_f32_16x16x32_bf16 v[22:25], v[204:207], v[180:183], v[22:25]
	v_mfma_f32_16x16x32_bf16 v[18:21], v[212:215], v[180:183], v[18:21]
	v_mfma_f32_16x16x32_bf16 v[14:17], v[204:207], v[188:191], v[14:17]
	v_mfma_f32_16x16x32_bf16 v[10:13], v[212:215], v[188:191], v[10:13]
	v_mfma_f32_16x16x32_bf16 v[6:9], v[204:207], v[196:199], v[6:9]
	v_mfma_f32_16x16x32_bf16 v[2:5], v[212:215], v[196:199], v[2:5]
	s_setprio 0
	s_barrier
	ds_read_b128 v[152:155], v222
	ds_read_b128 v[156:159], v222 offset:1024
	ds_read_b128 v[160:163], v222 offset:2048
	ds_read_b128 v[164:167], v222 offset:3072
	ds_read_b128 v[168:171], v143 offset:32768
	ds_read_b128 v[172:175], v143 offset:33792
	ds_read_b128 v[176:179], v143 offset:34816
	ds_read_b128 v[180:183], v143 offset:35840
	ds_read_b128 v[184:187], v143 offset:36864
	ds_read_b128 v[188:191], v143 offset:37888
	ds_read_b128 v[192:195], v143 offset:38912
	ds_read_b128 v[196:199], v143 offset:39936
	s_mov_b32 m0, s43
	s_add_u32 s98, s12, s68
	s_addc_u32 s99, s13, s69
	global_load_lds_dwordx4 v131, s[98:99]
	s_mov_b32 m0, s44
	s_add_u32 s98, s12, s70
	s_addc_u32 s99, s13, s71
	global_load_lds_dwordx4 v131, s[98:99]
	s_waitcnt lgkmcnt(8)
	s_waitcnt vmcnt(10)
	s_barrier
	s_waitcnt lgkmcnt(0)
	s_setprio 1
	s_waitcnt lgkmcnt(0)
	v_mfma_f32_16x16x32_bf16 v[126:129], v[152:155], v[168:171], v[126:129]
	v_mfma_f32_16x16x32_bf16 v[122:125], v[160:163], v[168:171], v[122:125]
	v_mfma_f32_16x16x32_bf16 v[118:121], v[152:155], v[176:179], v[118:121]
	v_mfma_f32_16x16x32_bf16 v[114:117], v[160:163], v[176:179], v[114:117]
	v_mfma_f32_16x16x32_bf16 v[110:113], v[152:155], v[184:187], v[110:113]
	v_mfma_f32_16x16x32_bf16 v[106:109], v[160:163], v[184:187], v[106:109]
	v_mfma_f32_16x16x32_bf16 v[102:105], v[152:155], v[192:195], v[102:105]
	v_mfma_f32_16x16x32_bf16 v[98:101], v[160:163], v[192:195], v[98:101]
	v_mfma_f32_16x16x32_bf16 v[126:129], v[156:159], v[172:175], v[126:129]
	v_mfma_f32_16x16x32_bf16 v[122:125], v[164:167], v[172:175], v[122:125]
	v_mfma_f32_16x16x32_bf16 v[118:121], v[156:159], v[180:183], v[118:121]
	v_mfma_f32_16x16x32_bf16 v[114:117], v[164:167], v[180:183], v[114:117]
	v_mfma_f32_16x16x32_bf16 v[110:113], v[156:159], v[188:191], v[110:113]
	v_mfma_f32_16x16x32_bf16 v[106:109], v[164:167], v[188:191], v[106:109]
	v_mfma_f32_16x16x32_bf16 v[102:105], v[156:159], v[196:199], v[102:105]
	v_mfma_f32_16x16x32_bf16 v[98:101], v[164:167], v[196:199], v[98:101]
	s_setprio 0
	s_barrier
	ds_read_b128 v[200:203], v223
	ds_read_b128 v[204:207], v223 offset:1024
	ds_read_b128 v[208:211], v223 offset:2048
	ds_read_b128 v[212:215], v223 offset:3072
	s_mov_b32 m0, s45
	s_add_u32 s98, s14, s94
	s_addc_u32 s99, s15, s95
	global_load_lds_dwordx4 v131, s[98:99]
	s_mov_b32 m0, s46
	s_add_u32 s98, s14, s72
	s_addc_u32 s99, s15, s73
	global_load_lds_dwordx4 v131, s[98:99]
	s_waitcnt vmcnt(10)
	s_barrier
	s_waitcnt lgkmcnt(0)
	s_setprio 1
	s_waitcnt lgkmcnt(0)
	v_mfma_f32_16x16x32_bf16 v[94:97], v[200:203], v[168:171], v[94:97]
	v_mfma_f32_16x16x32_bf16 v[90:93], v[208:211], v[168:171], v[90:93]
	v_mfma_f32_16x16x32_bf16 v[86:89], v[200:203], v[176:179], v[86:89]
	v_mfma_f32_16x16x32_bf16 v[82:85], v[208:211], v[176:179], v[82:85]
	v_mfma_f32_16x16x32_bf16 v[78:81], v[200:203], v[184:187], v[78:81]
	v_mfma_f32_16x16x32_bf16 v[74:77], v[208:211], v[184:187], v[74:77]
	v_mfma_f32_16x16x32_bf16 v[70:73], v[200:203], v[192:195], v[70:73]
	v_mfma_f32_16x16x32_bf16 v[66:69], v[208:211], v[192:195], v[66:69]
	v_mfma_f32_16x16x32_bf16 v[94:97], v[204:207], v[172:175], v[94:97]
	v_mfma_f32_16x16x32_bf16 v[90:93], v[212:215], v[172:175], v[90:93]
	v_mfma_f32_16x16x32_bf16 v[86:89], v[204:207], v[180:183], v[86:89]
	v_mfma_f32_16x16x32_bf16 v[82:85], v[212:215], v[180:183], v[82:85]
	v_mfma_f32_16x16x32_bf16 v[78:81], v[204:207], v[188:191], v[78:81]
	v_mfma_f32_16x16x32_bf16 v[74:77], v[212:215], v[188:191], v[74:77]
	v_mfma_f32_16x16x32_bf16 v[70:73], v[204:207], v[196:199], v[70:73]
	v_mfma_f32_16x16x32_bf16 v[66:69], v[212:215], v[196:199], v[66:69]
	s_setprio 0
	s_barrier
	ds_read_b128 v[168:171], v143 offset:49152
	ds_read_b128 v[172:175], v143 offset:50176
	ds_read_b128 v[176:179], v143 offset:51200
	ds_read_b128 v[180:183], v143 offset:52224
	ds_read_b128 v[184:187], v143 offset:53248
	ds_read_b128 v[188:191], v143 offset:54272
	ds_read_b128 v[192:195], v143 offset:55296
	ds_read_b128 v[196:199], v143 offset:56320
	s_mov_b32 m0, s47
	s_add_u32 s98, s12, s94
	s_addc_u32 s99, s13, s95
	global_load_lds_dwordx4 v131, s[98:99]
	s_mov_b32 m0, s48
	s_add_u32 s98, s12, s72
	s_addc_u32 s99, s13, s73
	global_load_lds_dwordx4 v131, s[98:99]
	s_barrier
; #define LDA(dst, b, h) for (int m = 0; m < 4; ++m) for (int k = 0; k < 2; ++k) \
;     dst[m][k] = *reinterpret_cast<const bf16x8*>((char*)SA(b, h) + a_thr + (m * 2 + k) * 1024)
; #define LDB(dst, b, h) for (int n = 0; n < 2; ++n) for (int k = 0; k < 2; ++k) \
;     dst[n][k] = *reinterpret_cast<const bf16x8*>((char*)SB(b, h) + b_thr + (n * 2 + k) * 1024)
; #define MMA(ai, bj, At, Btf) do { __builtin_amdgcn_s_setprio(1); \
;     for (int m = 0; m < 4; ++m) for (int n = 0; n < 2; ++n) for (int k = 0; k < 2; ++k) \
;       acc[ai][bj][m][n] = __builtin_amdgcn_mfma_f32_16x16x32_bf16(Btf[n][k], At[m][k], acc[ai][bj][m][n], 0, 0, 0); \
;     __builtin_amdgcn_s_setprio(0); } while (0)
; #define WAIT_V(n) asm volatile("s_waitcnt vmcnt(" #n ")" ::: "memory")
; #define WAIT_L(n) asm volatile("s_waitcnt lgkmcnt(" #n ")" ::: "memory")
; #define BAR __builtin_amdgcn_s_barrier()
; #define SCHED __builtin_amdgcn_sched_barrier(0)
; template <bool OVL, bool PANEL = false, class Epi>
; __device__ __forceinline__ void gemm_phase(const bf16_t* __restrict__ A, long lda, const bf16_t* __restrict__ Bt, long ldb, int nM, int nN, int K,
;                                            const Epi& epi, bf16_t* shm, int w0) {
;     ...
;       LDA(At, 1, 1); STAGE(SA(1, 0), A, lda, aoff, brow, t + 3);
;       BAR; WAIT_L(0); MMA(1, 0, At, B0); BAR; SCHED;
;       STAGE(SB(1, 1), Bt, ldb, boff, bcol + HALF, t + 3);
;       WAIT_V(6); BAR; MMA(1, 1, At, B1); BAR;
;     }
;     { LDB(B0, 0, 0); LDA(At, 0, 0); STAGE(SA(1, 1), A, lda, aoff, brow + HALF, nt - 1);
;       BAR; WAIT_L(0); MMA(0, 0, At, B0); BAR;
;       LDB(B1, 0, 1); BAR; WAIT_L(0); MMA(0, 1, At, B1); BAR;
	s_waitcnt lgkmcnt(0)
	s_setprio 1
	s_waitcnt lgkmcnt(0)
	v_mfma_f32_16x16x32_bf16 v[62:65], v[152:155], v[168:171], v[62:65]
	v_mfma_f32_16x16x32_bf16 v[58:61], v[160:163], v[168:171], v[58:61]
	v_mfma_f32_16x16x32_bf16 v[54:57], v[152:155], v[176:179], v[54:57]
	v_mfma_f32_16x16x32_bf16 v[50:53], v[160:163], v[176:179], v[50:53]
	v_mfma_f32_16x16x32_bf16 v[46:49], v[152:155], v[184:187], v[46:49]
	v_mfma_f32_16x16x32_bf16 v[42:45], v[160:163], v[184:187], v[42:45]
	v_mfma_f32_16x16x32_bf16 v[38:41], v[152:155], v[192:195], v[38:41]
	v_mfma_f32_16x16x32_bf16 v[34:37], v[160:163], v[192:195], v[34:37]
	v_mfma_f32_16x16x32_bf16 v[62:65], v[156:159], v[172:175], v[62:65]
	v_mfma_f32_16x16x32_bf16 v[58:61], v[164:167], v[172:175], v[58:61]
	v_mfma_f32_16x16x32_bf16 v[54:57], v[156:159], v[180:183], v[54:57]
	v_mfma_f32_16x16x32_bf16 v[50:53], v[164:167], v[180:183], v[50:53]
	v_mfma_f32_16x16x32_bf16 v[46:49], v[156:159], v[188:191], v[46:49]
	v_mfma_f32_16x16x32_bf16 v[42:45], v[164:167], v[188:191], v[42:45]
	v_mfma_f32_16x16x32_bf16 v[38:41], v[156:159], v[196:199], v[38:41]
	v_mfma_f32_16x16x32_bf16 v[34:37], v[164:167], v[196:199], v[34:37]
	s_setprio 0
	s_barrier
	s_mov_b32 m0, s49
	s_add_u32 s98, s14, s26
	s_addc_u32 s99, s15, s27
	global_load_lds_dwordx4 v131, s[98:99]
	s_mov_b32 m0, s50
	s_add_u32 s98, s14, s28
	s_addc_u32 s99, s15, s29
	global_load_lds_dwordx4 v131, s[98:99]
	s_waitcnt vmcnt(10)
	s_barrier
	s_setprio 1
	v_mfma_f32_16x16x32_bf16 v[30:33], v[200:203], v[168:171], v[30:33]
	v_mfma_f32_16x16x32_bf16 v[26:29], v[208:211], v[168:171], v[26:29]
	v_mfma_f32_16x16x32_bf16 v[22:25], v[200:203], v[176:179], v[22:25]
	v_mfma_f32_16x16x32_bf16 v[18:21], v[208:211], v[176:179], v[18:21]
	v_mfma_f32_16x16x32_bf16 v[14:17], v[200:203], v[184:187], v[14:17]
	v_mfma_f32_16x16x32_bf16 v[10:13], v[208:211], v[184:187], v[10:13]
	v_mfma_f32_16x16x32_bf16 v[6:9], v[200:203], v[192:195], v[6:9]
	v_mfma_f32_16x16x32_bf16 v[2:5], v[208:211], v[192:195], v[2:5]
	v_mfma_f32_16x16x32_bf16 v[30:33], v[204:207], v[172:175], v[30:33]
	v_mfma_f32_16x16x32_bf16 v[26:29], v[212:215], v[172:175], v[26:29]
	v_mfma_f32_16x16x32_bf16 v[22:25], v[204:207], v[180:183], v[22:25]
	v_mfma_f32_16x16x32_bf16 v[18:21], v[212:215], v[180:183], v[18:21]
	v_mfma_f32_16x16x32_bf16 v[14:17], v[204:207], v[188:191], v[14:17]
	v_mfma_f32_16x16x32_bf16 v[10:13], v[212:215], v[188:191], v[10:13]
	v_mfma_f32_16x16x32_bf16 v[6:9], v[204:207], v[196:199], v[6:9]
	v_mfma_f32_16x16x32_bf16 v[2:5], v[212:215], v[196:199], v[2:5]
	s_setprio 0
	s_add_i32 s21, s21, 2
	s_add_u32 s10, s10, 0x100
	s_addc_u32 s11, s11, 0
	s_cmp_lt_u32 s21, 12
	s_barrier
	s_cbranch_scc1 .LBB0_410
	s_waitcnt vmcnt(6)
	v_add_u32_e32 v212, 16, v140
	v_add_u32_e32 v0, 0x10000, v212
	ds_read_b128 v[144:147], v0
	ds_read_b128 v[152:155], v0 offset:1024
	ds_read_b128 v[156:159], v0 offset:2048
	ds_read_b128 v[160:163], v0 offset:3072
	ds_read_b128 v[164:167], v143
	ds_read_b128 v[168:171], v143 offset:1024
	ds_read_b128 v[172:175], v143 offset:2048
	ds_read_b128 v[176:179], v143 offset:3072
	ds_read_b128 v[180:183], v143 offset:4096
	ds_read_b128 v[184:187], v143 offset:5120
	ds_read_b128 v[188:191], v143 offset:6144
	ds_read_b128 v[192:195], v143 offset:7168
	v_mov_b32_e32 v0, v131
	s_mov_b64 s[0:1], 0x40780
	v_lshl_add_u64 v[148:149], s[8:9], 0, v[0:1]
	v_lshl_add_u64 v[196:197], v[148:149], 0, s[0:1]
	v_readfirstlane_b32 s0, v150
	s_mov_b32 m0, s0
	s_mov_b64 s[0:1], 0x60780
	v_lshl_add_u64 v[148:149], v[148:149], 0, s[0:1]
	v_readfirstlane_b32 s0, v151
	global_load_lds_dwordx4 v[196:197], off
	s_mov_b32 m0, s0
	s_nop 0
	global_load_lds_dwordx4 v[148:149], off
	s_barrier
	s_waitcnt lgkmcnt(0)
	s_setprio 1
	s_waitcnt lgkmcnt(0)
	v_mfma_f32_16x16x32_bf16 v[126:129], v[144:147], v[164:167], v[126:129]
	v_mfma_f32_16x16x32_bf16 v[122:125], v[156:159], v[164:167], v[122:125]
	v_mfma_f32_16x16x32_bf16 v[118:121], v[144:147], v[172:175], v[118:121]
	v_mfma_f32_16x16x32_bf16 v[114:117], v[156:159], v[172:175], v[114:117]
	v_mfma_f32_16x16x32_bf16 v[110:113], v[144:147], v[180:183], v[110:113]
	v_mfma_f32_16x16x32_bf16 v[106:109], v[156:159], v[180:183], v[106:109]
	v_mfma_f32_16x16x32_bf16 v[102:105], v[144:147], v[188:191], v[102:105]
	v_mfma_f32_16x16x32_bf16 v[126:129], v[152:155], v[168:171], v[126:129]
	v_mfma_f32_16x16x32_bf16 v[122:125], v[160:163], v[168:171], v[122:125]
	v_mfma_f32_16x16x32_bf16 v[118:121], v[152:155], v[176:179], v[118:121]
	v_mfma_f32_16x16x32_bf16 v[114:117], v[160:163], v[176:179], v[114:117]
	v_mfma_f32_16x16x32_bf16 v[110:113], v[152:155], v[184:187], v[110:113]
	v_mfma_f32_16x16x32_bf16 v[106:109], v[160:163], v[184:187], v[106:109]
	v_mfma_f32_16x16x32_bf16 v[102:105], v[152:155], v[192:195], v[102:105]
	v_mfma_f32_16x16x32_bf16 v[98:101], v[156:159], v[188:191], v[98:101]
	v_mfma_f32_16x16x32_bf16 v[148:151], v[160:163], v[192:195], v[98:101]
	s_setprio 0
	v_add_u32_e32 v0, 0x14000, v212
	s_barrier
	s_nop 3
	ds_read_b128 v[98:101], v0
	ds_read_b128 v[196:199], v0 offset:1024
	ds_read_b128 v[200:203], v0 offset:2048
	ds_read_b128 v[204:207], v0 offset:3072
	s_barrier
; #define LDA(dst, b, h) for (int m = 0; m < 4; ++m) for (int k = 0; k < 2; ++k) \
;     dst[m][k] = *reinterpret_cast<const bf16x8*>((char*)SA(b, h) + a_thr + (m * 2 + k) * 1024)
; #define LDB(dst, b, h) for (int n = 0; n < 2; ++n) for (int k = 0; k < 2; ++k) \
;     dst[n][k] = *reinterpret_cast<const bf16x8*>((char*)SB(b, h) + b_thr + (n * 2 + k) * 1024)
; #define MMA(ai, bj, At, Btf) do { __builtin_amdgcn_s_setprio(1); \
;     for (int m = 0; m < 4; ++m) for (int n = 0; n < 2; ++n) for (int k = 0; k < 2; ++k) \
;       acc[ai][bj][m][n] = __builtin_amdgcn_mfma_f32_16x16x32_bf16(Btf[n][k], At[m][k], acc[ai][bj][m][n], 0, 0, 0); \
;     __builtin_amdgcn_s_setprio(0); } while (0)
; #define WAIT_V(n) asm volatile("s_waitcnt vmcnt(" #n ")" ::: "memory")
; #define WAIT_L(n) asm volatile("s_waitcnt lgkmcnt(" #n ")" ::: "memory")
; #define BAR __builtin_amdgcn_s_barrier()
; template <bool OVL, bool PANEL = false, class Epi>
; __device__ __forceinline__ void gemm_phase(const bf16_t* __restrict__ A, long lda, const bf16_t* __restrict__ Bt, long ldb, int nM, int nN, int K,
;                                            const Epi& epi, bf16_t* shm, int w0) {
;     ...
;       LDB(B1, 0, 1); BAR; WAIT_L(0); MMA(0, 1, At, B1); BAR;
;       LDA(At, 0, 1); WAIT_V(4); BAR; WAIT_L(0); MMA(1, 0, At, B0); MMA(1, 1, At, B1); BAR; }
;     { LDB(B0, 1, 0); LDA(At, 1, 0); WAIT_V(2); BAR; WAIT_L(0); MMA(0, 0, At, B0); BAR;
	s_waitcnt lgkmcnt(0)
	s_setprio 1
	s_waitcnt lgkmcnt(0)
	v_mfma_f32_16x16x32_bf16 v[94:97], v[98:101], v[164:167], v[94:97]
	v_mfma_f32_16x16x32_bf16 v[86:89], v[98:101], v[172:175], v[86:89]
	v_mfma_f32_16x16x32_bf16 v[82:85], v[200:203], v[172:175], v[82:85]
	v_mfma_f32_16x16x32_bf16 v[78:81], v[98:101], v[180:183], v[78:81]
	v_mfma_f32_16x16x32_bf16 v[74:77], v[200:203], v[180:183], v[74:77]
	v_mfma_f32_16x16x32_bf16 v[94:97], v[196:199], v[168:171], v[94:97]
	v_mfma_f32_16x16x32_bf16 v[90:93], v[200:203], v[164:167], v[90:93]
	v_mfma_f32_16x16x32_bf16 v[86:89], v[196:199], v[176:179], v[86:89]
	v_mfma_f32_16x16x32_bf16 v[82:85], v[204:207], v[176:179], v[82:85]
	v_mfma_f32_16x16x32_bf16 v[78:81], v[196:199], v[184:187], v[78:81]
	v_mfma_f32_16x16x32_bf16 v[74:77], v[204:207], v[184:187], v[74:77]
	v_mfma_f32_16x16x32_bf16 v[70:73], v[98:101], v[188:191], v[70:73]
	v_mfma_f32_16x16x32_bf16 v[66:69], v[200:203], v[188:191], v[66:69]
	v_mfma_f32_16x16x32_bf16 v[164:167], v[204:207], v[168:171], v[90:93]
	v_mfma_f32_16x16x32_bf16 v[168:171], v[196:199], v[192:195], v[70:73]
	v_mfma_f32_16x16x32_bf16 v[172:175], v[204:207], v[192:195], v[66:69]
	s_setprio 0
	s_barrier
	s_nop 2
	ds_read_b128 v[66:69], v143 offset:16384
	ds_read_b128 v[70:73], v143 offset:17408
	ds_read_b128 v[90:93], v143 offset:18432
	ds_read_b128 v[176:179], v143 offset:19456
	ds_read_b128 v[180:183], v143 offset:20480
	ds_read_b128 v[184:187], v143 offset:21504
	ds_read_b128 v[188:191], v143 offset:22528
	ds_read_b128 v[192:195], v143 offset:23552
	s_waitcnt vmcnt(4)
	s_barrier
	s_waitcnt lgkmcnt(0)
	s_setprio 1
	s_waitcnt lgkmcnt(0)
	v_mfma_f32_16x16x32_bf16 v[62:65], v[144:147], v[66:69], v[62:65]
	v_mfma_f32_16x16x32_bf16 v[54:57], v[144:147], v[90:93], v[54:57]
	v_mfma_f32_16x16x32_bf16 v[50:53], v[156:159], v[90:93], v[50:53]
	v_mfma_f32_16x16x32_bf16 v[46:49], v[144:147], v[180:183], v[46:49]
	v_mfma_f32_16x16x32_bf16 v[42:45], v[156:159], v[180:183], v[42:45]
	v_mfma_f32_16x16x32_bf16 v[38:41], v[144:147], v[188:191], v[38:41]
	v_mfma_f32_16x16x32_bf16 v[34:37], v[156:159], v[188:191], v[34:37]
	v_mfma_f32_16x16x32_bf16 v[62:65], v[152:155], v[70:73], v[62:65]
	v_mfma_f32_16x16x32_bf16 v[58:61], v[156:159], v[66:69], v[58:61]
	v_mfma_f32_16x16x32_bf16 v[54:57], v[152:155], v[176:179], v[54:57]
	v_mfma_f32_16x16x32_bf16 v[50:53], v[160:163], v[176:179], v[50:53]
	v_mfma_f32_16x16x32_bf16 v[46:49], v[152:155], v[184:187], v[46:49]
	v_mfma_f32_16x16x32_bf16 v[42:45], v[160:163], v[184:187], v[42:45]
	v_mfma_f32_16x16x32_bf16 v[38:41], v[152:155], v[192:195], v[38:41]
	v_mfma_f32_16x16x32_bf16 v[34:37], v[160:163], v[192:195], v[34:37]
	v_mfma_f32_16x16x32_bf16 v[208:211], v[160:163], v[70:73], v[58:61]
	s_setprio 0
	s_setprio 1
	v_mfma_f32_16x16x32_bf16 v[30:33], v[98:101], v[66:69], v[30:33]
	v_mfma_f32_16x16x32_bf16 v[26:29], v[200:203], v[66:69], v[26:29]
	v_mfma_f32_16x16x32_bf16 v[22:25], v[98:101], v[90:93], v[22:25]
	v_mfma_f32_16x16x32_bf16 v[18:21], v[200:203], v[90:93], v[18:21]
	v_mfma_f32_16x16x32_bf16 v[14:17], v[98:101], v[180:183], v[14:17]
	v_mfma_f32_16x16x32_bf16 v[10:13], v[200:203], v[180:183], v[10:13]
	v_mfma_f32_16x16x32_bf16 v[6:9], v[98:101], v[188:191], v[6:9]
	v_mfma_f32_16x16x32_bf16 v[2:5], v[200:203], v[188:191], v[2:5]
	v_mfma_f32_16x16x32_bf16 v[30:33], v[196:199], v[70:73], v[30:33]
	v_mfma_f32_16x16x32_bf16 v[26:29], v[204:207], v[70:73], v[26:29]
	v_mfma_f32_16x16x32_bf16 v[22:25], v[196:199], v[176:179], v[22:25]
	v_mfma_f32_16x16x32_bf16 v[18:21], v[204:207], v[176:179], v[18:21]
	v_mfma_f32_16x16x32_bf16 v[14:17], v[196:199], v[184:187], v[14:17]
	v_mfma_f32_16x16x32_bf16 v[10:13], v[204:207], v[184:187], v[10:13]
	v_mfma_f32_16x16x32_bf16 v[6:9], v[196:199], v[192:195], v[6:9]
	v_mfma_f32_16x16x32_bf16 v[2:5], v[204:207], v[192:195], v[2:5]
	s_setprio 0
	v_add_u32_e32 v0, 0x18000, v212
	s_barrier
	ds_read_b128 v[144:147], v0
	ds_read_b128 v[152:155], v0 offset:1024
	ds_read_b128 v[156:159], v0 offset:2048
	ds_read_b128 v[160:163], v0 offset:3072
	ds_read_b128 v[58:61], v143 offset:32768
	ds_read_b128 v[66:69], v143 offset:33792
	ds_read_b128 v[70:73], v143 offset:34816
	ds_read_b128 v[176:179], v143 offset:35840
	ds_read_b128 v[180:183], v143 offset:36864
	ds_read_b128 v[184:187], v143 offset:37888
	ds_read_b128 v[188:191], v143 offset:38912
	ds_read_b128 v[192:195], v143 offset:39936
	s_waitcnt vmcnt(2)
	s_barrier
; #define LDA(dst, b, h) for (int m = 0; m < 4; ++m) for (int k = 0; k < 2; ++k) \
;     dst[m][k] = *reinterpret_cast<const bf16x8*>((char*)SA(b, h) + a_thr + (m * 2 + k) * 1024)
; #define LDB(dst, b, h) for (int n = 0; n < 2; ++n) for (int k = 0; k < 2; ++k) \
;     dst[n][k] = *reinterpret_cast<const bf16x8*>((char*)SB(b, h) + b_thr + (n * 2 + k) * 1024)
; #define MMA(ai, bj, At, Btf) do { __builtin_amdgcn_s_setprio(1); \
;     for (int m = 0; m < 4; ++m) for (int n = 0; n < 2; ++n) for (int k = 0; k < 2; ++k) \
;       acc[ai][bj][m][n] = __builtin_amdgcn_mfma_f32_16x16x32_bf16(Btf[n][k], At[m][k], acc[ai][bj][m][n], 0, 0, 0); \
;     __builtin_amdgcn_s_setprio(0); } while (0)
; #define WAIT_V(n) asm volatile("s_waitcnt vmcnt(" #n ")" ::: "memory")
; #define WAIT_L(n) asm volatile("s_waitcnt lgkmcnt(" #n ")" ::: "memory")
; #define BAR __builtin_amdgcn_s_barrier()
; template <bool OVL, bool PANEL = false, class Epi>
; __device__ __forceinline__ void gemm_phase(const bf16_t* __restrict__ A, long lda, const bf16_t* __restrict__ Bt, long ldb, int nM, int nN, int K,
;                                            const Epi& epi, bf16_t* shm, int w0) {
;     ...
;     { LDB(B0, 1, 0); LDA(At, 1, 0); WAIT_V(2); BAR; WAIT_L(0); MMA(0, 0, At, B0); BAR;
;       LDB(B1, 1, 1); WAIT_V(0); BAR; WAIT_L(0); MMA(0, 1, At, B1); BAR;
;       LDA(At, 1, 1); BAR; WAIT_L(0); MMA(1, 0, At, B0); MMA(1, 1, At, B1); BAR; }
;     if (wr == 0) BAR;
	s_waitcnt lgkmcnt(0)
	s_setprio 1
	s_waitcnt lgkmcnt(0)
	v_mfma_f32_16x16x32_bf16 v[90:93], v[144:147], v[58:61], v[126:129]
	v_mfma_f32_16x16x32_bf16 v[126:129], v[152:155], v[66:69], v[90:93]
	v_mfma_f32_16x16x32_bf16 v[90:93], v[156:159], v[58:61], v[122:125]
	v_mfma_f32_16x16x32_bf16 v[122:125], v[160:163], v[66:69], v[90:93]
	v_mfma_f32_16x16x32_bf16 v[90:93], v[144:147], v[70:73], v[118:121]
	v_mfma_f32_16x16x32_bf16 v[118:121], v[152:155], v[176:179], v[90:93]
	v_mfma_f32_16x16x32_bf16 v[90:93], v[156:159], v[70:73], v[114:117]
	v_mfma_f32_16x16x32_bf16 v[114:117], v[160:163], v[176:179], v[90:93]
	v_mfma_f32_16x16x32_bf16 v[90:93], v[144:147], v[180:183], v[110:113]
	v_mfma_f32_16x16x32_bf16 v[110:113], v[152:155], v[184:187], v[90:93]
	v_mfma_f32_16x16x32_bf16 v[90:93], v[156:159], v[180:183], v[106:109]
	v_mfma_f32_16x16x32_bf16 v[106:109], v[160:163], v[184:187], v[90:93]
	v_mfma_f32_16x16x32_bf16 v[90:93], v[144:147], v[188:191], v[102:105]
	v_mfma_f32_16x16x32_bf16 v[98:101], v[152:155], v[192:195], v[90:93]
	v_mfma_f32_16x16x32_bf16 v[90:93], v[156:159], v[188:191], v[148:151]
	v_mfma_f32_16x16x32_bf16 v[90:93], v[160:163], v[192:195], v[90:93]
	s_setprio 0
	v_add_u32_e32 v0, 0x1c000, v212
	s_barrier
	ds_read_b128 v[148:151], v0
	ds_read_b128 v[196:199], v0 offset:1024
	ds_read_b128 v[200:203], v0 offset:2048
	ds_read_b128 v[204:207], v0 offset:3072
	s_waitcnt vmcnt(0)
	s_barrier
	s_waitcnt lgkmcnt(0)
	s_setprio 1
	s_waitcnt lgkmcnt(0)
	v_mfma_f32_16x16x32_bf16 v[94:97], v[148:151], v[58:61], v[94:97]
	v_mfma_f32_16x16x32_bf16 v[58:61], v[200:203], v[58:61], v[164:167]
	v_mfma_f32_16x16x32_bf16 v[102:105], v[196:199], v[66:69], v[94:97]
	v_mfma_f32_16x16x32_bf16 v[94:97], v[204:207], v[66:69], v[58:61]
	v_mfma_f32_16x16x32_bf16 v[58:61], v[148:151], v[70:73], v[86:89]
	v_mfma_f32_16x16x32_bf16 v[86:89], v[196:199], v[176:179], v[58:61]
	v_mfma_f32_16x16x32_bf16 v[58:61], v[200:203], v[70:73], v[82:85]
	v_mfma_f32_16x16x32_bf16 v[82:85], v[204:207], v[176:179], v[58:61]
	v_mfma_f32_16x16x32_bf16 v[58:61], v[148:151], v[180:183], v[78:81]
	v_mfma_f32_16x16x32_bf16 v[78:81], v[196:199], v[184:187], v[58:61]
	v_mfma_f32_16x16x32_bf16 v[58:61], v[200:203], v[180:183], v[74:77]
	v_mfma_f32_16x16x32_bf16 v[70:73], v[204:207], v[184:187], v[58:61]
	v_mfma_f32_16x16x32_bf16 v[58:61], v[148:151], v[188:191], v[168:171]
	v_mfma_f32_16x16x32_bf16 v[66:69], v[196:199], v[192:195], v[58:61]
	v_mfma_f32_16x16x32_bf16 v[58:61], v[200:203], v[188:191], v[172:175]
	v_mfma_f32_16x16x32_bf16 v[58:61], v[204:207], v[192:195], v[58:61]
	s_setprio 0
	s_barrier
	ds_read_b128 v[164:167], v143 offset:49152
	ds_read_b128 v[168:171], v143 offset:50176
	ds_read_b128 v[172:175], v143 offset:51200
	ds_read_b128 v[176:179], v143 offset:52224
	ds_read_b128 v[180:183], v143 offset:53248
	ds_read_b128 v[184:187], v143 offset:54272
	ds_read_b128 v[188:191], v143 offset:55296
	ds_read_b128 v[192:195], v143 offset:56320
	s_barrier
	s_waitcnt lgkmcnt(0)
	s_setprio 1
	s_waitcnt lgkmcnt(0)
	v_mfma_f32_16x16x32_bf16 v[62:65], v[144:147], v[164:167], v[62:65]
	v_mfma_f32_16x16x32_bf16 v[74:77], v[152:155], v[168:171], v[62:65]
	v_mfma_f32_16x16x32_bf16 v[62:65], v[156:159], v[164:167], v[208:211]
	v_mfma_f32_16x16x32_bf16 v[54:57], v[144:147], v[172:175], v[54:57]
	v_mfma_f32_16x16x32_bf16 v[50:53], v[156:159], v[172:175], v[50:53]
	v_mfma_f32_16x16x32_bf16 v[46:49], v[144:147], v[180:183], v[46:49]
	v_mfma_f32_16x16x32_bf16 v[42:45], v[156:159], v[180:183], v[42:45]
	v_mfma_f32_16x16x32_bf16 v[38:41], v[144:147], v[188:191], v[38:41]
	v_mfma_f32_16x16x32_bf16 v[34:37], v[156:159], v[188:191], v[34:37]
	v_mfma_f32_16x16x32_bf16 v[62:65], v[160:163], v[168:171], v[62:65]
	v_mfma_f32_16x16x32_bf16 v[54:57], v[152:155], v[176:179], v[54:57]
	v_mfma_f32_16x16x32_bf16 v[50:53], v[160:163], v[176:179], v[50:53]
	v_mfma_f32_16x16x32_bf16 v[46:49], v[152:155], v[184:187], v[46:49]
	v_mfma_f32_16x16x32_bf16 v[42:45], v[160:163], v[184:187], v[42:45]
	v_mfma_f32_16x16x32_bf16 v[38:41], v[152:155], v[192:195], v[38:41]
	v_mfma_f32_16x16x32_bf16 v[34:37], v[160:163], v[192:195], v[34:37]
	s_setprio 0
	s_setprio 1
	v_mfma_f32_16x16x32_bf16 v[30:33], v[148:151], v[164:167], v[30:33]
	v_mfma_f32_16x16x32_bf16 v[26:29], v[200:203], v[164:167], v[26:29]
	v_mfma_f32_16x16x32_bf16 v[22:25], v[148:151], v[172:175], v[22:25]
	v_mfma_f32_16x16x32_bf16 v[18:21], v[200:203], v[172:175], v[18:21]
	v_mfma_f32_16x16x32_bf16 v[14:17], v[148:151], v[180:183], v[14:17]
	v_mfma_f32_16x16x32_bf16 v[10:13], v[200:203], v[180:183], v[10:13]
	v_mfma_f32_16x16x32_bf16 v[6:9], v[148:151], v[188:191], v[6:9]
	v_mfma_f32_16x16x32_bf16 v[2:5], v[200:203], v[188:191], v[2:5]
	v_mfma_f32_16x16x32_bf16 v[30:33], v[196:199], v[168:171], v[30:33]
	v_mfma_f32_16x16x32_bf16 v[26:29], v[204:207], v[168:171], v[26:29]
	v_mfma_f32_16x16x32_bf16 v[22:25], v[196:199], v[176:179], v[22:25]
	v_mfma_f32_16x16x32_bf16 v[18:21], v[204:207], v[176:179], v[18:21]
	v_mfma_f32_16x16x32_bf16 v[14:17], v[196:199], v[184:187], v[14:17]
	v_mfma_f32_16x16x32_bf16 v[10:13], v[204:207], v[184:187], v[10:13]
	v_mfma_f32_16x16x32_bf16 v[6:9], v[196:199], v[192:195], v[6:9]
	v_mfma_f32_16x16x32_bf16 v[2:5], v[204:207], v[192:195], v[2:5]
	s_setprio 0
	s_barrier
	s_and_saveexec_b64 s[0:1], s[6:7]
	s_cbranch_execz .LBB0_413
	s_barrier

; #define LDA(dst, b, h) for (int m = 0; m < 4; ++m) for (int k = 0; k < 2; ++k) \
;     dst[m][k] = *reinterpret_cast<const bf16x8*>((char*)SA(b, h) + a_thr + (m * 2 + k) * 1024)
; #define LDB(dst, b, h) for (int n = 0; n < 2; ++n) for (int k = 0; k < 2; ++k) \
;     dst[n][k] = *reinterpret_cast<const bf16x8*>((char*)SB(b, h) + b_thr + (n * 2 + k) * 1024)
; #define MMA(ai, bj, At, Btf) do { __builtin_amdgcn_s_setprio(1); \
;     for (int m = 0; m < 4; ++m) for (int n = 0; n < 2; ++n) for (int k = 0; k < 2; ++k) \
;       acc[ai][bj][m][n] = __builtin_amdgcn_mfma_f32_16x16x32_bf16(Btf[n][k], At[m][k], acc[ai][bj][m][n], 0, 0, 0); \
;     __builtin_amdgcn_s_setprio(0); } while (0)
; #define WAIT_V(n) asm volatile("s_waitcnt vmcnt(" #n ")" ::: "memory")
; #define WAIT_L(n) asm volatile("s_waitcnt lgkmcnt(" #n ")" ::: "memory")
; #define BAR __builtin_amdgcn_s_barrier()
; #define SCHED __builtin_amdgcn_sched_barrier(0)
; template <bool OVL, bool PANEL = false, class Epi>
; __device__ __forceinline__ void gemm_phase(const bf16_t* __restrict__ A, long lda, const bf16_t* __restrict__ Bt, long ldb, int nM, int nN, int K,
;                                            const Epi& epi, bf16_t* shm, int w0) {
;     ...
;     for (int t = 0; t < nt - 2; t += 2) {
;       LDB(B0, 0, 0); SCHED; LDA(At, 0, 0); STAGE(SA(1, 1), A, lda, aoff, brow + HALF, t + 1);
;       WAIT_L(8); BAR; WAIT_L(0); MMA(0, 0, At, B0); BAR; SCHED;
;       LDB(B1, 0, 1); STAGE(SB(0, 0), Bt, ldb, boff, bcol, t + 2);
;       BAR; WAIT_L(0); MMA(0, 1, At, B1); BAR;
;       LDA(At, 0, 1); STAGE(SA(0, 0), A, lda, aoff, brow, t + 2);
;       BAR; WAIT_L(0); MMA(1, 0, At, B0); BAR; SCHED;
;       STAGE(SB(0, 1), Bt, ldb, boff, bcol + HALF, t + 2);
;       WAIT_V(6); BAR; MMA(1, 1, At, B1); BAR;
.LBB0_472:
	ds_read_b128 v[138:141], v206
	ds_read_b128 v[142:145], v206 offset:1024
	ds_read_b128 v[146:149], v206 offset:2048
	ds_read_b128 v[150:153], v206 offset:3072
	s_add_u32 vcc_lo, s8, s80
	s_addc_u32 vcc_hi, s9, s81
	ds_read_b128 v[154:157], v241
	ds_read_b128 v[158:161], v241 offset:1024
	ds_read_b128 v[162:165], v241 offset:2048
	ds_read_b128 v[166:169], v241 offset:3072
	ds_read_b128 v[170:173], v241 offset:4096
	ds_read_b128 v[174:177], v241 offset:5120
	ds_read_b128 v[178:181], v241 offset:6144
	ds_read_b128 v[182:185], v241 offset:7168
	s_mov_b32 m0, s16
	s_add_u32 s98, vcc_lo, s12
	s_addc_u32 s99, vcc_hi, s13
	global_load_lds_dwordx4 v221, s[98:99]
	s_mov_b32 m0, s32
	s_add_u32 s98, vcc_lo, s36
	s_addc_u32 s99, vcc_hi, s37
	global_load_lds_dwordx4 v221, s[98:99]
	s_waitcnt lgkmcnt(8)
	s_waitcnt vmcnt(10)
	s_barrier
	s_waitcnt lgkmcnt(0)
	s_setprio 1
	s_waitcnt lgkmcnt(0)
	v_mfma_f32_16x16x32_bf16 v[126:129], v[138:141], v[154:157], v[126:129]
	v_mfma_f32_16x16x32_bf16 v[122:125], v[146:149], v[154:157], v[122:125]
	v_mfma_f32_16x16x32_bf16 v[118:121], v[138:141], v[162:165], v[118:121]
	v_mfma_f32_16x16x32_bf16 v[114:117], v[146:149], v[162:165], v[114:117]
	v_mfma_f32_16x16x32_bf16 v[110:113], v[138:141], v[170:173], v[110:113]
	v_mfma_f32_16x16x32_bf16 v[106:109], v[146:149], v[170:173], v[106:109]
	v_mfma_f32_16x16x32_bf16 v[102:105], v[138:141], v[178:181], v[102:105]
	v_mfma_f32_16x16x32_bf16 v[98:101], v[146:149], v[178:181], v[98:101]
	v_mfma_f32_16x16x32_bf16 v[126:129], v[142:145], v[158:161], v[126:129]
	v_mfma_f32_16x16x32_bf16 v[122:125], v[150:153], v[158:161], v[122:125]
	v_mfma_f32_16x16x32_bf16 v[118:121], v[142:145], v[166:169], v[118:121]
	v_mfma_f32_16x16x32_bf16 v[114:117], v[150:153], v[166:169], v[114:117]
	v_mfma_f32_16x16x32_bf16 v[110:113], v[142:145], v[174:177], v[110:113]
	v_mfma_f32_16x16x32_bf16 v[106:109], v[150:153], v[174:177], v[106:109]
	v_mfma_f32_16x16x32_bf16 v[102:105], v[142:145], v[182:185], v[102:105]
	v_mfma_f32_16x16x32_bf16 v[98:101], v[150:153], v[182:185], v[98:101]
	s_setprio 0
	s_barrier
	s_add_u32 s0, s6, s80
	ds_read_b128 v[186:189], v207
	ds_read_b128 v[190:193], v207 offset:1024
	ds_read_b128 v[194:197], v207 offset:2048
	ds_read_b128 v[198:201], v207 offset:3072
	s_addc_u32 s1, s7, s81
	s_mov_b32 m0, s44
	s_add_u32 s98, s0, s34
	s_addc_u32 s99, s1, s35
	global_load_lds_dwordx4 v221, s[98:99]
	s_mov_b32 m0, s45
	s_add_u32 s98, s0, s64
	s_addc_u32 s99, s1, s65
	global_load_lds_dwordx4 v221, s[98:99]
	s_waitcnt vmcnt(10)
	s_barrier
	s_waitcnt lgkmcnt(0)
	s_setprio 1
	s_waitcnt lgkmcnt(0)
	v_mfma_f32_16x16x32_bf16 v[94:97], v[186:189], v[154:157], v[94:97]
	v_mfma_f32_16x16x32_bf16 v[90:93], v[194:197], v[154:157], v[90:93]
	v_mfma_f32_16x16x32_bf16 v[86:89], v[186:189], v[162:165], v[86:89]
	v_mfma_f32_16x16x32_bf16 v[82:85], v[194:197], v[162:165], v[82:85]
	v_mfma_f32_16x16x32_bf16 v[78:81], v[186:189], v[170:173], v[78:81]
	v_mfma_f32_16x16x32_bf16 v[74:77], v[194:197], v[170:173], v[74:77]
	v_mfma_f32_16x16x32_bf16 v[70:73], v[186:189], v[178:181], v[70:73]
	v_mfma_f32_16x16x32_bf16 v[66:69], v[194:197], v[178:181], v[66:69]
	v_mfma_f32_16x16x32_bf16 v[94:97], v[190:193], v[158:161], v[94:97]
	v_mfma_f32_16x16x32_bf16 v[90:93], v[198:201], v[158:161], v[90:93]
	v_mfma_f32_16x16x32_bf16 v[86:89], v[190:193], v[166:169], v[86:89]
	v_mfma_f32_16x16x32_bf16 v[82:85], v[198:201], v[166:169], v[82:85]
	v_mfma_f32_16x16x32_bf16 v[78:81], v[190:193], v[174:177], v[78:81]
	v_mfma_f32_16x16x32_bf16 v[74:77], v[198:201], v[174:177], v[74:77]
	v_mfma_f32_16x16x32_bf16 v[70:73], v[190:193], v[182:185], v[70:73]
	v_mfma_f32_16x16x32_bf16 v[66:69], v[198:201], v[182:185], v[66:69]
	s_setprio 0
	s_barrier
	ds_read_b128 v[154:157], v241 offset:16384
	ds_read_b128 v[158:161], v241 offset:17408
	ds_read_b128 v[162:165], v241 offset:18432
	ds_read_b128 v[166:169], v241 offset:19456
	ds_read_b128 v[170:173], v241 offset:20480
	ds_read_b128 v[174:177], v241 offset:21504
	ds_read_b128 v[178:181], v241 offset:22528
	ds_read_b128 v[182:185], v241 offset:23552
	s_mov_b32 m0, s46
	s_add_u32 s98, vcc_lo, s34
	s_addc_u32 s99, vcc_hi, s35
	global_load_lds_dwordx4 v221, s[98:99]
	s_mov_b32 m0, s47
	s_add_u32 s98, vcc_lo, s64
	s_addc_u32 s99, vcc_hi, s65
	global_load_lds_dwordx4 v221, s[98:99]
	s_barrier
	s_waitcnt lgkmcnt(0)
	s_setprio 1
	s_waitcnt lgkmcnt(0)
	v_mfma_f32_16x16x32_bf16 v[62:65], v[138:141], v[154:157], v[62:65]
	v_mfma_f32_16x16x32_bf16 v[58:61], v[146:149], v[154:157], v[58:61]
	v_mfma_f32_16x16x32_bf16 v[54:57], v[138:141], v[162:165], v[54:57]
	v_mfma_f32_16x16x32_bf16 v[50:53], v[146:149], v[162:165], v[50:53]
	v_mfma_f32_16x16x32_bf16 v[46:49], v[138:141], v[170:173], v[46:49]
	v_mfma_f32_16x16x32_bf16 v[42:45], v[146:149], v[170:173], v[42:45]
	v_mfma_f32_16x16x32_bf16 v[38:41], v[138:141], v[178:181], v[38:41]
	v_mfma_f32_16x16x32_bf16 v[34:37], v[146:149], v[178:181], v[34:37]
	v_mfma_f32_16x16x32_bf16 v[62:65], v[142:145], v[158:161], v[62:65]
	v_mfma_f32_16x16x32_bf16 v[58:61], v[150:153], v[158:161], v[58:61]
	v_mfma_f32_16x16x32_bf16 v[54:57], v[142:145], v[166:169], v[54:57]
	v_mfma_f32_16x16x32_bf16 v[50:53], v[150:153], v[166:169], v[50:53]
	v_mfma_f32_16x16x32_bf16 v[46:49], v[142:145], v[174:177], v[46:49]
	v_mfma_f32_16x16x32_bf16 v[42:45], v[150:153], v[174:177], v[42:45]
	v_mfma_f32_16x16x32_bf16 v[38:41], v[142:145], v[182:185], v[38:41]
	v_mfma_f32_16x16x32_bf16 v[34:37], v[150:153], v[182:185], v[34:37]
	s_setprio 0
	s_barrier
	s_mov_b32 m0, s48
	s_add_u32 s98, s0, s68
	s_addc_u32 s99, s1, s69
	global_load_lds_dwordx4 v221, s[98:99]
	s_mov_b32 m0, s49
	s_add_u32 s98, s0, s70
	s_addc_u32 s99, s1, s71
	global_load_lds_dwordx4 v221, s[98:99]
	s_waitcnt vmcnt(10)
	s_barrier
; #define LDA(dst, b, h) for (int m = 0; m < 4; ++m) for (int k = 0; k < 2; ++k) \
;     dst[m][k] = *reinterpret_cast<const bf16x8*>((char*)SA(b, h) + a_thr + (m * 2 + k) * 1024)
; #define LDB(dst, b, h) for (int n = 0; n < 2; ++n) for (int k = 0; k < 2; ++k) \
;     dst[n][k] = *reinterpret_cast<const bf16x8*>((char*)SB(b, h) + b_thr + (n * 2 + k) * 1024)
; #define MMA(ai, bj, At, Btf) do { __builtin_amdgcn_s_setprio(1); \
;     for (int m = 0; m < 4; ++m) for (int n = 0; n < 2; ++n) for (int k = 0; k < 2; ++k) \
;       acc[ai][bj][m][n] = __builtin_amdgcn_mfma_f32_16x16x32_bf16(Btf[n][k], At[m][k], acc[ai][bj][m][n], 0, 0, 0); \
;     __builtin_amdgcn_s_setprio(0); } while (0)
; #define WAIT_V(n) asm volatile("s_waitcnt vmcnt(" #n ")" ::: "memory")
; #define WAIT_L(n) asm volatile("s_waitcnt lgkmcnt(" #n ")" ::: "memory")
; #define BAR __builtin_amdgcn_s_barrier()
; #define SCHED __builtin_amdgcn_sched_barrier(0)
; template <bool OVL, bool PANEL = false, class Epi>
; __device__ __forceinline__ void gemm_phase(const bf16_t* __restrict__ A, long lda, const bf16_t* __restrict__ Bt, long ldb, int nM, int nN, int K,
;                                            const Epi& epi, bf16_t* shm, int w0) {
;     ...
;       WAIT_V(6); BAR; MMA(1, 1, At, B1); BAR;
;       LDB(B0, 1, 0); SCHED; LDA(At, 1, 0); STAGE(SA(0, 1), A, lda, aoff, brow + HALF, t + 2);
;       WAIT_L(8); BAR; WAIT_L(0); MMA(0, 0, At, B0); BAR; SCHED;
;       LDB(B1, 1, 1); STAGE(SB(1, 0), Bt, ldb, boff, bcol, t + 3);
;       BAR; WAIT_L(0); MMA(0, 1, At, B1); BAR;
;       LDA(At, 1, 1); STAGE(SA(1, 0), A, lda, aoff, brow, t + 3);
	s_setprio 1
	v_mfma_f32_16x16x32_bf16 v[30:33], v[186:189], v[154:157], v[30:33]
	v_mfma_f32_16x16x32_bf16 v[26:29], v[194:197], v[154:157], v[26:29]
	v_mfma_f32_16x16x32_bf16 v[22:25], v[186:189], v[162:165], v[22:25]
	v_mfma_f32_16x16x32_bf16 v[18:21], v[194:197], v[162:165], v[18:21]
	v_mfma_f32_16x16x32_bf16 v[14:17], v[186:189], v[170:173], v[14:17]
	v_mfma_f32_16x16x32_bf16 v[10:13], v[194:197], v[170:173], v[10:13]
	v_mfma_f32_16x16x32_bf16 v[6:9], v[186:189], v[178:181], v[6:9]
	v_mfma_f32_16x16x32_bf16 v[2:5], v[194:197], v[178:181], v[2:5]
	v_mfma_f32_16x16x32_bf16 v[30:33], v[190:193], v[158:161], v[30:33]
	v_mfma_f32_16x16x32_bf16 v[26:29], v[198:201], v[158:161], v[26:29]
	v_mfma_f32_16x16x32_bf16 v[22:25], v[190:193], v[166:169], v[22:25]
	v_mfma_f32_16x16x32_bf16 v[18:21], v[198:201], v[166:169], v[18:21]
	v_mfma_f32_16x16x32_bf16 v[14:17], v[190:193], v[174:177], v[14:17]
	v_mfma_f32_16x16x32_bf16 v[10:13], v[198:201], v[174:177], v[10:13]
	v_mfma_f32_16x16x32_bf16 v[6:9], v[190:193], v[182:185], v[6:9]
	v_mfma_f32_16x16x32_bf16 v[2:5], v[198:201], v[182:185], v[2:5]
	s_setprio 0
	s_barrier
	ds_read_b128 v[138:141], v208
	ds_read_b128 v[142:145], v208 offset:1024
	ds_read_b128 v[146:149], v208 offset:2048
	ds_read_b128 v[150:153], v208 offset:3072
	ds_read_b128 v[154:157], v241 offset:32768
	ds_read_b128 v[158:161], v241 offset:33792
	ds_read_b128 v[162:165], v241 offset:34816
	ds_read_b128 v[166:169], v241 offset:35840
	ds_read_b128 v[170:173], v241 offset:36864
	ds_read_b128 v[174:177], v241 offset:37888
	ds_read_b128 v[178:181], v241 offset:38912
	ds_read_b128 v[182:185], v241 offset:39936
	s_mov_b32 m0, s50
	s_add_u32 s98, vcc_lo, s68
	s_addc_u32 s99, vcc_hi, s69
	global_load_lds_dwordx4 v221, s[98:99]
	s_mov_b32 m0, s51
	s_add_u32 s98, vcc_lo, s70
	s_addc_u32 s99, vcc_hi, s71
	global_load_lds_dwordx4 v221, s[98:99]
	s_waitcnt lgkmcnt(8)
	s_waitcnt vmcnt(10)
	s_barrier
	s_waitcnt lgkmcnt(0)
	s_setprio 1
	s_waitcnt lgkmcnt(0)
	v_mfma_f32_16x16x32_bf16 v[126:129], v[138:141], v[154:157], v[126:129]
	v_mfma_f32_16x16x32_bf16 v[122:125], v[146:149], v[154:157], v[122:125]
	v_mfma_f32_16x16x32_bf16 v[118:121], v[138:141], v[162:165], v[118:121]
	v_mfma_f32_16x16x32_bf16 v[114:117], v[146:149], v[162:165], v[114:117]
	v_mfma_f32_16x16x32_bf16 v[110:113], v[138:141], v[170:173], v[110:113]
	v_mfma_f32_16x16x32_bf16 v[106:109], v[146:149], v[170:173], v[106:109]
	v_mfma_f32_16x16x32_bf16 v[102:105], v[138:141], v[178:181], v[102:105]
	v_mfma_f32_16x16x32_bf16 v[98:101], v[146:149], v[178:181], v[98:101]
	v_mfma_f32_16x16x32_bf16 v[126:129], v[142:145], v[158:161], v[126:129]
	v_mfma_f32_16x16x32_bf16 v[122:125], v[150:153], v[158:161], v[122:125]
	v_mfma_f32_16x16x32_bf16 v[118:121], v[142:145], v[166:169], v[118:121]
	v_mfma_f32_16x16x32_bf16 v[114:117], v[150:153], v[166:169], v[114:117]
	v_mfma_f32_16x16x32_bf16 v[110:113], v[142:145], v[174:177], v[110:113]
	v_mfma_f32_16x16x32_bf16 v[106:109], v[150:153], v[174:177], v[106:109]
	v_mfma_f32_16x16x32_bf16 v[102:105], v[142:145], v[182:185], v[102:105]
	v_mfma_f32_16x16x32_bf16 v[98:101], v[150:153], v[182:185], v[98:101]
	s_setprio 0
	s_barrier
	ds_read_b128 v[186:189], v209
	ds_read_b128 v[190:193], v209 offset:1024
	ds_read_b128 v[194:197], v209 offset:2048
	ds_read_b128 v[198:201], v209 offset:3072
	s_mov_b32 m0, s52
	s_add_u32 s98, s0, s94
	s_addc_u32 s99, s1, s95
	global_load_lds_dwordx4 v221, s[98:99]
	s_mov_b32 m0, s53
	s_add_u32 s98, s0, s72
	s_addc_u32 s99, s1, s73
	global_load_lds_dwordx4 v221, s[98:99]
	s_waitcnt vmcnt(10)
	s_barrier
	s_waitcnt lgkmcnt(0)
	s_setprio 1
	s_waitcnt lgkmcnt(0)
	v_mfma_f32_16x16x32_bf16 v[94:97], v[186:189], v[154:157], v[94:97]
	v_mfma_f32_16x16x32_bf16 v[90:93], v[194:197], v[154:157], v[90:93]
	v_mfma_f32_16x16x32_bf16 v[86:89], v[186:189], v[162:165], v[86:89]
	v_mfma_f32_16x16x32_bf16 v[82:85], v[194:197], v[162:165], v[82:85]
	v_mfma_f32_16x16x32_bf16 v[78:81], v[186:189], v[170:173], v[78:81]
	v_mfma_f32_16x16x32_bf16 v[74:77], v[194:197], v[170:173], v[74:77]
	v_mfma_f32_16x16x32_bf16 v[70:73], v[186:189], v[178:181], v[70:73]
	v_mfma_f32_16x16x32_bf16 v[66:69], v[194:197], v[178:181], v[66:69]
	v_mfma_f32_16x16x32_bf16 v[94:97], v[190:193], v[158:161], v[94:97]
	v_mfma_f32_16x16x32_bf16 v[90:93], v[198:201], v[158:161], v[90:93]
	v_mfma_f32_16x16x32_bf16 v[86:89], v[190:193], v[166:169], v[86:89]
	v_mfma_f32_16x16x32_bf16 v[82:85], v[198:201], v[166:169], v[82:85]
	v_mfma_f32_16x16x32_bf16 v[78:81], v[190:193], v[174:177], v[78:81]
	v_mfma_f32_16x16x32_bf16 v[74:77], v[198:201], v[174:177], v[74:77]
	v_mfma_f32_16x16x32_bf16 v[70:73], v[190:193], v[182:185], v[70:73]
	v_mfma_f32_16x16x32_bf16 v[66:69], v[198:201], v[182:185], v[66:69]
	s_setprio 0
	s_barrier
	ds_read_b128 v[154:157], v241 offset:49152
	ds_read_b128 v[158:161], v241 offset:50176
	ds_read_b128 v[162:165], v241 offset:51200
	ds_read_b128 v[166:169], v241 offset:52224
	ds_read_b128 v[170:173], v241 offset:53248
	ds_read_b128 v[174:177], v241 offset:54272
	ds_read_b128 v[178:181], v241 offset:55296
	ds_read_b128 v[182:185], v241 offset:56320
	s_mov_b32 m0, s54
	s_add_u32 s98, vcc_lo, s94
	s_addc_u32 s99, vcc_hi, s95
	global_load_lds_dwordx4 v221, s[98:99]
	s_mov_b32 m0, s55
	s_add_u32 s98, vcc_lo, s72
	s_addc_u32 s99, vcc_hi, s73
	global_load_lds_dwordx4 v221, s[98:99]
	s_barrier
; #define LDA(dst, b, h) for (int m = 0; m < 4; ++m) for (int k = 0; k < 2; ++k) \
;     dst[m][k] = *reinterpret_cast<const bf16x8*>((char*)SA(b, h) + a_thr + (m * 2 + k) * 1024)
; #define LDB(dst, b, h) for (int n = 0; n < 2; ++n) for (int k = 0; k < 2; ++k) \
;     dst[n][k] = *reinterpret_cast<const bf16x8*>((char*)SB(b, h) + b_thr + (n * 2 + k) * 1024)
; #define MMA(ai, bj, At, Btf) do { __builtin_amdgcn_s_setprio(1); \
;     for (int m = 0; m < 4; ++m) for (int n = 0; n < 2; ++n) for (int k = 0; k < 2; ++k) \
;       acc[ai][bj][m][n] = __builtin_amdgcn_mfma_f32_16x16x32_bf16(Btf[n][k], At[m][k], acc[ai][bj][m][n], 0, 0, 0); \
;     __builtin_amdgcn_s_setprio(0); } while (0)
; #define WAIT_V(n) asm volatile("s_waitcnt vmcnt(" #n ")" ::: "memory")
; #define WAIT_L(n) asm volatile("s_waitcnt lgkmcnt(" #n ")" ::: "memory")
; #define BAR __builtin_amdgcn_s_barrier()
; #define SCHED __builtin_amdgcn_sched_barrier(0)
; template <bool OVL, bool PANEL = false, class Epi>
; __device__ __forceinline__ void gemm_phase(const bf16_t* __restrict__ A, long lda, const bf16_t* __restrict__ Bt, long ldb, int nM, int nN, int K,
;                                            const Epi& epi, bf16_t* shm, int w0) {
;     ...
;       BAR; WAIT_L(0); MMA(1, 0, At, B0); BAR; SCHED;
;       STAGE(SB(1, 1), Bt, ldb, boff, bcol + HALF, t + 3);
;       WAIT_V(6); BAR; MMA(1, 1, At, B1); BAR;
;     }
;     { LDB(B0, 0, 0); LDA(At, 0, 0); STAGE(SA(1, 1), A, lda, aoff, brow + HALF, nt - 1);
;       BAR; WAIT_L(0); MMA(0, 0, At, B0); BAR;
;       LDB(B1, 0, 1); BAR; WAIT_L(0); MMA(0, 1, At, B1); BAR;
	s_waitcnt lgkmcnt(0)
	s_setprio 1
	s_waitcnt lgkmcnt(0)
	v_mfma_f32_16x16x32_bf16 v[62:65], v[138:141], v[154:157], v[62:65]
	v_mfma_f32_16x16x32_bf16 v[58:61], v[146:149], v[154:157], v[58:61]
	v_mfma_f32_16x16x32_bf16 v[54:57], v[138:141], v[162:165], v[54:57]
	v_mfma_f32_16x16x32_bf16 v[50:53], v[146:149], v[162:165], v[50:53]
	v_mfma_f32_16x16x32_bf16 v[46:49], v[138:141], v[170:173], v[46:49]
	v_mfma_f32_16x16x32_bf16 v[42:45], v[146:149], v[170:173], v[42:45]
	v_mfma_f32_16x16x32_bf16 v[38:41], v[138:141], v[178:181], v[38:41]
	v_mfma_f32_16x16x32_bf16 v[34:37], v[146:149], v[178:181], v[34:37]
	v_mfma_f32_16x16x32_bf16 v[62:65], v[142:145], v[158:161], v[62:65]
	v_mfma_f32_16x16x32_bf16 v[58:61], v[150:153], v[158:161], v[58:61]
	v_mfma_f32_16x16x32_bf16 v[54:57], v[142:145], v[166:169], v[54:57]
	v_mfma_f32_16x16x32_bf16 v[50:53], v[150:153], v[166:169], v[50:53]
	v_mfma_f32_16x16x32_bf16 v[46:49], v[142:145], v[174:177], v[46:49]
	v_mfma_f32_16x16x32_bf16 v[42:45], v[150:153], v[174:177], v[42:45]
	v_mfma_f32_16x16x32_bf16 v[38:41], v[142:145], v[182:185], v[38:41]
	v_mfma_f32_16x16x32_bf16 v[34:37], v[150:153], v[182:185], v[34:37]
	s_setprio 0
	s_barrier
	s_mov_b32 m0, s56
	s_add_u32 s98, s0, s14
	s_addc_u32 s99, s1, s15
	global_load_lds_dwordx4 v221, s[98:99]
	s_mov_b32 m0, s57
	s_add_u32 s98, s0, s18
	s_addc_u32 s99, s1, s19
	global_load_lds_dwordx4 v221, s[98:99]
	s_waitcnt vmcnt(10)
	s_barrier
	s_setprio 1
	v_mfma_f32_16x16x32_bf16 v[30:33], v[186:189], v[154:157], v[30:33]
	v_mfma_f32_16x16x32_bf16 v[26:29], v[194:197], v[154:157], v[26:29]
	v_mfma_f32_16x16x32_bf16 v[22:25], v[186:189], v[162:165], v[22:25]
	v_mfma_f32_16x16x32_bf16 v[18:21], v[194:197], v[162:165], v[18:21]
	v_mfma_f32_16x16x32_bf16 v[14:17], v[186:189], v[170:173], v[14:17]
	v_mfma_f32_16x16x32_bf16 v[10:13], v[194:197], v[170:173], v[10:13]
	v_mfma_f32_16x16x32_bf16 v[6:9], v[186:189], v[178:181], v[6:9]
	v_mfma_f32_16x16x32_bf16 v[2:5], v[194:197], v[178:181], v[2:5]
	v_mfma_f32_16x16x32_bf16 v[30:33], v[190:193], v[158:161], v[30:33]
	v_mfma_f32_16x16x32_bf16 v[26:29], v[198:201], v[158:161], v[26:29]
	v_mfma_f32_16x16x32_bf16 v[22:25], v[190:193], v[166:169], v[22:25]
	v_mfma_f32_16x16x32_bf16 v[18:21], v[198:201], v[166:169], v[18:21]
	v_mfma_f32_16x16x32_bf16 v[14:17], v[190:193], v[174:177], v[14:17]
	v_mfma_f32_16x16x32_bf16 v[10:13], v[198:201], v[174:177], v[10:13]
	v_mfma_f32_16x16x32_bf16 v[6:9], v[190:193], v[182:185], v[6:9]
	v_mfma_f32_16x16x32_bf16 v[2:5], v[198:201], v[182:185], v[2:5]
	s_setprio 0
	s_add_i32 s2, s2, 2
	s_add_u32 s80, s80, 0x100
	s_addc_u32 s81, s81, 0
	s_cmp_gt_u32 s2, 11
	s_barrier
	s_cbranch_scc0 .LBB0_472
	s_waitcnt vmcnt(6)
	s_or_b32 s0, s82, 0x80
	s_ashr_i32 s1, s0, 31
	v_readlane_b32 s44, v252, 20
	s_lshl_b64 s[0:1], s[0:1], 11
	v_readlane_b32 s50, v252, 26
	v_add_u32_e32 v206, 16, v240
	v_readlane_b32 s51, v252, 27
	s_add_u32 s0, s50, s0
	v_add_u32_e32 v0, 0x10000, v206
	s_addc_u32 s1, s51, s1
	ds_read_b128 v[130:133], v0
	ds_read_b128 v[138:141], v0 offset:1024
	ds_read_b128 v[142:145], v0 offset:2048
	ds_read_b128 v[146:149], v0 offset:3072
	ds_read_b128 v[150:153], v241
	ds_read_b128 v[154:157], v241 offset:1024
	ds_read_b128 v[158:161], v241 offset:2048
	ds_read_b128 v[162:165], v241 offset:3072
	ds_read_b128 v[166:169], v241 offset:4096
	ds_read_b128 v[170:173], v241 offset:5120
	ds_read_b128 v[174:177], v241 offset:6144
	ds_read_b128 v[178:181], v241 offset:7168
	v_mov_b32_e32 v0, v221
	v_readlane_b32 s45, v252, 21
	v_lshl_add_u64 v[134:135], s[0:1], 0, v[0:1]
	s_mov_b64 s[0:1], 0x780
	v_lshl_add_u64 v[182:183], v[134:135], 0, s[0:1]
	v_readfirstlane_b32 s0, v136
	s_mov_b32 m0, s0
	s_mov_b64 s[0:1], 0x20780
	v_lshl_add_u64 v[134:135], v[134:135], 0, s[0:1]
	v_readfirstlane_b32 s0, v137
	global_load_lds_dwordx4 v[182:183], off
	s_mov_b32 m0, s0
	v_readlane_b32 s46, v252, 22
	global_load_lds_dwordx4 v[134:135], off
	s_barrier
	s_waitcnt lgkmcnt(0)
	v_readlane_b32 s47, v252, 23
	v_readlane_b32 s48, v252, 24
	v_readlane_b32 s49, v252, 25
	v_readlane_b32 s52, v252, 28
	v_readlane_b32 s53, v252, 29
	v_readlane_b32 s54, v252, 30
	v_readlane_b32 s55, v252, 31
	v_readlane_b32 s56, v252, 32
	v_readlane_b32 s57, v252, 33
	v_readlane_b32 s58, v252, 34
	v_readlane_b32 s59, v252, 35
	s_setprio 1
	s_waitcnt lgkmcnt(0)
	v_mfma_f32_16x16x32_bf16 v[126:129], v[130:133], v[150:153], v[126:129]
	v_mfma_f32_16x16x32_bf16 v[122:125], v[142:145], v[150:153], v[122:125]
	v_mfma_f32_16x16x32_bf16 v[118:121], v[130:133], v[158:161], v[118:121]
	v_mfma_f32_16x16x32_bf16 v[114:117], v[142:145], v[158:161], v[114:117]
	v_mfma_f32_16x16x32_bf16 v[106:109], v[142:145], v[166:169], v[106:109]
	v_mfma_f32_16x16x32_bf16 v[102:105], v[130:133], v[174:177], v[102:105]
	v_mfma_f32_16x16x32_bf16 v[98:101], v[142:145], v[174:177], v[98:101]
	v_mfma_f32_16x16x32_bf16 v[126:129], v[138:141], v[154:157], v[126:129]
	v_mfma_f32_16x16x32_bf16 v[122:125], v[146:149], v[154:157], v[122:125]
	v_mfma_f32_16x16x32_bf16 v[118:121], v[138:141], v[162:165], v[118:121]
	v_mfma_f32_16x16x32_bf16 v[114:117], v[146:149], v[162:165], v[114:117]
	v_mfma_f32_16x16x32_bf16 v[110:113], v[130:133], v[166:169], v[110:113]
	v_mfma_f32_16x16x32_bf16 v[106:109], v[146:149], v[170:173], v[106:109]
	v_mfma_f32_16x16x32_bf16 v[102:105], v[138:141], v[178:181], v[102:105]
	v_mfma_f32_16x16x32_bf16 v[98:101], v[146:149], v[178:181], v[98:101]
	v_mfma_f32_16x16x32_bf16 v[134:137], v[138:141], v[170:173], v[110:113]
	s_setprio 0
	v_add_u32_e32 v0, 0x14000, v206
	s_barrier
	s_nop 0
	ds_read_b128 v[110:113], v0
	ds_read_b128 v[182:185], v0 offset:1024
	ds_read_b128 v[186:189], v0 offset:2048
	ds_read_b128 v[190:193], v0 offset:3072
	s_barrier
; #define LDA(dst, b, h) for (int m = 0; m < 4; ++m) for (int k = 0; k < 2; ++k) \
;     dst[m][k] = *reinterpret_cast<const bf16x8*>((char*)SA(b, h) + a_thr + (m * 2 + k) * 1024)
; #define LDB(dst, b, h) for (int n = 0; n < 2; ++n) for (int k = 0; k < 2; ++k) \
;     dst[n][k] = *reinterpret_cast<const bf16x8*>((char*)SB(b, h) + b_thr + (n * 2 + k) * 1024)
; #define MMA(ai, bj, At, Btf) do { __builtin_amdgcn_s_setprio(1); \
;     for (int m = 0; m < 4; ++m) for (int n = 0; n < 2; ++n) for (int k = 0; k < 2; ++k) \
;       acc[ai][bj][m][n] = __builtin_amdgcn_mfma_f32_16x16x32_bf16(Btf[n][k], At[m][k], acc[ai][bj][m][n], 0, 0, 0); \
;     __builtin_amdgcn_s_setprio(0); } while (0)
; #define WAIT_V(n) asm volatile("s_waitcnt vmcnt(" #n ")" ::: "memory")
; #define WAIT_L(n) asm volatile("s_waitcnt lgkmcnt(" #n ")" ::: "memory")
; #define BAR __builtin_amdgcn_s_barrier()
; template <bool OVL, bool PANEL = false, class Epi>
; __device__ __forceinline__ void gemm_phase(const bf16_t* __restrict__ A, long lda, const bf16_t* __restrict__ Bt, long ldb, int nM, int nN, int K,
;                                            const Epi& epi, bf16_t* shm, int w0) {
;     ...
;       LDB(B1, 0, 1); BAR; WAIT_L(0); MMA(0, 1, At, B1); BAR;
;       LDA(At, 0, 1); WAIT_V(4); BAR; WAIT_L(0); MMA(1, 0, At, B0); MMA(1, 1, At, B1); BAR; }
;     { LDB(B0, 1, 0); LDA(At, 1, 0); WAIT_V(2); BAR; WAIT_L(0); MMA(0, 0, At, B0); BAR;
	s_waitcnt lgkmcnt(0)
	s_setprio 1
	s_waitcnt lgkmcnt(0)
	v_mfma_f32_16x16x32_bf16 v[90:93], v[186:189], v[150:153], v[90:93]
	v_mfma_f32_16x16x32_bf16 v[74:77], v[186:189], v[166:169], v[74:77]
	v_mfma_f32_16x16x32_bf16 v[70:73], v[110:113], v[174:177], v[70:73]
	v_mfma_f32_16x16x32_bf16 v[66:69], v[186:189], v[174:177], v[66:69]
	v_mfma_f32_16x16x32_bf16 v[94:97], v[110:113], v[150:153], v[94:97]
	v_mfma_f32_16x16x32_bf16 v[90:93], v[190:193], v[154:157], v[90:93]
	v_mfma_f32_16x16x32_bf16 v[86:89], v[110:113], v[158:161], v[86:89]
	v_mfma_f32_16x16x32_bf16 v[82:85], v[186:189], v[158:161], v[82:85]
	v_mfma_f32_16x16x32_bf16 v[78:81], v[110:113], v[166:169], v[78:81]
	v_mfma_f32_16x16x32_bf16 v[74:77], v[190:193], v[170:173], v[74:77]
	v_mfma_f32_16x16x32_bf16 v[70:73], v[182:185], v[178:181], v[70:73]
	v_mfma_f32_16x16x32_bf16 v[66:69], v[190:193], v[178:181], v[66:69]
	v_mfma_f32_16x16x32_bf16 v[194:197], v[182:185], v[154:157], v[94:97]
	v_mfma_f32_16x16x32_bf16 v[150:153], v[182:185], v[162:165], v[86:89]
	v_mfma_f32_16x16x32_bf16 v[154:157], v[190:193], v[162:165], v[82:85]
	v_mfma_f32_16x16x32_bf16 v[158:161], v[182:185], v[170:173], v[78:81]
	s_setprio 0
	s_barrier
	s_nop 0
	ds_read_b128 v[78:81], v241 offset:16384
	ds_read_b128 v[82:85], v241 offset:17408
	ds_read_b128 v[86:89], v241 offset:18432
	ds_read_b128 v[94:97], v241 offset:19456
	ds_read_b128 v[162:165], v241 offset:20480
	ds_read_b128 v[166:169], v241 offset:21504
	ds_read_b128 v[170:173], v241 offset:22528
	ds_read_b128 v[174:177], v241 offset:23552
	s_waitcnt vmcnt(4)
	s_barrier
	s_waitcnt lgkmcnt(0)
	s_setprio 1
	s_waitcnt lgkmcnt(0)
	v_mfma_f32_16x16x32_bf16 v[62:65], v[130:133], v[78:81], v[62:65]
	v_mfma_f32_16x16x32_bf16 v[58:61], v[142:145], v[78:81], v[58:61]
	v_mfma_f32_16x16x32_bf16 v[54:57], v[130:133], v[86:89], v[54:57]
	v_mfma_f32_16x16x32_bf16 v[50:53], v[142:145], v[86:89], v[50:53]
	v_mfma_f32_16x16x32_bf16 v[46:49], v[130:133], v[162:165], v[46:49]
	v_mfma_f32_16x16x32_bf16 v[42:45], v[142:145], v[162:165], v[42:45]
	v_mfma_f32_16x16x32_bf16 v[34:37], v[142:145], v[170:173], v[34:37]
	v_mfma_f32_16x16x32_bf16 v[62:65], v[138:141], v[82:85], v[62:65]
	v_mfma_f32_16x16x32_bf16 v[58:61], v[146:149], v[82:85], v[58:61]
	v_mfma_f32_16x16x32_bf16 v[54:57], v[138:141], v[94:97], v[54:57]
	v_mfma_f32_16x16x32_bf16 v[50:53], v[146:149], v[94:97], v[50:53]
	v_mfma_f32_16x16x32_bf16 v[46:49], v[138:141], v[166:169], v[46:49]
	v_mfma_f32_16x16x32_bf16 v[42:45], v[146:149], v[166:169], v[42:45]
	v_mfma_f32_16x16x32_bf16 v[38:41], v[130:133], v[170:173], v[38:41]
	v_mfma_f32_16x16x32_bf16 v[34:37], v[146:149], v[174:177], v[34:37]
	v_mfma_f32_16x16x32_bf16 v[130:133], v[138:141], v[174:177], v[38:41]
	s_setprio 0
	s_setprio 1
	v_mfma_f32_16x16x32_bf16 v[30:33], v[110:113], v[78:81], v[30:33]
	v_mfma_f32_16x16x32_bf16 v[26:29], v[186:189], v[78:81], v[26:29]
	v_mfma_f32_16x16x32_bf16 v[22:25], v[110:113], v[86:89], v[22:25]
	v_mfma_f32_16x16x32_bf16 v[18:21], v[186:189], v[86:89], v[18:21]
	v_mfma_f32_16x16x32_bf16 v[14:17], v[110:113], v[162:165], v[14:17]
	v_mfma_f32_16x16x32_bf16 v[10:13], v[186:189], v[162:165], v[10:13]
	v_mfma_f32_16x16x32_bf16 v[6:9], v[110:113], v[170:173], v[6:9]
	v_mfma_f32_16x16x32_bf16 v[2:5], v[186:189], v[170:173], v[2:5]
	v_mfma_f32_16x16x32_bf16 v[138:141], v[182:185], v[82:85], v[30:33]
	v_mfma_f32_16x16x32_bf16 v[142:145], v[190:193], v[82:85], v[26:29]
	v_mfma_f32_16x16x32_bf16 v[146:149], v[182:185], v[94:97], v[22:25]
	v_mfma_f32_16x16x32_bf16 v[178:181], v[190:193], v[94:97], v[18:21]
	v_mfma_f32_16x16x32_bf16 v[198:201], v[182:185], v[166:169], v[14:17]
	v_mfma_f32_16x16x32_bf16 v[162:165], v[190:193], v[166:169], v[10:13]
	v_mfma_f32_16x16x32_bf16 v[166:169], v[182:185], v[174:177], v[6:9]
	v_mfma_f32_16x16x32_bf16 v[170:173], v[190:193], v[174:177], v[2:5]
	s_setprio 0
	v_add_u32_e32 v0, 0x18000, v206
	s_barrier
	ds_read_b128 v[174:177], v0
	ds_read_b128 v[182:185], v0 offset:1024
	ds_read_b128 v[186:189], v0 offset:2048
	ds_read_b128 v[190:193], v0 offset:3072
	ds_read_b128 v[6:9], v241 offset:32768
	ds_read_b128 v[14:17], v241 offset:33792
	ds_read_b128 v[18:21], v241 offset:34816
	ds_read_b128 v[22:25], v241 offset:35840
	ds_read_b128 v[26:29], v241 offset:36864
	ds_read_b128 v[30:33], v241 offset:37888
	ds_read_b128 v[38:41], v241 offset:38912
	ds_read_b128 v[202:205], v241 offset:39936
	s_waitcnt vmcnt(2)
	s_barrier
; #define LDA(dst, b, h) for (int m = 0; m < 4; ++m) for (int k = 0; k < 2; ++k) \
;     dst[m][k] = *reinterpret_cast<const bf16x8*>((char*)SA(b, h) + a_thr + (m * 2 + k) * 1024)
; #define LDB(dst, b, h) for (int n = 0; n < 2; ++n) for (int k = 0; k < 2; ++k) \
;     dst[n][k] = *reinterpret_cast<const bf16x8*>((char*)SB(b, h) + b_thr + (n * 2 + k) * 1024)
; #define MMA(ai, bj, At, Btf) do { __builtin_amdgcn_s_setprio(1); \
;     for (int m = 0; m < 4; ++m) for (int n = 0; n < 2; ++n) for (int k = 0; k < 2; ++k) \
;       acc[ai][bj][m][n] = __builtin_amdgcn_mfma_f32_16x16x32_bf16(Btf[n][k], At[m][k], acc[ai][bj][m][n], 0, 0, 0); \
;     __builtin_amdgcn_s_setprio(0); } while (0)
; #define WAIT_V(n) asm volatile("s_waitcnt vmcnt(" #n ")" ::: "memory")
; #define WAIT_L(n) asm volatile("s_waitcnt lgkmcnt(" #n ")" ::: "memory")
; #define BAR __builtin_amdgcn_s_barrier()
; template <bool OVL, bool PANEL = false, class Epi>
; __device__ __forceinline__ void gemm_phase(const bf16_t* __restrict__ A, long lda, const bf16_t* __restrict__ Bt, long ldb, int nM, int nN, int K,
;                                            const Epi& epi, bf16_t* shm, int w0) {
;     ...
;     { LDB(B0, 1, 0); LDA(At, 1, 0); WAIT_V(2); BAR; WAIT_L(0); MMA(0, 0, At, B0); BAR;
;       LDB(B1, 1, 1); WAIT_V(0); BAR; WAIT_L(0); MMA(0, 1, At, B1); BAR;
;       LDA(At, 1, 1); BAR; WAIT_L(0); MMA(1, 0, At, B0); MMA(1, 1, At, B1); BAR; }
;     if (wr == 0) BAR;
	s_waitcnt lgkmcnt(0)
	s_setprio 1
	s_waitcnt lgkmcnt(0)
	v_mfma_f32_16x16x32_bf16 v[2:5], v[174:177], v[6:9], v[126:129]
	v_mfma_f32_16x16x32_bf16 v[126:129], v[182:185], v[14:17], v[2:5]
	v_mfma_f32_16x16x32_bf16 v[2:5], v[186:189], v[6:9], v[122:125]
	v_mfma_f32_16x16x32_bf16 v[82:85], v[190:193], v[14:17], v[2:5]
	v_mfma_f32_16x16x32_bf16 v[2:5], v[174:177], v[18:21], v[118:121]
	v_mfma_f32_16x16x32_bf16 v[110:113], v[182:185], v[22:25], v[2:5]
	v_mfma_f32_16x16x32_bf16 v[2:5], v[186:189], v[18:21], v[114:117]
	v_mfma_f32_16x16x32_bf16 v[86:89], v[190:193], v[22:25], v[2:5]
	v_mfma_f32_16x16x32_bf16 v[2:5], v[174:177], v[26:29], v[134:137]
	v_mfma_f32_16x16x32_bf16 v[94:97], v[182:185], v[30:33], v[2:5]
	v_mfma_f32_16x16x32_bf16 v[2:5], v[186:189], v[26:29], v[106:109]
	v_mfma_f32_16x16x32_bf16 v[78:81], v[190:193], v[30:33], v[2:5]
	v_mfma_f32_16x16x32_bf16 v[2:5], v[174:177], v[38:41], v[102:105]
	v_mfma_f32_16x16x32_bf16 v[10:13], v[186:189], v[38:41], v[98:101]
	v_mfma_f32_16x16x32_bf16 v[2:5], v[182:185], v[202:205], v[2:5]
	v_mfma_f32_16x16x32_bf16 v[10:13], v[190:193], v[202:205], v[10:13]
	s_setprio 0
	v_add_u32_e32 v0, 0x1c000, v206
	s_barrier
	ds_read_b128 v[122:125], v0
	ds_read_b128 v[134:137], v0 offset:1024
	ds_read_b128 v[206:209], v0 offset:2048
	ds_read_b128 v[210:213], v0 offset:3072
	s_waitcnt vmcnt(0)
	s_barrier
	s_waitcnt lgkmcnt(0)
	s_setprio 1
	s_waitcnt lgkmcnt(0)
	v_mfma_f32_16x16x32_bf16 v[98:101], v[122:125], v[6:9], v[194:197]
	v_mfma_f32_16x16x32_bf16 v[6:9], v[206:209], v[6:9], v[90:93]
	v_mfma_f32_16x16x32_bf16 v[114:117], v[210:213], v[14:17], v[6:9]
	v_mfma_f32_16x16x32_bf16 v[6:9], v[122:125], v[18:21], v[150:153]
	v_mfma_f32_16x16x32_bf16 v[102:105], v[134:137], v[22:25], v[6:9]
	v_mfma_f32_16x16x32_bf16 v[6:9], v[206:209], v[18:21], v[154:157]
	v_mfma_f32_16x16x32_bf16 v[118:121], v[210:213], v[22:25], v[6:9]
	v_mfma_f32_16x16x32_bf16 v[6:9], v[122:125], v[26:29], v[158:161]
	v_mfma_f32_16x16x32_bf16 v[90:93], v[134:137], v[30:33], v[6:9]
	v_mfma_f32_16x16x32_bf16 v[6:9], v[206:209], v[26:29], v[74:77]
	v_mfma_f32_16x16x32_bf16 v[106:109], v[210:213], v[30:33], v[6:9]
	v_mfma_f32_16x16x32_bf16 v[6:9], v[122:125], v[38:41], v[70:73]
	v_mfma_f32_16x16x32_bf16 v[22:25], v[134:137], v[202:205], v[6:9]
	v_mfma_f32_16x16x32_bf16 v[6:9], v[206:209], v[38:41], v[66:69]
	v_mfma_f32_16x16x32_bf16 v[98:101], v[134:137], v[14:17], v[98:101]
	v_mfma_f32_16x16x32_bf16 v[38:41], v[210:213], v[202:205], v[6:9]
	s_setprio 0
	s_barrier
	ds_read_b128 v[70:73], v241 offset:49152
	ds_read_b128 v[74:77], v241 offset:50176
	ds_read_b128 v[150:153], v241 offset:51200
	ds_read_b128 v[154:157], v241 offset:52224
	ds_read_b128 v[158:161], v241 offset:53248
	ds_read_b128 v[194:197], v241 offset:54272
	ds_read_b128 v[202:205], v241 offset:55296
	ds_read_b128 v[214:217], v241 offset:56320
	s_barrier
	s_waitcnt lgkmcnt(0)
	s_setprio 1
	s_waitcnt lgkmcnt(0)
	v_mfma_f32_16x16x32_bf16 v[14:17], v[186:189], v[70:73], v[58:61]
	v_mfma_f32_16x16x32_bf16 v[42:45], v[186:189], v[158:161], v[42:45]
	v_mfma_f32_16x16x32_bf16 v[6:9], v[174:177], v[70:73], v[62:65]
	v_mfma_f32_16x16x32_bf16 v[18:21], v[190:193], v[74:77], v[14:17]
	v_mfma_f32_16x16x32_bf16 v[14:17], v[174:177], v[150:153], v[54:57]
	v_mfma_f32_16x16x32_bf16 v[26:29], v[186:189], v[150:153], v[50:53]
	v_mfma_f32_16x16x32_bf16 v[30:33], v[174:177], v[158:161], v[46:49]
	v_mfma_f32_16x16x32_bf16 v[46:49], v[190:193], v[194:197], v[42:45]
	v_mfma_f32_16x16x32_bf16 v[42:45], v[174:177], v[202:205], v[130:133]
	v_mfma_f32_16x16x32_bf16 v[34:37], v[186:189], v[202:205], v[34:37]
	v_mfma_f32_16x16x32_bf16 v[6:9], v[182:185], v[74:77], v[6:9]
	v_mfma_f32_16x16x32_bf16 v[14:17], v[182:185], v[154:157], v[14:17]
	v_mfma_f32_16x16x32_bf16 v[26:29], v[190:193], v[154:157], v[26:29]
	v_mfma_f32_16x16x32_bf16 v[30:33], v[182:185], v[194:197], v[30:33]
	v_mfma_f32_16x16x32_bf16 v[54:57], v[182:185], v[214:217], v[42:45]
	v_mfma_f32_16x16x32_bf16 v[66:69], v[190:193], v[214:217], v[34:37]
	s_setprio 0
	s_setprio 1
	v_mfma_f32_16x16x32_bf16 v[34:37], v[122:125], v[70:73], v[138:141]
	v_mfma_f32_16x16x32_bf16 v[42:45], v[206:209], v[70:73], v[142:145]
	v_mfma_f32_16x16x32_bf16 v[34:37], v[134:137], v[74:77], v[34:37]
	v_mfma_f32_16x16x32_bf16 v[50:53], v[210:213], v[74:77], v[42:45]
	v_mfma_f32_16x16x32_bf16 v[42:45], v[122:125], v[150:153], v[146:149]
	v_mfma_f32_16x16x32_bf16 v[58:61], v[206:209], v[150:153], v[178:181]
	v_mfma_f32_16x16x32_bf16 v[62:65], v[122:125], v[158:161], v[198:201]
	v_mfma_f32_16x16x32_bf16 v[70:73], v[206:209], v[158:161], v[162:165]
	v_mfma_f32_16x16x32_bf16 v[74:77], v[122:125], v[202:205], v[166:169]
	v_mfma_f32_16x16x32_bf16 v[122:125], v[206:209], v[202:205], v[170:173]
	v_mfma_f32_16x16x32_bf16 v[42:45], v[134:137], v[154:157], v[42:45]
	v_mfma_f32_16x16x32_bf16 v[58:61], v[210:213], v[154:157], v[58:61]
	v_mfma_f32_16x16x32_bf16 v[62:65], v[134:137], v[194:197], v[62:65]
	v_mfma_f32_16x16x32_bf16 v[70:73], v[210:213], v[194:197], v[70:73]
	v_mfma_f32_16x16x32_bf16 v[74:77], v[134:137], v[214:217], v[74:77]
	v_mfma_f32_16x16x32_bf16 v[122:125], v[210:213], v[214:217], v[122:125]
	s_setprio 0
	s_barrier
	s_and_saveexec_b64 s[0:1], s[90:91]
	s_cbranch_execz .LBB0_475
	s_barrier

; #define LDA(dst, b, h) for (int m = 0; m < 4; ++m) for (int k = 0; k < 2; ++k) \
;     dst[m][k] = *reinterpret_cast<const bf16x8*>((char*)SA(b, h) + a_thr + (m * 2 + k) * 1024)
; #define LDB(dst, b, h) for (int n = 0; n < 2; ++n) for (int k = 0; k < 2; ++k) \
;     dst[n][k] = *reinterpret_cast<const bf16x8*>((char*)SB(b, h) + b_thr + (n * 2 + k) * 1024)
; #define MMA(ai, bj, At, Btf) do { __builtin_amdgcn_s_setprio(1); \
;     for (int m = 0; m < 4; ++m) for (int n = 0; n < 2; ++n) for (int k = 0; k < 2; ++k) \
;       acc[ai][bj][m][n] = __builtin_amdgcn_mfma_f32_16x16x32_bf16(Btf[n][k], At[m][k], acc[ai][bj][m][n], 0, 0, 0); \
;     __builtin_amdgcn_s_setprio(0); } while (0)
; #define WAIT_V(n) asm volatile("s_waitcnt vmcnt(" #n ")" ::: "memory")
; #define WAIT_L(n) asm volatile("s_waitcnt lgkmcnt(" #n ")" ::: "memory")
; #define BAR __builtin_amdgcn_s_barrier()
; #define SCHED __builtin_amdgcn_sched_barrier(0)
; template <bool OVL, bool PANEL = false, class Epi>
; __device__ __forceinline__ void gemm_phase(const bf16_t* __restrict__ A, long lda, const bf16_t* __restrict__ Bt, long ldb, int nM, int nN, int K,
;                                            const Epi& epi, bf16_t* shm, int w0) {
;     ...
;     for (int t = 0; t < nt - 2; t += 2) {
;       LDB(B0, 0, 0); SCHED; LDA(At, 0, 0); STAGE(SA(1, 1), A, lda, aoff, brow + HALF, t + 1);
;       WAIT_L(8); BAR; WAIT_L(0); MMA(0, 0, At, B0); BAR; SCHED;
;       LDB(B1, 0, 1); STAGE(SB(0, 0), Bt, ldb, boff, bcol, t + 2);
;       BAR; WAIT_L(0); MMA(0, 1, At, B1); BAR;
;       LDA(At, 0, 1); STAGE(SA(0, 0), A, lda, aoff, brow, t + 2);
;       BAR; WAIT_L(0); MMA(1, 0, At, B0); BAR; SCHED;
;       STAGE(SB(0, 1), Bt, ldb, boff, bcol + HALF, t + 2);
;       WAIT_V(6); BAR; MMA(1, 1, At, B1); BAR;
.LBB0_1053:
	ds_read_b128 v[152:155], v184
	ds_read_b128 v[156:159], v184 offset:1024
	ds_read_b128 v[160:163], v184 offset:2048
	ds_read_b128 v[164:167], v184 offset:3072
	s_add_u32 s40, s10, s14
	s_addc_u32 s41, s11, s15
	ds_read_b128 v[168:171], v147
	ds_read_b128 v[172:175], v147 offset:1024
	ds_read_b128 v[176:179], v147 offset:2048
	ds_read_b128 v[194:197], v147 offset:3072
	ds_read_b128 v[198:201], v147 offset:4096
	ds_read_b128 v[202:205], v147 offset:5120
	ds_read_b128 v[206:209], v147 offset:6144
	ds_read_b128 v[210:213], v147 offset:7168
	s_mov_b32 m0, s22
	s_add_u32 s98, s40, s16
	s_addc_u32 s99, s41, s17
	global_load_lds_dwordx4 v135, s[98:99]
	s_mov_b32 m0, s23
	s_add_u32 s98, s40, s36
	s_addc_u32 s99, s41, s37
	global_load_lds_dwordx4 v135, s[98:99]
	s_waitcnt lgkmcnt(8)
	s_waitcnt vmcnt(10)
	s_barrier
	s_waitcnt lgkmcnt(0)
	s_setprio 1
	s_waitcnt lgkmcnt(0)
	v_mfma_f32_16x16x32_bf16 v[126:129], v[152:155], v[168:171], v[126:129]
	v_mfma_f32_16x16x32_bf16 v[122:125], v[160:163], v[168:171], v[122:125]
	v_mfma_f32_16x16x32_bf16 v[118:121], v[152:155], v[176:179], v[118:121]
	v_mfma_f32_16x16x32_bf16 v[114:117], v[160:163], v[176:179], v[114:117]
	v_mfma_f32_16x16x32_bf16 v[110:113], v[152:155], v[198:201], v[110:113]
	v_mfma_f32_16x16x32_bf16 v[106:109], v[160:163], v[198:201], v[106:109]
	v_mfma_f32_16x16x32_bf16 v[102:105], v[152:155], v[206:209], v[102:105]
	v_mfma_f32_16x16x32_bf16 v[98:101], v[160:163], v[206:209], v[98:101]
	v_mfma_f32_16x16x32_bf16 v[126:129], v[156:159], v[172:175], v[126:129]
	v_mfma_f32_16x16x32_bf16 v[122:125], v[164:167], v[172:175], v[122:125]
	v_mfma_f32_16x16x32_bf16 v[118:121], v[156:159], v[194:197], v[118:121]
	v_mfma_f32_16x16x32_bf16 v[114:117], v[164:167], v[194:197], v[114:117]
	v_mfma_f32_16x16x32_bf16 v[110:113], v[156:159], v[202:205], v[110:113]
	v_mfma_f32_16x16x32_bf16 v[106:109], v[164:167], v[202:205], v[106:109]
	v_mfma_f32_16x16x32_bf16 v[102:105], v[156:159], v[210:213], v[102:105]
	v_mfma_f32_16x16x32_bf16 v[98:101], v[164:167], v[210:213], v[98:101]
	s_setprio 0
	s_barrier
	s_add_u32 s42, s8, s14
	ds_read_b128 v[214:217], v185
	ds_read_b128 v[218:221], v185 offset:1024
	ds_read_b128 v[234:237], v185 offset:2048
	ds_read_b128 v[238:241], v185 offset:3072
	s_addc_u32 s43, s9, s15
	s_mov_b32 m0, s24
	s_add_u32 s98, s42, s34
	s_addc_u32 s99, s43, s35
	global_load_lds_dwordx4 v135, s[98:99]
	s_mov_b32 m0, s25
	s_add_u32 s98, s42, s64
	s_addc_u32 s99, s43, s65
	global_load_lds_dwordx4 v135, s[98:99]
	s_waitcnt vmcnt(10)
	s_barrier
	s_waitcnt lgkmcnt(0)
	s_setprio 1
	s_waitcnt lgkmcnt(0)
	v_mfma_f32_16x16x32_bf16 v[94:97], v[214:217], v[168:171], v[94:97]
	v_mfma_f32_16x16x32_bf16 v[90:93], v[234:237], v[168:171], v[90:93]
	v_mfma_f32_16x16x32_bf16 v[86:89], v[214:217], v[176:179], v[86:89]
	v_mfma_f32_16x16x32_bf16 v[82:85], v[234:237], v[176:179], v[82:85]
	v_mfma_f32_16x16x32_bf16 v[78:81], v[214:217], v[198:201], v[78:81]
	v_mfma_f32_16x16x32_bf16 v[74:77], v[234:237], v[198:201], v[74:77]
	v_mfma_f32_16x16x32_bf16 v[70:73], v[214:217], v[206:209], v[70:73]
	v_mfma_f32_16x16x32_bf16 v[66:69], v[234:237], v[206:209], v[66:69]
	v_mfma_f32_16x16x32_bf16 v[94:97], v[218:221], v[172:175], v[94:97]
	v_mfma_f32_16x16x32_bf16 v[90:93], v[238:241], v[172:175], v[90:93]
	v_mfma_f32_16x16x32_bf16 v[86:89], v[218:221], v[194:197], v[86:89]
	v_mfma_f32_16x16x32_bf16 v[82:85], v[238:241], v[194:197], v[82:85]
	v_mfma_f32_16x16x32_bf16 v[78:81], v[218:221], v[202:205], v[78:81]
	v_mfma_f32_16x16x32_bf16 v[74:77], v[238:241], v[202:205], v[74:77]
	v_mfma_f32_16x16x32_bf16 v[70:73], v[218:221], v[210:213], v[70:73]
	v_mfma_f32_16x16x32_bf16 v[66:69], v[238:241], v[210:213], v[66:69]
	s_setprio 0
	s_barrier
	ds_read_b128 v[168:171], v147 offset:16384
	ds_read_b128 v[172:175], v147 offset:17408
	ds_read_b128 v[176:179], v147 offset:18432
	ds_read_b128 v[194:197], v147 offset:19456
	ds_read_b128 v[198:201], v147 offset:20480
	ds_read_b128 v[202:205], v147 offset:21504
	ds_read_b128 v[206:209], v147 offset:22528
	ds_read_b128 v[210:213], v147 offset:23552
	s_mov_b32 m0, s26
	s_add_u32 s98, s40, s34
	s_addc_u32 s99, s41, s35
	global_load_lds_dwordx4 v135, s[98:99]
	s_mov_b32 m0, s27
	s_add_u32 s98, s40, s64
	s_addc_u32 s99, s41, s65
	global_load_lds_dwordx4 v135, s[98:99]
	s_barrier
	s_waitcnt lgkmcnt(0)
	s_setprio 1
	s_waitcnt lgkmcnt(0)
	v_mfma_f32_16x16x32_bf16 v[62:65], v[152:155], v[168:171], v[62:65]
	v_mfma_f32_16x16x32_bf16 v[58:61], v[160:163], v[168:171], v[58:61]
	v_mfma_f32_16x16x32_bf16 v[54:57], v[152:155], v[176:179], v[54:57]
	v_mfma_f32_16x16x32_bf16 v[50:53], v[160:163], v[176:179], v[50:53]
	v_mfma_f32_16x16x32_bf16 v[46:49], v[152:155], v[198:201], v[46:49]
	v_mfma_f32_16x16x32_bf16 v[42:45], v[160:163], v[198:201], v[42:45]
	v_mfma_f32_16x16x32_bf16 v[38:41], v[152:155], v[206:209], v[38:41]
	v_mfma_f32_16x16x32_bf16 v[34:37], v[160:163], v[206:209], v[34:37]
	v_mfma_f32_16x16x32_bf16 v[62:65], v[156:159], v[172:175], v[62:65]
	v_mfma_f32_16x16x32_bf16 v[58:61], v[164:167], v[172:175], v[58:61]
	v_mfma_f32_16x16x32_bf16 v[54:57], v[156:159], v[194:197], v[54:57]
	v_mfma_f32_16x16x32_bf16 v[50:53], v[164:167], v[194:197], v[50:53]
	v_mfma_f32_16x16x32_bf16 v[46:49], v[156:159], v[202:205], v[46:49]
	v_mfma_f32_16x16x32_bf16 v[42:45], v[164:167], v[202:205], v[42:45]
	v_mfma_f32_16x16x32_bf16 v[38:41], v[156:159], v[210:213], v[38:41]
	v_mfma_f32_16x16x32_bf16 v[34:37], v[164:167], v[210:213], v[34:37]
	s_setprio 0
	s_barrier
	s_mov_b32 m0, s28
	s_add_u32 s98, s42, s68
	s_addc_u32 s99, s43, s69
	global_load_lds_dwordx4 v135, s[98:99]
	s_mov_b32 m0, s29
	s_add_u32 s98, s42, s70
	s_addc_u32 s99, s43, s71
	global_load_lds_dwordx4 v135, s[98:99]
	s_waitcnt vmcnt(10)
	s_barrier
; #define LDA(dst, b, h) for (int m = 0; m < 4; ++m) for (int k = 0; k < 2; ++k) \
;     dst[m][k] = *reinterpret_cast<const bf16x8*>((char*)SA(b, h) + a_thr + (m * 2 + k) * 1024)
; #define LDB(dst, b, h) for (int n = 0; n < 2; ++n) for (int k = 0; k < 2; ++k) \
;     dst[n][k] = *reinterpret_cast<const bf16x8*>((char*)SB(b, h) + b_thr + (n * 2 + k) * 1024)
; #define MMA(ai, bj, At, Btf) do { __builtin_amdgcn_s_setprio(1); \
;     for (int m = 0; m < 4; ++m) for (int n = 0; n < 2; ++n) for (int k = 0; k < 2; ++k) \
;       acc[ai][bj][m][n] = __builtin_amdgcn_mfma_f32_16x16x32_bf16(Btf[n][k], At[m][k], acc[ai][bj][m][n], 0, 0, 0); \
;     __builtin_amdgcn_s_setprio(0); } while (0)
; #define WAIT_V(n) asm volatile("s_waitcnt vmcnt(" #n ")" ::: "memory")
; #define WAIT_L(n) asm volatile("s_waitcnt lgkmcnt(" #n ")" ::: "memory")
; #define BAR __builtin_amdgcn_s_barrier()
; #define SCHED __builtin_amdgcn_sched_barrier(0)
; template <bool OVL, bool PANEL = false, class Epi>
; __device__ __forceinline__ void gemm_phase(const bf16_t* __restrict__ A, long lda, const bf16_t* __restrict__ Bt, long ldb, int nM, int nN, int K,
;                                            const Epi& epi, bf16_t* shm, int w0) {
;     ...
;       WAIT_V(6); BAR; MMA(1, 1, At, B1); BAR;
;       LDB(B0, 1, 0); SCHED; LDA(At, 1, 0); STAGE(SA(0, 1), A, lda, aoff, brow + HALF, t + 2);
;       WAIT_L(8); BAR; WAIT_L(0); MMA(0, 0, At, B0); BAR; SCHED;
;       LDB(B1, 1, 1); STAGE(SB(1, 0), Bt, ldb, boff, bcol, t + 3);
;       BAR; WAIT_L(0); MMA(0, 1, At, B1); BAR;
;       LDA(At, 1, 1); STAGE(SA(1, 0), A, lda, aoff, brow, t + 3);
	s_setprio 1
	v_mfma_f32_16x16x32_bf16 v[30:33], v[214:217], v[168:171], v[30:33]
	v_mfma_f32_16x16x32_bf16 v[26:29], v[234:237], v[168:171], v[26:29]
	v_mfma_f32_16x16x32_bf16 v[22:25], v[214:217], v[176:179], v[22:25]
	v_mfma_f32_16x16x32_bf16 v[18:21], v[234:237], v[176:179], v[18:21]
	v_mfma_f32_16x16x32_bf16 v[14:17], v[214:217], v[198:201], v[14:17]
	v_mfma_f32_16x16x32_bf16 v[10:13], v[234:237], v[198:201], v[10:13]
	v_mfma_f32_16x16x32_bf16 v[6:9], v[214:217], v[206:209], v[6:9]
	v_mfma_f32_16x16x32_bf16 v[2:5], v[234:237], v[206:209], v[2:5]
	v_mfma_f32_16x16x32_bf16 v[30:33], v[218:221], v[172:175], v[30:33]
	v_mfma_f32_16x16x32_bf16 v[26:29], v[238:241], v[172:175], v[26:29]
	v_mfma_f32_16x16x32_bf16 v[22:25], v[218:221], v[194:197], v[22:25]
	v_mfma_f32_16x16x32_bf16 v[18:21], v[238:241], v[194:197], v[18:21]
	v_mfma_f32_16x16x32_bf16 v[14:17], v[218:221], v[202:205], v[14:17]
	v_mfma_f32_16x16x32_bf16 v[10:13], v[238:241], v[202:205], v[10:13]
	v_mfma_f32_16x16x32_bf16 v[6:9], v[218:221], v[210:213], v[6:9]
	v_mfma_f32_16x16x32_bf16 v[2:5], v[238:241], v[210:213], v[2:5]
	s_setprio 0
	s_barrier
	ds_read_b128 v[152:155], v186
	ds_read_b128 v[156:159], v186 offset:1024
	ds_read_b128 v[160:163], v186 offset:2048
	ds_read_b128 v[164:167], v186 offset:3072
	ds_read_b128 v[168:171], v147 offset:32768
	ds_read_b128 v[172:175], v147 offset:33792
	ds_read_b128 v[176:179], v147 offset:34816
	ds_read_b128 v[194:197], v147 offset:35840
	ds_read_b128 v[198:201], v147 offset:36864
	ds_read_b128 v[202:205], v147 offset:37888
	ds_read_b128 v[206:209], v147 offset:38912
	ds_read_b128 v[210:213], v147 offset:39936
	s_mov_b32 m0, s30
	s_add_u32 s98, s40, s68
	s_addc_u32 s99, s41, s69
	global_load_lds_dwordx4 v135, s[98:99]
	s_mov_b32 m0, s31
	s_add_u32 s98, s40, s70
	s_addc_u32 s99, s41, s71
	global_load_lds_dwordx4 v135, s[98:99]
	s_waitcnt lgkmcnt(8)
	s_waitcnt vmcnt(10)
	s_barrier
	s_waitcnt lgkmcnt(0)
	s_setprio 1
	s_waitcnt lgkmcnt(0)
	v_mfma_f32_16x16x32_bf16 v[126:129], v[152:155], v[168:171], v[126:129]
	v_mfma_f32_16x16x32_bf16 v[122:125], v[160:163], v[168:171], v[122:125]
	v_mfma_f32_16x16x32_bf16 v[118:121], v[152:155], v[176:179], v[118:121]
	v_mfma_f32_16x16x32_bf16 v[114:117], v[160:163], v[176:179], v[114:117]
	v_mfma_f32_16x16x32_bf16 v[110:113], v[152:155], v[198:201], v[110:113]
	v_mfma_f32_16x16x32_bf16 v[106:109], v[160:163], v[198:201], v[106:109]
	v_mfma_f32_16x16x32_bf16 v[102:105], v[152:155], v[206:209], v[102:105]
	v_mfma_f32_16x16x32_bf16 v[98:101], v[160:163], v[206:209], v[98:101]
	v_mfma_f32_16x16x32_bf16 v[126:129], v[156:159], v[172:175], v[126:129]
	v_mfma_f32_16x16x32_bf16 v[122:125], v[164:167], v[172:175], v[122:125]
	v_mfma_f32_16x16x32_bf16 v[118:121], v[156:159], v[194:197], v[118:121]
	v_mfma_f32_16x16x32_bf16 v[114:117], v[164:167], v[194:197], v[114:117]
	v_mfma_f32_16x16x32_bf16 v[110:113], v[156:159], v[202:205], v[110:113]
	v_mfma_f32_16x16x32_bf16 v[106:109], v[164:167], v[202:205], v[106:109]
	v_mfma_f32_16x16x32_bf16 v[102:105], v[156:159], v[210:213], v[102:105]
	v_mfma_f32_16x16x32_bf16 v[98:101], v[164:167], v[210:213], v[98:101]
	s_setprio 0
	s_barrier
	ds_read_b128 v[214:217], v187
	ds_read_b128 v[218:221], v187 offset:1024
	ds_read_b128 v[234:237], v187 offset:2048
	ds_read_b128 v[238:241], v187 offset:3072
	s_mov_b32 m0, s32
	s_add_u32 s98, s42, s94
	s_addc_u32 s99, s43, s95
	global_load_lds_dwordx4 v135, s[98:99]
	s_mov_b32 m0, s44
	s_add_u32 s98, s42, s72
	s_addc_u32 s99, s43, s73
	global_load_lds_dwordx4 v135, s[98:99]
	s_waitcnt vmcnt(10)
	s_barrier
	s_waitcnt lgkmcnt(0)
	s_setprio 1
	s_waitcnt lgkmcnt(0)
	v_mfma_f32_16x16x32_bf16 v[94:97], v[214:217], v[168:171], v[94:97]
	v_mfma_f32_16x16x32_bf16 v[90:93], v[234:237], v[168:171], v[90:93]
	v_mfma_f32_16x16x32_bf16 v[86:89], v[214:217], v[176:179], v[86:89]
	v_mfma_f32_16x16x32_bf16 v[82:85], v[234:237], v[176:179], v[82:85]
	v_mfma_f32_16x16x32_bf16 v[78:81], v[214:217], v[198:201], v[78:81]
	v_mfma_f32_16x16x32_bf16 v[74:77], v[234:237], v[198:201], v[74:77]
	v_mfma_f32_16x16x32_bf16 v[70:73], v[214:217], v[206:209], v[70:73]
	v_mfma_f32_16x16x32_bf16 v[66:69], v[234:237], v[206:209], v[66:69]
	v_mfma_f32_16x16x32_bf16 v[94:97], v[218:221], v[172:175], v[94:97]
	v_mfma_f32_16x16x32_bf16 v[90:93], v[238:241], v[172:175], v[90:93]
	v_mfma_f32_16x16x32_bf16 v[86:89], v[218:221], v[194:197], v[86:89]
	v_mfma_f32_16x16x32_bf16 v[82:85], v[238:241], v[194:197], v[82:85]
	v_mfma_f32_16x16x32_bf16 v[78:81], v[218:221], v[202:205], v[78:81]
	v_mfma_f32_16x16x32_bf16 v[74:77], v[238:241], v[202:205], v[74:77]
	v_mfma_f32_16x16x32_bf16 v[70:73], v[218:221], v[210:213], v[70:73]
	v_mfma_f32_16x16x32_bf16 v[66:69], v[238:241], v[210:213], v[66:69]
	s_setprio 0
	s_barrier
	ds_read_b128 v[168:171], v147 offset:49152
	ds_read_b128 v[172:175], v147 offset:50176
	ds_read_b128 v[176:179], v147 offset:51200
	ds_read_b128 v[194:197], v147 offset:52224
	ds_read_b128 v[198:201], v147 offset:53248
	ds_read_b128 v[202:205], v147 offset:54272
	ds_read_b128 v[206:209], v147 offset:55296
	ds_read_b128 v[210:213], v147 offset:56320
	s_mov_b32 m0, s45
	s_add_u32 s98, s40, s94
	s_addc_u32 s99, s41, s95
	global_load_lds_dwordx4 v135, s[98:99]
	s_mov_b32 m0, s46
	s_add_u32 s98, s40, s72
	s_addc_u32 s99, s41, s73
	global_load_lds_dwordx4 v135, s[98:99]
	s_barrier
; #define LDA(dst, b, h) for (int m = 0; m < 4; ++m) for (int k = 0; k < 2; ++k) \
;     dst[m][k] = *reinterpret_cast<const bf16x8*>((char*)SA(b, h) + a_thr + (m * 2 + k) * 1024)
; #define LDB(dst, b, h) for (int n = 0; n < 2; ++n) for (int k = 0; k < 2; ++k) \
;     dst[n][k] = *reinterpret_cast<const bf16x8*>((char*)SB(b, h) + b_thr + (n * 2 + k) * 1024)
; #define MMA(ai, bj, At, Btf) do { __builtin_amdgcn_s_setprio(1); \
;     for (int m = 0; m < 4; ++m) for (int n = 0; n < 2; ++n) for (int k = 0; k < 2; ++k) \
;       acc[ai][bj][m][n] = __builtin_amdgcn_mfma_f32_16x16x32_bf16(Btf[n][k], At[m][k], acc[ai][bj][m][n], 0, 0, 0); \
;     __builtin_amdgcn_s_setprio(0); } while (0)
; #define WAIT_V(n) asm volatile("s_waitcnt vmcnt(" #n ")" ::: "memory")
; #define WAIT_L(n) asm volatile("s_waitcnt lgkmcnt(" #n ")" ::: "memory")
; #define BAR __builtin_amdgcn_s_barrier()
; #define SCHED __builtin_amdgcn_sched_barrier(0)
; template <bool OVL, bool PANEL = false, class Epi>
; __device__ __forceinline__ void gemm_phase(const bf16_t* __restrict__ A, long lda, const bf16_t* __restrict__ Bt, long ldb, int nM, int nN, int K,
;                                            const Epi& epi, bf16_t* shm, int w0) {
;     ...
;       BAR; WAIT_L(0); MMA(1, 0, At, B0); BAR; SCHED;
;       STAGE(SB(1, 1), Bt, ldb, boff, bcol + HALF, t + 3);
;       WAIT_V(6); BAR; MMA(1, 1, At, B1); BAR;
;     }
;     { LDB(B0, 0, 0); LDA(At, 0, 0); STAGE(SA(1, 1), A, lda, aoff, brow + HALF, nt - 1);
;       BAR; WAIT_L(0); MMA(0, 0, At, B0); BAR;
;       LDB(B1, 0, 1); BAR; WAIT_L(0); MMA(0, 1, At, B1); BAR;
	s_waitcnt lgkmcnt(0)
	s_setprio 1
	s_waitcnt lgkmcnt(0)
	v_mfma_f32_16x16x32_bf16 v[62:65], v[152:155], v[168:171], v[62:65]
	v_mfma_f32_16x16x32_bf16 v[58:61], v[160:163], v[168:171], v[58:61]
	v_mfma_f32_16x16x32_bf16 v[54:57], v[152:155], v[176:179], v[54:57]
	v_mfma_f32_16x16x32_bf16 v[50:53], v[160:163], v[176:179], v[50:53]
	v_mfma_f32_16x16x32_bf16 v[46:49], v[152:155], v[198:201], v[46:49]
	v_mfma_f32_16x16x32_bf16 v[42:45], v[160:163], v[198:201], v[42:45]
	v_mfma_f32_16x16x32_bf16 v[38:41], v[152:155], v[206:209], v[38:41]
	v_mfma_f32_16x16x32_bf16 v[34:37], v[160:163], v[206:209], v[34:37]
	v_mfma_f32_16x16x32_bf16 v[62:65], v[156:159], v[172:175], v[62:65]
	v_mfma_f32_16x16x32_bf16 v[58:61], v[164:167], v[172:175], v[58:61]
	v_mfma_f32_16x16x32_bf16 v[54:57], v[156:159], v[194:197], v[54:57]
	v_mfma_f32_16x16x32_bf16 v[50:53], v[164:167], v[194:197], v[50:53]
	v_mfma_f32_16x16x32_bf16 v[46:49], v[156:159], v[202:205], v[46:49]
	v_mfma_f32_16x16x32_bf16 v[42:45], v[164:167], v[202:205], v[42:45]
	v_mfma_f32_16x16x32_bf16 v[38:41], v[156:159], v[210:213], v[38:41]
	v_mfma_f32_16x16x32_bf16 v[34:37], v[164:167], v[210:213], v[34:37]
	s_setprio 0
	s_barrier
	s_mov_b32 m0, s47
	s_add_u32 s98, s42, s18
	s_addc_u32 s99, s43, s19
	global_load_lds_dwordx4 v135, s[98:99]
	s_mov_b32 m0, s48
	s_add_u32 s98, s42, s20
	s_addc_u32 s99, s43, s21
	global_load_lds_dwordx4 v135, s[98:99]
	s_waitcnt vmcnt(10)
	s_barrier
	s_setprio 1
	v_mfma_f32_16x16x32_bf16 v[30:33], v[214:217], v[168:171], v[30:33]
	v_mfma_f32_16x16x32_bf16 v[26:29], v[234:237], v[168:171], v[26:29]
	v_mfma_f32_16x16x32_bf16 v[22:25], v[214:217], v[176:179], v[22:25]
	v_mfma_f32_16x16x32_bf16 v[18:21], v[234:237], v[176:179], v[18:21]
	v_mfma_f32_16x16x32_bf16 v[14:17], v[214:217], v[198:201], v[14:17]
	v_mfma_f32_16x16x32_bf16 v[10:13], v[234:237], v[198:201], v[10:13]
	v_mfma_f32_16x16x32_bf16 v[6:9], v[214:217], v[206:209], v[6:9]
	v_mfma_f32_16x16x32_bf16 v[2:5], v[234:237], v[206:209], v[2:5]
	v_mfma_f32_16x16x32_bf16 v[30:33], v[218:221], v[172:175], v[30:33]
	v_mfma_f32_16x16x32_bf16 v[26:29], v[238:241], v[172:175], v[26:29]
	v_mfma_f32_16x16x32_bf16 v[22:25], v[218:221], v[194:197], v[22:25]
	v_mfma_f32_16x16x32_bf16 v[18:21], v[238:241], v[194:197], v[18:21]
	v_mfma_f32_16x16x32_bf16 v[14:17], v[218:221], v[202:205], v[14:17]
	v_mfma_f32_16x16x32_bf16 v[10:13], v[238:241], v[202:205], v[10:13]
	v_mfma_f32_16x16x32_bf16 v[6:9], v[218:221], v[210:213], v[6:9]
	v_mfma_f32_16x16x32_bf16 v[2:5], v[238:241], v[210:213], v[2:5]
	s_setprio 0
	s_add_i32 s1, s1, 2
	s_add_u32 s14, s14, 0x100
	s_addc_u32 s15, s15, 0
	s_cmp_lt_u32 s1, 12
	s_barrier
	s_cbranch_scc1 .LBB0_1053
	s_waitcnt vmcnt(6)
	s_or_b32 s8, s0, 0x80
	s_ashr_i32 s9, s8, 31
	v_readlane_b32 s40, v252, 20
	s_lshl_b64 s[8:9], s[8:9], 11
	v_readlane_b32 s46, v252, 26
	v_add_u32_e32 v182, 16, v144
	v_readlane_b32 s47, v252, 27
	s_add_u32 s8, s46, s8
	v_add_u32_e32 v0, 0x10000, v182
	s_addc_u32 s9, s47, s9
	ds_read_b128 v[130:133], v0
	ds_read_b128 v[152:155], v0 offset:1024
	ds_read_b128 v[156:159], v0 offset:2048
	ds_read_b128 v[160:163], v0 offset:3072
	ds_read_b128 v[164:167], v147
	ds_read_b128 v[168:171], v147 offset:1024
	ds_read_b128 v[172:175], v147 offset:2048
	ds_read_b128 v[176:179], v147 offset:3072
	ds_read_b128 v[194:197], v147 offset:4096
	ds_read_b128 v[198:201], v147 offset:5120
	ds_read_b128 v[202:205], v147 offset:6144
	ds_read_b128 v[206:209], v147 offset:7168
	v_mov_b32_e32 v0, v135
	v_readfirstlane_b32 s1, v150
	v_lshl_add_u64 v[148:149], s[8:9], 0, v[0:1]
	s_mov_b64 s[8:9], 0x780
	v_lshl_add_u64 v[180:181], v[148:149], 0, s[8:9]
	s_mov_b32 m0, s1
	s_mov_b64 s[8:9], 0x20780
	v_readfirstlane_b32 s1, v151
	global_load_lds_dwordx4 v[180:181], off
	v_lshl_add_u64 v[148:149], v[148:149], 0, s[8:9]
	s_mov_b32 m0, s1
	v_readlane_b32 s41, v252, 21
	global_load_lds_dwordx4 v[148:149], off
	s_barrier
	s_waitcnt lgkmcnt(0)
	v_readlane_b32 s42, v252, 22
	v_readlane_b32 s43, v252, 23
	v_readlane_b32 s44, v252, 24
	v_readlane_b32 s45, v252, 25
	v_readlane_b32 s48, v252, 28
	v_readlane_b32 s49, v252, 29
	v_readlane_b32 s50, v252, 30
	v_readlane_b32 s51, v252, 31
	v_readlane_b32 s52, v252, 32
	v_readlane_b32 s53, v252, 33
	v_readlane_b32 s54, v252, 34
	v_readlane_b32 s55, v252, 35
	s_setprio 1
	s_waitcnt lgkmcnt(0)
	v_mfma_f32_16x16x32_bf16 v[126:129], v[130:133], v[164:167], v[126:129]
	v_mfma_f32_16x16x32_bf16 v[122:125], v[156:159], v[164:167], v[122:125]
	v_mfma_f32_16x16x32_bf16 v[118:121], v[130:133], v[172:175], v[118:121]
	v_mfma_f32_16x16x32_bf16 v[114:117], v[156:159], v[172:175], v[114:117]
	v_mfma_f32_16x16x32_bf16 v[110:113], v[130:133], v[194:197], v[110:113]
	v_mfma_f32_16x16x32_bf16 v[106:109], v[156:159], v[194:197], v[106:109]
	v_mfma_f32_16x16x32_bf16 v[102:105], v[130:133], v[202:205], v[102:105]
	v_mfma_f32_16x16x32_bf16 v[98:101], v[156:159], v[202:205], v[98:101]
	v_mfma_f32_16x16x32_bf16 v[126:129], v[152:155], v[168:171], v[126:129]
	v_mfma_f32_16x16x32_bf16 v[122:125], v[160:163], v[168:171], v[122:125]
	v_mfma_f32_16x16x32_bf16 v[118:121], v[152:155], v[176:179], v[118:121]
	v_mfma_f32_16x16x32_bf16 v[114:117], v[160:163], v[176:179], v[114:117]
	v_mfma_f32_16x16x32_bf16 v[110:113], v[152:155], v[198:201], v[110:113]
	v_mfma_f32_16x16x32_bf16 v[106:109], v[160:163], v[198:201], v[106:109]
	v_mfma_f32_16x16x32_bf16 v[102:105], v[152:155], v[206:209], v[102:105]
	v_mfma_f32_16x16x32_bf16 v[98:101], v[160:163], v[206:209], v[98:101]
	s_setprio 0
	v_add_u32_e32 v0, 0x14000, v182
	s_barrier
	ds_read_b128 v[148:151], v0
	ds_read_b128 v[210:213], v0 offset:1024
	ds_read_b128 v[214:217], v0 offset:2048
	ds_read_b128 v[218:221], v0 offset:3072
	s_barrier
; #define LDA(dst, b, h) for (int m = 0; m < 4; ++m) for (int k = 0; k < 2; ++k) \
;     dst[m][k] = *reinterpret_cast<const bf16x8*>((char*)SA(b, h) + a_thr + (m * 2 + k) * 1024)
; #define LDB(dst, b, h) for (int n = 0; n < 2; ++n) for (int k = 0; k < 2; ++k) \
;     dst[n][k] = *reinterpret_cast<const bf16x8*>((char*)SB(b, h) + b_thr + (n * 2 + k) * 1024)
; #define MMA(ai, bj, At, Btf) do { __builtin_amdgcn_s_setprio(1); \
;     for (int m = 0; m < 4; ++m) for (int n = 0; n < 2; ++n) for (int k = 0; k < 2; ++k) \
;       acc[ai][bj][m][n] = __builtin_amdgcn_mfma_f32_16x16x32_bf16(Btf[n][k], At[m][k], acc[ai][bj][m][n], 0, 0, 0); \
;     __builtin_amdgcn_s_setprio(0); } while (0)
; #define WAIT_V(n) asm volatile("s_waitcnt vmcnt(" #n ")" ::: "memory")
; #define WAIT_L(n) asm volatile("s_waitcnt lgkmcnt(" #n ")" ::: "memory")
; #define BAR __builtin_amdgcn_s_barrier()
; template <bool OVL, bool PANEL = false, class Epi>
; __device__ __forceinline__ void gemm_phase(const bf16_t* __restrict__ A, long lda, const bf16_t* __restrict__ Bt, long ldb, int nM, int nN, int K,
;                                            const Epi& epi, bf16_t* shm, int w0) {
;     ...
;       LDB(B1, 0, 1); BAR; WAIT_L(0); MMA(0, 1, At, B1); BAR;
;       LDA(At, 0, 1); WAIT_V(4); BAR; WAIT_L(0); MMA(1, 0, At, B0); MMA(1, 1, At, B1); BAR; }
;     { LDB(B0, 1, 0); LDA(At, 1, 0); WAIT_V(2); BAR; WAIT_L(0); MMA(0, 0, At, B0); BAR;
	s_waitcnt lgkmcnt(0)
	s_setprio 1
	s_waitcnt lgkmcnt(0)
	v_mfma_f32_16x16x32_bf16 v[94:97], v[148:151], v[164:167], v[94:97]
	v_mfma_f32_16x16x32_bf16 v[90:93], v[214:217], v[164:167], v[90:93]
	v_mfma_f32_16x16x32_bf16 v[86:89], v[148:151], v[172:175], v[86:89]
	v_mfma_f32_16x16x32_bf16 v[82:85], v[214:217], v[172:175], v[82:85]
	v_mfma_f32_16x16x32_bf16 v[78:81], v[148:151], v[194:197], v[78:81]
	v_mfma_f32_16x16x32_bf16 v[74:77], v[214:217], v[194:197], v[74:77]
	v_mfma_f32_16x16x32_bf16 v[70:73], v[148:151], v[202:205], v[70:73]
	v_mfma_f32_16x16x32_bf16 v[66:69], v[214:217], v[202:205], v[66:69]
	v_mfma_f32_16x16x32_bf16 v[94:97], v[210:213], v[168:171], v[94:97]
	v_mfma_f32_16x16x32_bf16 v[90:93], v[218:221], v[168:171], v[90:93]
	v_mfma_f32_16x16x32_bf16 v[86:89], v[210:213], v[176:179], v[86:89]
	v_mfma_f32_16x16x32_bf16 v[82:85], v[218:221], v[176:179], v[82:85]
	v_mfma_f32_16x16x32_bf16 v[78:81], v[210:213], v[198:201], v[78:81]
	v_mfma_f32_16x16x32_bf16 v[74:77], v[218:221], v[198:201], v[74:77]
	v_mfma_f32_16x16x32_bf16 v[70:73], v[210:213], v[206:209], v[70:73]
	v_mfma_f32_16x16x32_bf16 v[66:69], v[218:221], v[206:209], v[66:69]
	s_setprio 0
	s_barrier
	ds_read_b128 v[164:167], v147 offset:16384
	ds_read_b128 v[168:171], v147 offset:17408
	ds_read_b128 v[172:175], v147 offset:18432
	ds_read_b128 v[176:179], v147 offset:19456
	ds_read_b128 v[194:197], v147 offset:20480
	ds_read_b128 v[198:201], v147 offset:21504
	ds_read_b128 v[202:205], v147 offset:22528
	ds_read_b128 v[206:209], v147 offset:23552
	s_waitcnt vmcnt(4)
	s_barrier
	s_waitcnt lgkmcnt(0)
	s_setprio 1
	s_waitcnt lgkmcnt(0)
	v_mfma_f32_16x16x32_bf16 v[62:65], v[130:133], v[164:167], v[62:65]
	v_mfma_f32_16x16x32_bf16 v[58:61], v[156:159], v[164:167], v[58:61]
	v_mfma_f32_16x16x32_bf16 v[54:57], v[130:133], v[172:175], v[54:57]
	v_mfma_f32_16x16x32_bf16 v[50:53], v[156:159], v[172:175], v[50:53]
	v_mfma_f32_16x16x32_bf16 v[46:49], v[130:133], v[194:197], v[46:49]
	v_mfma_f32_16x16x32_bf16 v[42:45], v[156:159], v[194:197], v[42:45]
	v_mfma_f32_16x16x32_bf16 v[38:41], v[130:133], v[202:205], v[38:41]
	v_mfma_f32_16x16x32_bf16 v[34:37], v[156:159], v[202:205], v[34:37]
	v_mfma_f32_16x16x32_bf16 v[62:65], v[152:155], v[168:171], v[62:65]
	v_mfma_f32_16x16x32_bf16 v[58:61], v[160:163], v[168:171], v[58:61]
	v_mfma_f32_16x16x32_bf16 v[54:57], v[152:155], v[176:179], v[54:57]
	v_mfma_f32_16x16x32_bf16 v[50:53], v[160:163], v[176:179], v[50:53]
	v_mfma_f32_16x16x32_bf16 v[46:49], v[152:155], v[198:201], v[46:49]
	v_mfma_f32_16x16x32_bf16 v[42:45], v[160:163], v[198:201], v[42:45]
	v_mfma_f32_16x16x32_bf16 v[38:41], v[152:155], v[206:209], v[38:41]
	v_mfma_f32_16x16x32_bf16 v[34:37], v[160:163], v[206:209], v[34:37]
	s_setprio 0
	s_setprio 1
	v_mfma_f32_16x16x32_bf16 v[30:33], v[148:151], v[164:167], v[30:33]
	v_mfma_f32_16x16x32_bf16 v[26:29], v[214:217], v[164:167], v[26:29]
	v_mfma_f32_16x16x32_bf16 v[22:25], v[148:151], v[172:175], v[22:25]
	v_mfma_f32_16x16x32_bf16 v[18:21], v[214:217], v[172:175], v[18:21]
	v_mfma_f32_16x16x32_bf16 v[14:17], v[148:151], v[194:197], v[14:17]
	v_mfma_f32_16x16x32_bf16 v[10:13], v[214:217], v[194:197], v[10:13]
	v_mfma_f32_16x16x32_bf16 v[6:9], v[148:151], v[202:205], v[6:9]
	v_mfma_f32_16x16x32_bf16 v[2:5], v[214:217], v[202:205], v[2:5]
	v_mfma_f32_16x16x32_bf16 v[30:33], v[210:213], v[168:171], v[30:33]
	v_mfma_f32_16x16x32_bf16 v[26:29], v[218:221], v[168:171], v[26:29]
	v_mfma_f32_16x16x32_bf16 v[22:25], v[210:213], v[176:179], v[22:25]
	v_mfma_f32_16x16x32_bf16 v[18:21], v[218:221], v[176:179], v[18:21]
	v_mfma_f32_16x16x32_bf16 v[14:17], v[210:213], v[198:201], v[14:17]
	v_mfma_f32_16x16x32_bf16 v[10:13], v[218:221], v[198:201], v[10:13]
	v_mfma_f32_16x16x32_bf16 v[6:9], v[210:213], v[206:209], v[6:9]
	v_mfma_f32_16x16x32_bf16 v[2:5], v[218:221], v[206:209], v[2:5]
	s_setprio 0
	v_add_u32_e32 v0, 0x18000, v182
	s_barrier
	ds_read_b128 v[130:133], v0
	ds_read_b128 v[148:151], v0 offset:1024
	ds_read_b128 v[152:155], v0 offset:2048
	ds_read_b128 v[156:159], v0 offset:3072
	ds_read_b128 v[160:163], v147 offset:32768
	ds_read_b128 v[164:167], v147 offset:33792
	ds_read_b128 v[168:171], v147 offset:34816
	ds_read_b128 v[172:175], v147 offset:35840
	ds_read_b128 v[176:179], v147 offset:36864
	ds_read_b128 v[194:197], v147 offset:37888
	ds_read_b128 v[198:201], v147 offset:38912
	ds_read_b128 v[202:205], v147 offset:39936
	s_waitcnt vmcnt(2)
	s_barrier
; #define LDA(dst, b, h) for (int m = 0; m < 4; ++m) for (int k = 0; k < 2; ++k) \
;     dst[m][k] = *reinterpret_cast<const bf16x8*>((char*)SA(b, h) + a_thr + (m * 2 + k) * 1024)
; #define LDB(dst, b, h) for (int n = 0; n < 2; ++n) for (int k = 0; k < 2; ++k) \
;     dst[n][k] = *reinterpret_cast<const bf16x8*>((char*)SB(b, h) + b_thr + (n * 2 + k) * 1024)
; #define MMA(ai, bj, At, Btf) do { __builtin_amdgcn_s_setprio(1); \
;     for (int m = 0; m < 4; ++m) for (int n = 0; n < 2; ++n) for (int k = 0; k < 2; ++k) \
;       acc[ai][bj][m][n] = __builtin_amdgcn_mfma_f32_16x16x32_bf16(Btf[n][k], At[m][k], acc[ai][bj][m][n], 0, 0, 0); \
;     __builtin_amdgcn_s_setprio(0); } while (0)
; #define WAIT_V(n) asm volatile("s_waitcnt vmcnt(" #n ")" ::: "memory")
; #define WAIT_L(n) asm volatile("s_waitcnt lgkmcnt(" #n ")" ::: "memory")
; #define BAR __builtin_amdgcn_s_barrier()
; template <bool OVL, bool PANEL = false, class Epi>
; __device__ __forceinline__ void gemm_phase(const bf16_t* __restrict__ A, long lda, const bf16_t* __restrict__ Bt, long ldb, int nM, int nN, int K,
;                                            const Epi& epi, bf16_t* shm, int w0) {
;     ...
;     { LDB(B0, 1, 0); LDA(At, 1, 0); WAIT_V(2); BAR; WAIT_L(0); MMA(0, 0, At, B0); BAR;
;       LDB(B1, 1, 1); WAIT_V(0); BAR; WAIT_L(0); MMA(0, 1, At, B1); BAR;
;       LDA(At, 1, 1); BAR; WAIT_L(0); MMA(1, 0, At, B0); MMA(1, 1, At, B1); BAR; }
;     if (wr == 0) BAR;
	s_waitcnt lgkmcnt(0)
	s_setprio 1
	s_waitcnt lgkmcnt(0)
	v_mfma_f32_16x16x32_bf16 v[126:129], v[130:133], v[160:163], v[126:129]
	v_mfma_f32_16x16x32_bf16 v[122:125], v[152:155], v[160:163], v[122:125]
	v_mfma_f32_16x16x32_bf16 v[118:121], v[130:133], v[168:171], v[118:121]
	v_mfma_f32_16x16x32_bf16 v[114:117], v[152:155], v[168:171], v[114:117]
	v_mfma_f32_16x16x32_bf16 v[110:113], v[130:133], v[176:179], v[110:113]
	v_mfma_f32_16x16x32_bf16 v[106:109], v[152:155], v[176:179], v[106:109]
	v_mfma_f32_16x16x32_bf16 v[102:105], v[130:133], v[198:201], v[102:105]
	v_mfma_f32_16x16x32_bf16 v[98:101], v[152:155], v[198:201], v[98:101]
	v_mfma_f32_16x16x32_bf16 v[126:129], v[148:151], v[164:167], v[126:129]
	v_mfma_f32_16x16x32_bf16 v[122:125], v[156:159], v[164:167], v[122:125]
	v_mfma_f32_16x16x32_bf16 v[118:121], v[148:151], v[172:175], v[118:121]
	v_mfma_f32_16x16x32_bf16 v[114:117], v[156:159], v[172:175], v[114:117]
	v_mfma_f32_16x16x32_bf16 v[110:113], v[148:151], v[194:197], v[110:113]
	v_mfma_f32_16x16x32_bf16 v[106:109], v[156:159], v[194:197], v[106:109]
	v_mfma_f32_16x16x32_bf16 v[102:105], v[148:151], v[202:205], v[102:105]
	v_mfma_f32_16x16x32_bf16 v[98:101], v[156:159], v[202:205], v[98:101]
	s_setprio 0
	v_add_u32_e32 v0, 0x1c000, v182
	s_barrier
	ds_read_b128 v[206:209], v0
	ds_read_b128 v[210:213], v0 offset:1024
	ds_read_b128 v[214:217], v0 offset:2048
	ds_read_b128 v[218:221], v0 offset:3072
	s_waitcnt vmcnt(0)
	s_barrier
	s_waitcnt lgkmcnt(0)
	s_setprio 1
	s_waitcnt lgkmcnt(0)
	v_mfma_f32_16x16x32_bf16 v[94:97], v[206:209], v[160:163], v[94:97]
	v_mfma_f32_16x16x32_bf16 v[90:93], v[214:217], v[160:163], v[90:93]
	v_mfma_f32_16x16x32_bf16 v[86:89], v[206:209], v[168:171], v[86:89]
	v_mfma_f32_16x16x32_bf16 v[82:85], v[214:217], v[168:171], v[82:85]
	v_mfma_f32_16x16x32_bf16 v[78:81], v[206:209], v[176:179], v[78:81]
	v_mfma_f32_16x16x32_bf16 v[74:77], v[214:217], v[176:179], v[74:77]
	v_mfma_f32_16x16x32_bf16 v[70:73], v[206:209], v[198:201], v[70:73]
	v_mfma_f32_16x16x32_bf16 v[66:69], v[214:217], v[198:201], v[66:69]
	v_mfma_f32_16x16x32_bf16 v[94:97], v[210:213], v[164:167], v[94:97]
	v_mfma_f32_16x16x32_bf16 v[90:93], v[218:221], v[164:167], v[90:93]
	v_mfma_f32_16x16x32_bf16 v[86:89], v[210:213], v[172:175], v[86:89]
	v_mfma_f32_16x16x32_bf16 v[82:85], v[218:221], v[172:175], v[82:85]
	v_mfma_f32_16x16x32_bf16 v[78:81], v[210:213], v[194:197], v[78:81]
	v_mfma_f32_16x16x32_bf16 v[74:77], v[218:221], v[194:197], v[74:77]
	v_mfma_f32_16x16x32_bf16 v[70:73], v[210:213], v[202:205], v[70:73]
	v_mfma_f32_16x16x32_bf16 v[66:69], v[218:221], v[202:205], v[66:69]
	s_setprio 0
	s_barrier
	ds_read_b128 v[160:163], v147 offset:49152
	ds_read_b128 v[164:167], v147 offset:50176
	ds_read_b128 v[168:171], v147 offset:51200
	ds_read_b128 v[172:175], v147 offset:52224
	ds_read_b128 v[176:179], v147 offset:53248
	ds_read_b128 v[194:197], v147 offset:54272
	ds_read_b128 v[198:201], v147 offset:55296
	ds_read_b128 v[202:205], v147 offset:56320
	s_barrier
	s_waitcnt lgkmcnt(0)
	s_setprio 1
	s_waitcnt lgkmcnt(0)
	v_mfma_f32_16x16x32_bf16 v[62:65], v[130:133], v[160:163], v[62:65]
	v_mfma_f32_16x16x32_bf16 v[58:61], v[152:155], v[160:163], v[58:61]
	v_mfma_f32_16x16x32_bf16 v[54:57], v[130:133], v[168:171], v[54:57]
	v_mfma_f32_16x16x32_bf16 v[50:53], v[152:155], v[168:171], v[50:53]
	v_mfma_f32_16x16x32_bf16 v[46:49], v[130:133], v[176:179], v[46:49]
	v_mfma_f32_16x16x32_bf16 v[42:45], v[152:155], v[176:179], v[42:45]
	v_mfma_f32_16x16x32_bf16 v[38:41], v[130:133], v[198:201], v[38:41]
	v_mfma_f32_16x16x32_bf16 v[34:37], v[152:155], v[198:201], v[34:37]
	v_mfma_f32_16x16x32_bf16 v[62:65], v[148:151], v[164:167], v[62:65]
	v_mfma_f32_16x16x32_bf16 v[58:61], v[156:159], v[164:167], v[58:61]
	v_mfma_f32_16x16x32_bf16 v[54:57], v[148:151], v[172:175], v[54:57]
	v_mfma_f32_16x16x32_bf16 v[50:53], v[156:159], v[172:175], v[50:53]
	v_mfma_f32_16x16x32_bf16 v[46:49], v[148:151], v[194:197], v[46:49]
	v_mfma_f32_16x16x32_bf16 v[42:45], v[156:159], v[194:197], v[42:45]
	v_mfma_f32_16x16x32_bf16 v[38:41], v[148:151], v[202:205], v[38:41]
	v_mfma_f32_16x16x32_bf16 v[34:37], v[156:159], v[202:205], v[34:37]
	s_setprio 0
	s_setprio 1
	v_mfma_f32_16x16x32_bf16 v[30:33], v[206:209], v[160:163], v[30:33]
	v_mfma_f32_16x16x32_bf16 v[26:29], v[214:217], v[160:163], v[26:29]
	v_mfma_f32_16x16x32_bf16 v[22:25], v[206:209], v[168:171], v[22:25]
	v_mfma_f32_16x16x32_bf16 v[18:21], v[214:217], v[168:171], v[18:21]
	v_mfma_f32_16x16x32_bf16 v[14:17], v[206:209], v[176:179], v[14:17]
	v_mfma_f32_16x16x32_bf16 v[10:13], v[214:217], v[176:179], v[10:13]
	v_mfma_f32_16x16x32_bf16 v[6:9], v[206:209], v[198:201], v[6:9]
	v_mfma_f32_16x16x32_bf16 v[2:5], v[214:217], v[198:201], v[2:5]
	v_mfma_f32_16x16x32_bf16 v[30:33], v[210:213], v[164:167], v[30:33]
	v_mfma_f32_16x16x32_bf16 v[26:29], v[218:221], v[164:167], v[26:29]
	v_mfma_f32_16x16x32_bf16 v[22:25], v[210:213], v[172:175], v[22:25]
	v_mfma_f32_16x16x32_bf16 v[18:21], v[218:221], v[172:175], v[18:21]
	v_mfma_f32_16x16x32_bf16 v[14:17], v[210:213], v[194:197], v[14:17]
	v_mfma_f32_16x16x32_bf16 v[10:13], v[218:221], v[194:197], v[10:13]
	v_mfma_f32_16x16x32_bf16 v[6:9], v[210:213], v[202:205], v[6:9]
	v_mfma_f32_16x16x32_bf16 v[2:5], v[218:221], v[202:205], v[2:5]
	s_setprio 0
	s_barrier
	s_and_saveexec_b64 s[8:9], s[6:7]
	s_cbranch_execz .LBB0_1056
	s_barrier
